# rg chunk-summary pass: x column read straight into the high half (ds_read_u16_d16_hi) after the first tile, no unpack shift
# speedup vs baseline: 1.0071x; 1.0011x over previous
; #define LAS __attribute__((address_space(3)))
; template <bool FINAL>
; __device__ __forceinline__ void rg_item(PREF p, int l, int item, LAS unsigned char* wl, int lane) {
;     ...
;     const int h = item & 7, rest = item >> 3;
;     const int ci = rest < 512 ? 4 + (rest & 255) : ((rest - 512) & 3), b = rest < 512 ? (rest >> 8) : ((rest - 512) >> 2);
;     const int seq_row0 = ci < 4 ? TL + b * 256 : b * 16384;
;     const int t0 = ci < 4 ? ci * 64 : (ci - 4) * 64;
;     const int seqlen = ci < 4 ? 256 : 16384;
;     const int ch = h * 64 + lane;
;     LAS bf16_t* sXc = (LAS bf16_t*)wl;
;     LAS float* stg = (LAS float*)(wl + 9216);
;     {
;         const float cw0 = p.conv_w[(l * 4 + 0) * 512 + ch], cw1 = p.conv_w[(l * 4 + 1) * 512 + ch], cw2 = p.conv_w[(l * 4 + 2) * 512 + ch], cw3 = p.conv_w[(l * 4 + 3) * 512 + ch];
;         const float cb = p.conv_b[l * 512 + ch];
;         float xv[67]; unsigned xr_[67];
; #pragma unroll
;         for (int i = 0; i < 67; ++i) { const int t = t0 - 2 + i; const int tc = t < 0 ? 0 : (t >= seqlen ? seqlen - 1 : t);
;             xr_[i] = P[(size_t)(seq_row0 + tc) * PW + ch]; }
.Lrg5_dec:
	s_add_i32 s15, s11, s10
	s_mul_i32 s36, s9, 0x104
	s_add_i32 s36, s36, s8
	s_lshl_b32 s36, s36, 12
	s_cmp_eq_u32 s10, 0
	s_cselect_b32 s37, 0, -1
	s_add_i32 s38, s10, 64
	s_cmp_eq_u32 s38, s14
	s_cselect_b32 s38, 0, -1
	s_bfe_u32 s44, s44, 0x30006
	s_mul_i32 s44, s44, 0x4800
	v_lshl_or_b32 v234, s7, 6, v233
	v_lshlrev_b32_e32 v235, 2, v234
	v_lshlrev_b32_e32 v234, 1, v234
	v_and_b32_e32 v236, 15, v233
	v_lshrrev_b32_e32 v241, 4, v233
	s_movk_i32 s39, 0x90
	v_mul_u32_u24_e32 v237, 0x90, v236
	v_lshl_add_u32 v237, v241, 4, v237
	v_lshlrev_b32_e32 v238, 7, v236
	v_lshl_add_u32 v238, v241, 4, v238
	v_lshlrev_b32_e32 v239, 10, v241
	v_lshl_add_u32 v239, v236, 2, v239
	v_mov_b32_e32 v241, v238
	v_add_u32_e32 v236, s44, v237
	s_add_i32 s39, s44, 0x2400
	v_add_u32_e32 v237, s39, v239
	v_add_u32_e32 v238, 0x1000, v237
	v_lshl_add_u32 v239, v233, 2, s44
	v_lshl_add_u32 v240, v233, 1, s44
	s_add_i32 s39, s15, -2
	s_mul_hi_i32 s83, s39, 0x1600
	s_mul_i32 s82, s39, 0x1600
	s_waitcnt lgkmcnt(0)
	s_add_u32 s82, s82, s0
	s_addc_u32 s83, s83, s1
	s_add_u32 s82, s82, 0xbc00000
	s_addc_u32 s83, s83, 0
	global_load_ushort v158, v234, s[82:83]
	s_add_u32 s82, s82, 0x1600
	s_addc_u32 s83, s83, 0
	global_load_ushort v159, v234, s[82:83]
	s_add_u32 s82, s82, 0x1600
	s_addc_u32 s83, s83, 0
	global_load_ushort v160, v234, s[82:83]
	s_add_u32 s82, s82, 0x1600
	s_addc_u32 s83, s83, 0
	global_load_ushort v161, v234, s[82:83]
	s_add_u32 s82, s82, 0x1600
	s_addc_u32 s83, s83, 0
	global_load_ushort v162, v234, s[82:83]
	s_add_u32 s82, s82, 0x1600
	s_addc_u32 s83, s83, 0
	global_load_ushort v163, v234, s[82:83]
	s_add_u32 s82, s82, 0x1600
	s_addc_u32 s83, s83, 0
	global_load_ushort v164, v234, s[82:83]
	s_add_u32 s82, s82, 0x1600
	s_addc_u32 s83, s83, 0
	global_load_ushort v165, v234, s[82:83]
	s_add_u32 s82, s82, 0x1600
	s_addc_u32 s83, s83, 0
	global_load_ushort v166, v234, s[82:83]
	s_add_u32 s82, s82, 0x1600
	s_addc_u32 s83, s83, 0
	global_load_ushort v167, v234, s[82:83]
	s_add_u32 s82, s82, 0x1600
	s_addc_u32 s83, s83, 0
	global_load_ushort v168, v234, s[82:83]
	s_add_u32 s82, s82, 0x1600
	s_addc_u32 s83, s83, 0
	global_load_ushort v169, v234, s[82:83]
	s_add_u32 s82, s82, 0x1600
	s_addc_u32 s83, s83, 0
	global_load_ushort v170, v234, s[82:83]
	s_add_u32 s82, s82, 0x1600
	s_addc_u32 s83, s83, 0
	global_load_ushort v171, v234, s[82:83]
	s_add_u32 s82, s82, 0x1600
	s_addc_u32 s83, s83, 0
	global_load_ushort v172, v234, s[82:83]
	s_add_u32 s82, s82, 0x1600
	s_addc_u32 s83, s83, 0
	global_load_ushort v173, v234, s[82:83]
	s_add_u32 s82, s82, 0x1600
	s_addc_u32 s83, s83, 0
	global_load_ushort v174, v234, s[82:83]
	s_add_u32 s82, s82, 0x1600
	s_addc_u32 s83, s83, 0
	global_load_ushort v175, v234, s[82:83]
	s_add_u32 s82, s82, 0x1600
	s_addc_u32 s83, s83, 0
	global_load_ushort v176, v234, s[82:83]
	s_add_u32 s82, s82, 0x1600
	s_addc_u32 s83, s83, 0
	global_load_ushort v177, v234, s[82:83]
	s_add_u32 s82, s82, 0x1600
	s_addc_u32 s83, s83, 0
	global_load_ushort v178, v234, s[82:83]
	s_add_u32 s82, s82, 0x1600
	s_addc_u32 s83, s83, 0
	global_load_ushort v179, v234, s[82:83]
	s_add_u32 s82, s82, 0x1600
	s_addc_u32 s83, s83, 0
	global_load_ushort v180, v234, s[82:83]
	s_add_u32 s82, s82, 0x1600
	s_addc_u32 s83, s83, 0
	global_load_ushort v181, v234, s[82:83]
	s_add_u32 s82, s82, 0x1600
	s_addc_u32 s83, s83, 0
	global_load_ushort v182, v234, s[82:83]
	s_add_u32 s82, s82, 0x1600
	s_addc_u32 s83, s83, 0
	global_load_ushort v183, v234, s[82:83]
	s_add_u32 s82, s82, 0x1600
	s_addc_u32 s83, s83, 0
	global_load_ushort v184, v234, s[82:83]
	s_add_u32 s82, s82, 0x1600
	s_addc_u32 s83, s83, 0
	global_load_ushort v185, v234, s[82:83]
	s_add_u32 s82, s82, 0x1600
	s_addc_u32 s83, s83, 0
	global_load_ushort v186, v234, s[82:83]
	s_add_u32 s82, s82, 0x1600
	s_addc_u32 s83, s83, 0
	global_load_ushort v187, v234, s[82:83]
	s_add_u32 s82, s82, 0x1600
	s_addc_u32 s83, s83, 0
	global_load_ushort v188, v234, s[82:83]
	s_add_u32 s82, s82, 0x1600
	s_addc_u32 s83, s83, 0
	global_load_ushort v189, v234, s[82:83]
	s_add_u32 s82, s82, 0x1600
	s_addc_u32 s83, s83, 0
	global_load_ushort v190, v234, s[82:83]
	s_add_u32 s82, s82, 0x1600
	s_addc_u32 s83, s83, 0
	global_load_ushort v191, v234, s[82:83]
	s_add_u32 s82, s82, 0x1600
	s_addc_u32 s83, s83, 0
	global_load_ushort v192, v234, s[82:83]
	s_add_u32 s82, s82, 0x1600
	s_addc_u32 s83, s83, 0
	global_load_ushort v193, v234, s[82:83]
	s_add_u32 s82, s82, 0x1600
	s_addc_u32 s83, s83, 0
	global_load_ushort v194, v234, s[82:83]
	s_add_u32 s82, s82, 0x1600
	s_addc_u32 s83, s83, 0
	global_load_ushort v195, v234, s[82:83]
	s_add_u32 s82, s82, 0x1600
	s_addc_u32 s83, s83, 0
	global_load_ushort v196, v234, s[82:83]
	s_add_u32 s82, s82, 0x1600
	s_addc_u32 s83, s83, 0
	global_load_ushort v197, v234, s[82:83]
	s_add_u32 s82, s82, 0x1600
	s_addc_u32 s83, s83, 0
	global_load_ushort v198, v234, s[82:83]
	s_add_u32 s82, s82, 0x1600
	s_addc_u32 s83, s83, 0
	global_load_ushort v199, v234, s[82:83]
	s_add_u32 s82, s82, 0x1600
	s_addc_u32 s83, s83, 0
	global_load_ushort v200, v234, s[82:83]
	s_add_u32 s82, s82, 0x1600
	s_addc_u32 s83, s83, 0
	global_load_ushort v201, v234, s[82:83]
	s_add_u32 s82, s82, 0x1600
	s_addc_u32 s83, s83, 0
	global_load_ushort v202, v234, s[82:83]
	s_add_u32 s82, s82, 0x1600
	s_addc_u32 s83, s83, 0
	global_load_ushort v203, v234, s[82:83]
	s_add_u32 s82, s82, 0x1600
	s_addc_u32 s83, s83, 0
	global_load_ushort v204, v234, s[82:83]
	s_add_u32 s82, s82, 0x1600
	s_addc_u32 s83, s83, 0
	global_load_ushort v205, v234, s[82:83]
	s_add_u32 s82, s82, 0x1600
	s_addc_u32 s83, s83, 0
	global_load_ushort v206, v234, s[82:83]
	s_add_u32 s82, s82, 0x1600
; __device__ __forceinline__ unsigned f2bf(float f) { unsigned r; asm("v_cvt_pk_bf16_f32 %0, %1, %1" : "=v"(r) : "v"(f)); return r & 0xffffu; }
; __device__ __forceinline__ float rcpf_(float x) { return __builtin_amdgcn_rcpf(x); }
; template <bool FINAL, int D>
; __device__ __forceinline__ void rg_dir(PREF p, int l, int h, int ch, int sidx, int rowbase  , LAS bf16_t* sXc, LAS float* stg, int lane) {
;     ...
;     const float ba = p.rg_ba[(l * 2 + D) * 512 + ch], bi = p.rg_bi[(l * 2 + D) * 512 + ch], lam = p.rg_lam[(l * 2 + D) * 512 + ch];
;     const float e_ = __expf(-lam), u_ = 1.f + e_;
;     const float l1p = (u_ == 1.f) ? e_ : __logf(u_) * e_ * rcpf_(u_ - 1.f);
;     const float sp8 = -8.f * 1.4426950408889634f * l1p;
;     float hc = FINAL ? RGC[sidx] : 0.f, Ap = 1.f;
;     bf16x8 Br[4][2], Bi[4][2];
; #pragma unroll
;     for (int nt = 0; nt < 4; ++nt) { const int o0 = (nt * 16 + (lane & 15)) * 64 + (lane >> 4) * 8;
;         Br[nt][0] = *(const bf16x8*)(wr_ + o0); Br[nt][1] = *(const bf16x8*)(wr_ + o0 + 32); Bi[nt][0] = *(const bf16x8*)(wi_ + o0); Bi[nt][1] = *(const bf16x8*)(wi_ + o0 + 32); }
; template <bool FINAL>
; __device__ __forceinline__ void rg_item(PREF p, int l, int item, LAS unsigned char* wl, int lane) {
;     ...
;         const float cw0 = p.conv_w[(l * 4 + 0) * 512 + ch], cw1 = p.conv_w[(l * 4 + 1) * 512 + ch], cw2 = p.conv_w[(l * 4 + 2) * 512 + ch], cw3 = p.conv_w[(l * 4 + 3) * 512 + ch];
;         const float cb = p.conv_b[l * 512 + ch];
;         float xv[67]; unsigned xr_[67];
; #pragma unroll
;         for (int i = 0; i < 67; ++i) { const int t = t0 - 2 + i; const int tc = t < 0 ? 0 : (t >= seqlen ? seqlen - 1 : t);
;             xr_[i] = P[(size_t)(seq_row0 + tc) * PW + ch]; }
;         __builtin_amdgcn_sched_barrier(0);
; #pragma unroll
;         for (int i = 0; i < 67; ++i) { const int t = t0 - 2 + i; const int tc = t < 0 ? 0 : (t >= seqlen ? seqlen - 1 : t); xv[i] = (t == tc) ? bf2f(xr_[i]) : 0.f; }
; #pragma unroll
;         for (int tt = 0; tt < 64; ++tt) { const float xc = xv[tt] * cw0 + xv[tt + 1] * cw1 + xv[tt + 2] * cw2 + xv[tt + 3] * cw3 + cb; sXc[tt * 72 + lane] = (bf16_t)f2bf(xc); }
	s_addc_u32 s83, s83, 0
	global_load_ushort v207, v234, s[82:83]
	s_add_u32 s82, s82, 0x1600
	s_addc_u32 s83, s83, 0
	global_load_ushort v208, v234, s[82:83]
	s_add_u32 s82, s82, 0x1600
	s_addc_u32 s83, s83, 0
	global_load_ushort v209, v234, s[82:83]
	s_add_u32 s82, s82, 0x1600
	s_addc_u32 s83, s83, 0
	global_load_ushort v210, v234, s[82:83]
	s_add_u32 s82, s82, 0x1600
	s_addc_u32 s83, s83, 0
	global_load_ushort v211, v234, s[82:83]
	s_add_u32 s82, s82, 0x1600
	s_addc_u32 s83, s83, 0
	global_load_ushort v212, v234, s[82:83]
	s_add_u32 s82, s82, 0x1600
	s_addc_u32 s83, s83, 0
	global_load_ushort v213, v234, s[82:83]
	s_add_u32 s82, s82, 0x1600
	s_addc_u32 s83, s83, 0
	global_load_ushort v214, v234, s[82:83]
	s_add_u32 s82, s82, 0x1600
	s_addc_u32 s83, s83, 0
	global_load_ushort v215, v234, s[82:83]
	s_add_u32 s82, s82, 0x1600
	s_addc_u32 s83, s83, 0
	global_load_ushort v216, v234, s[82:83]
	s_add_u32 s82, s82, 0x1600
	s_addc_u32 s83, s83, 0
	global_load_ushort v217, v234, s[82:83]
	s_add_u32 s82, s82, 0x1600
	s_addc_u32 s83, s83, 0
	global_load_ushort v218, v234, s[82:83]
	s_add_u32 s82, s82, 0x1600
	s_addc_u32 s83, s83, 0
	global_load_ushort v219, v234, s[82:83]
	s_add_u32 s82, s82, 0x1600
	s_addc_u32 s83, s83, 0
	global_load_ushort v222, v234, s[82:83]
	s_add_u32 s82, s82, 0x1600
	s_addc_u32 s83, s83, 0
	global_load_ushort v223, v234, s[82:83]
	s_add_u32 s82, s82, 0x1600
	s_addc_u32 s83, s83, 0
	global_load_ushort v140, v234, s[82:83]
	s_add_u32 s82, s82, 0x1600
	s_addc_u32 s83, s83, 0
	global_load_ushort v141, v234, s[82:83]
	s_add_u32 s82, s82, 0x1600
	s_addc_u32 s83, s83, 0
	global_load_ushort v232, v234, s[82:83]
	s_lshl_b32 s39, s57, 13
	s_add_u32 s72, s72, s39
	s_addc_u32 s73, s73, 0
	global_load_dword v40, v235, s[72:73]
	global_load_dword v41, v235, s[72:73] offset:2048
	s_add_u32 s72, s72, 0x1000
	s_addc_u32 s73, s73, 0
	global_load_dword v42, v235, s[72:73]
	global_load_dword v43, v235, s[72:73] offset:2048
	s_lshl_b32 s39, s57, 11
	s_add_u32 s74, s74, s39
	s_addc_u32 s75, s75, 0
	global_load_dword v44, v235, s[74:75]
	s_lshl_b32 s39, s57, 12
	s_add_u32 s76, s76, s39
	s_addc_u32 s77, s77, 0
	s_add_u32 s78, s78, s39
	s_addc_u32 s79, s79, 0
	s_add_u32 s80, s80, s39
	s_addc_u32 s81, s81, 0
	s_lshl_b32 s39, s57, 5
	s_add_i32 s39, s39, s7
	s_lshl_b32 s39, s39, 13
	s_add_u32 s92, s0, 0x300000
	s_addc_u32 s93, s1, 0
	s_add_u32 s92, s92, s39
	s_addc_u32 s93, s93, 0
	global_load_dword v45, v235, s[76:77]
	global_load_dword v46, v235, s[78:79]
	global_load_dword v47, v235, s[80:81]
	s_add_u32 s90, s92, 0x0
	s_addc_u32 s91, s93, 0
	global_load_dwordx4 v[80:83], v241, s[90:91]
	global_load_dwordx4 v[84:87], v241, s[90:91] offset:64
	global_load_dwordx4 v[88:91], v241, s[90:91] offset:2048
	global_load_dwordx4 v[92:95], v241, s[90:91] offset:2112
	s_add_u32 s90, s92, 0x1000
	s_addc_u32 s91, s93, 0
	global_load_dwordx4 v[96:99], v241, s[90:91]
	global_load_dwordx4 v[100:103], v241, s[90:91] offset:64
	global_load_dwordx4 v[104:107], v241, s[90:91] offset:2048
	global_load_dwordx4 v[108:111], v241, s[90:91] offset:2112
	s_add_u32 s90, s92, 0x10000
	s_addc_u32 s91, s93, 0
	global_load_dwordx4 v[112:115], v241, s[90:91]
	global_load_dwordx4 v[148:151], v241, s[90:91] offset:64
	global_load_dwordx4 v[120:123], v241, s[90:91] offset:2048
	global_load_dwordx4 v[124:127], v241, s[90:91] offset:2112
	s_add_u32 s90, s92, 0x11000
	s_addc_u32 s91, s93, 0
	global_load_dwordx4 v[128:131], v241, s[90:91]
	global_load_dwordx4 v[132:135], v241, s[90:91] offset:64
	global_load_dwordx4 v[136:139], v241, s[90:91] offset:2048
	global_load_dwordx4 v[228:231], v241, s[90:91] offset:2112
	s_waitcnt vmcnt(19)
	v_lshlrev_b32_e32 v158, 16, v158
	v_lshlrev_b32_e32 v159, 16, v159
	v_lshlrev_b32_e32 v160, 16, v160
	v_lshlrev_b32_e32 v161, 16, v161
	v_lshlrev_b32_e32 v162, 16, v162
	v_lshlrev_b32_e32 v163, 16, v163
	v_lshlrev_b32_e32 v164, 16, v164
	v_lshlrev_b32_e32 v165, 16, v165
	v_lshlrev_b32_e32 v166, 16, v166
	v_lshlrev_b32_e32 v167, 16, v167
	v_lshlrev_b32_e32 v168, 16, v168
	v_lshlrev_b32_e32 v169, 16, v169
	v_lshlrev_b32_e32 v170, 16, v170
	v_lshlrev_b32_e32 v171, 16, v171
	v_lshlrev_b32_e32 v172, 16, v172
	v_lshlrev_b32_e32 v173, 16, v173
	v_lshlrev_b32_e32 v174, 16, v174
	v_lshlrev_b32_e32 v175, 16, v175
	v_lshlrev_b32_e32 v176, 16, v176
	v_lshlrev_b32_e32 v177, 16, v177
	v_lshlrev_b32_e32 v178, 16, v178
	v_lshlrev_b32_e32 v179, 16, v179
	v_lshlrev_b32_e32 v180, 16, v180
	v_lshlrev_b32_e32 v181, 16, v181
	v_lshlrev_b32_e32 v182, 16, v182
	v_lshlrev_b32_e32 v183, 16, v183
	v_lshlrev_b32_e32 v184, 16, v184
	v_lshlrev_b32_e32 v185, 16, v185
	v_lshlrev_b32_e32 v186, 16, v186
	v_lshlrev_b32_e32 v187, 16, v187
	v_lshlrev_b32_e32 v188, 16, v188
	v_lshlrev_b32_e32 v189, 16, v189
	v_lshlrev_b32_e32 v190, 16, v190
	v_lshlrev_b32_e32 v191, 16, v191
	v_lshlrev_b32_e32 v192, 16, v192
	v_lshlrev_b32_e32 v193, 16, v193
	v_lshlrev_b32_e32 v194, 16, v194
	v_lshlrev_b32_e32 v195, 16, v195
	v_lshlrev_b32_e32 v196, 16, v196
	v_lshlrev_b32_e32 v197, 16, v197
	v_lshlrev_b32_e32 v198, 16, v198
	v_lshlrev_b32_e32 v199, 16, v199
	v_lshlrev_b32_e32 v200, 16, v200
	v_lshlrev_b32_e32 v201, 16, v201
	v_lshlrev_b32_e32 v202, 16, v202
	v_lshlrev_b32_e32 v203, 16, v203
	v_lshlrev_b32_e32 v204, 16, v204
	v_lshlrev_b32_e32 v205, 16, v205
	v_lshlrev_b32_e32 v206, 16, v206
	v_lshlrev_b32_e32 v207, 16, v207
	v_lshlrev_b32_e32 v208, 16, v208
	v_lshlrev_b32_e32 v209, 16, v209
	v_lshlrev_b32_e32 v210, 16, v210
	v_lshlrev_b32_e32 v211, 16, v211
	v_lshlrev_b32_e32 v212, 16, v212
	v_lshlrev_b32_e32 v213, 16, v213
	v_lshlrev_b32_e32 v214, 16, v214
	v_lshlrev_b32_e32 v215, 16, v215
	v_lshlrev_b32_e32 v216, 16, v216
; __device__ __forceinline__ unsigned f2bf(float f) { unsigned r; asm("v_cvt_pk_bf16_f32 %0, %1, %1" : "=v"(r) : "v"(f)); return r & 0xffffu; }
; template <bool FINAL>
; __device__ __forceinline__ void rg_item(PREF p, int l, int item, LAS unsigned char* wl, int lane) {
;     ...
;         for (int i = 0; i < 67; ++i) { const int t = t0 - 2 + i; const int tc = t < 0 ? 0 : (t >= seqlen ? seqlen - 1 : t); xv[i] = (t == tc) ? bf2f(xr_[i]) : 0.f; }
; #pragma unroll
;         for (int tt = 0; tt < 64; ++tt) { const float xc = xv[tt] * cw0 + xv[tt + 1] * cw1 + xv[tt + 2] * cw2 + xv[tt + 3] * cw3 + cb; sXc[tt * 72 + lane] = (bf16_t)f2bf(xc); }
	v_lshlrev_b32_e32 v217, 16, v217
	v_lshlrev_b32_e32 v218, 16, v218
	v_lshlrev_b32_e32 v219, 16, v219
	v_lshlrev_b32_e32 v222, 16, v222
	v_lshlrev_b32_e32 v223, 16, v223
	v_lshlrev_b32_e32 v140, 16, v140
	v_lshlrev_b32_e32 v141, 16, v141
	v_lshlrev_b32_e32 v232, 16, v232
	v_and_b32_e32 v158, s37, v158
	v_and_b32_e32 v159, s37, v159
	v_and_b32_e32 v232, s38, v232
	v_mul_f32_e32 v32, v41, v159
	v_mul_f32_e32 v33, v41, v160
	v_mul_f32_e32 v34, v41, v161
	v_mul_f32_e32 v35, v41, v162
	v_mul_f32_e32 v36, v41, v163
	v_mul_f32_e32 v37, v41, v164
	v_mul_f32_e32 v38, v41, v165
	v_mul_f32_e32 v39, v41, v166
	v_fmac_f32_e32 v32, v40, v158
	v_fmac_f32_e32 v33, v40, v159
	v_fmac_f32_e32 v34, v40, v160
	v_fmac_f32_e32 v35, v40, v161
	v_fmac_f32_e32 v36, v40, v162
	v_fmac_f32_e32 v37, v40, v163
	v_fmac_f32_e32 v38, v40, v164
	v_fmac_f32_e32 v39, v40, v165
	v_fmac_f32_e32 v32, v42, v160
	v_fmac_f32_e32 v33, v42, v161
	v_fmac_f32_e32 v34, v42, v162
	v_fmac_f32_e32 v35, v42, v163
	v_fmac_f32_e32 v36, v42, v164
	v_fmac_f32_e32 v37, v42, v165
	v_fmac_f32_e32 v38, v42, v166
	v_fmac_f32_e32 v39, v42, v167
	v_fmac_f32_e32 v32, v43, v161
	v_fmac_f32_e32 v33, v43, v162
	v_fmac_f32_e32 v34, v43, v163
	v_fmac_f32_e32 v35, v43, v164
	v_fmac_f32_e32 v36, v43, v165
	v_fmac_f32_e32 v37, v43, v166
	v_fmac_f32_e32 v38, v43, v167
	v_fmac_f32_e32 v39, v43, v168
	v_add_f32_e32 v32, v44, v32
	v_add_f32_e32 v33, v44, v33
	v_add_f32_e32 v34, v44, v34
	v_add_f32_e32 v35, v44, v35
	v_add_f32_e32 v36, v44, v36
	v_add_f32_e32 v37, v44, v37
	v_add_f32_e32 v38, v44, v38
	v_add_f32_e32 v39, v44, v39
	v_cvt_pk_bf16_f32 v32, v32, v33
	v_cvt_pk_bf16_f32 v34, v34, v35
	v_cvt_pk_bf16_f32 v36, v36, v37
	v_cvt_pk_bf16_f32 v38, v38, v39
	ds_write_b16 v240, v32 offset:0
	ds_write_b16_d16_hi v240, v32 offset:144
	ds_write_b16 v240, v34 offset:288
	ds_write_b16_d16_hi v240, v34 offset:432
	ds_write_b16 v240, v36 offset:576
	ds_write_b16_d16_hi v240, v36 offset:720
	ds_write_b16 v240, v38 offset:864
	ds_write_b16_d16_hi v240, v38 offset:1008
	v_mul_f32_e32 v32, v41, v167
	v_mul_f32_e32 v33, v41, v168
	v_mul_f32_e32 v34, v41, v169
	v_mul_f32_e32 v35, v41, v170
	v_mul_f32_e32 v36, v41, v171
	v_mul_f32_e32 v37, v41, v172
	v_mul_f32_e32 v38, v41, v173
	v_mul_f32_e32 v39, v41, v174
	v_fmac_f32_e32 v32, v40, v166
	v_fmac_f32_e32 v33, v40, v167
	v_fmac_f32_e32 v34, v40, v168
	v_fmac_f32_e32 v35, v40, v169
	v_fmac_f32_e32 v36, v40, v170
	v_fmac_f32_e32 v37, v40, v171
	v_fmac_f32_e32 v38, v40, v172
	v_fmac_f32_e32 v39, v40, v173
	v_fmac_f32_e32 v32, v42, v168
	v_fmac_f32_e32 v33, v42, v169
	v_fmac_f32_e32 v34, v42, v170
	v_fmac_f32_e32 v35, v42, v171
	v_fmac_f32_e32 v36, v42, v172
	v_fmac_f32_e32 v37, v42, v173
	v_fmac_f32_e32 v38, v42, v174
	v_fmac_f32_e32 v39, v42, v175
	v_fmac_f32_e32 v32, v43, v169
	v_fmac_f32_e32 v33, v43, v170
	v_fmac_f32_e32 v34, v43, v171
	v_fmac_f32_e32 v35, v43, v172
	v_fmac_f32_e32 v36, v43, v173
	v_fmac_f32_e32 v37, v43, v174
	v_fmac_f32_e32 v38, v43, v175
	v_fmac_f32_e32 v39, v43, v176
	v_add_f32_e32 v32, v44, v32
	v_add_f32_e32 v33, v44, v33
	v_add_f32_e32 v34, v44, v34
	v_add_f32_e32 v35, v44, v35
	v_add_f32_e32 v36, v44, v36
	v_add_f32_e32 v37, v44, v37
	v_add_f32_e32 v38, v44, v38
	v_add_f32_e32 v39, v44, v39
	v_cvt_pk_bf16_f32 v32, v32, v33
	v_cvt_pk_bf16_f32 v34, v34, v35
	v_cvt_pk_bf16_f32 v36, v36, v37
	v_cvt_pk_bf16_f32 v38, v38, v39
	ds_write_b16 v240, v32 offset:1152
	ds_write_b16_d16_hi v240, v32 offset:1296
	ds_write_b16 v240, v34 offset:1440
	ds_write_b16_d16_hi v240, v34 offset:1584
	ds_write_b16 v240, v36 offset:1728
	ds_write_b16_d16_hi v240, v36 offset:1872
	ds_write_b16 v240, v38 offset:2016
	ds_write_b16_d16_hi v240, v38 offset:2160
	v_mul_f32_e32 v32, v41, v175
	v_mul_f32_e32 v33, v41, v176
	v_mul_f32_e32 v34, v41, v177
	v_mul_f32_e32 v35, v41, v178
	v_mul_f32_e32 v36, v41, v179
	v_mul_f32_e32 v37, v41, v180
	v_mul_f32_e32 v38, v41, v181
	v_mul_f32_e32 v39, v41, v182
	v_fmac_f32_e32 v32, v40, v174
	v_fmac_f32_e32 v33, v40, v175
	v_fmac_f32_e32 v34, v40, v176
	v_fmac_f32_e32 v35, v40, v177
	v_fmac_f32_e32 v36, v40, v178
	v_fmac_f32_e32 v37, v40, v179
	v_fmac_f32_e32 v38, v40, v180
	v_fmac_f32_e32 v39, v40, v181
	v_fmac_f32_e32 v32, v42, v176
	v_fmac_f32_e32 v33, v42, v177
	v_fmac_f32_e32 v34, v42, v178
	v_fmac_f32_e32 v35, v42, v179
	v_fmac_f32_e32 v36, v42, v180
	v_fmac_f32_e32 v37, v42, v181
	v_fmac_f32_e32 v38, v42, v182
	v_fmac_f32_e32 v39, v42, v183
	v_fmac_f32_e32 v32, v43, v177
	v_fmac_f32_e32 v33, v43, v178
	v_fmac_f32_e32 v34, v43, v179
	v_fmac_f32_e32 v35, v43, v180
	v_fmac_f32_e32 v36, v43, v181
	v_fmac_f32_e32 v37, v43, v182
	v_fmac_f32_e32 v38, v43, v183
	v_fmac_f32_e32 v39, v43, v184
	v_add_f32_e32 v32, v44, v32
	v_add_f32_e32 v33, v44, v33
	v_add_f32_e32 v34, v44, v34
	v_add_f32_e32 v35, v44, v35
	v_add_f32_e32 v36, v44, v36
	v_add_f32_e32 v37, v44, v37
	v_add_f32_e32 v38, v44, v38
	v_add_f32_e32 v39, v44, v39
	v_cvt_pk_bf16_f32 v32, v32, v33
	v_cvt_pk_bf16_f32 v34, v34, v35
	v_cvt_pk_bf16_f32 v36, v36, v37
	v_cvt_pk_bf16_f32 v38, v38, v39
	ds_write_b16 v240, v32 offset:2304
	ds_write_b16_d16_hi v240, v32 offset:2448
	ds_write_b16 v240, v34 offset:2592
	ds_write_b16_d16_hi v240, v34 offset:2736
	ds_write_b16 v240, v36 offset:2880
	ds_write_b16_d16_hi v240, v36 offset:3024
	ds_write_b16 v240, v38 offset:3168
	ds_write_b16_d16_hi v240, v38 offset:3312
	v_mul_f32_e32 v32, v41, v183
	v_mul_f32_e32 v33, v41, v184
	v_mul_f32_e32 v34, v41, v185
	v_mul_f32_e32 v35, v41, v186
	v_mul_f32_e32 v36, v41, v187
	v_mul_f32_e32 v37, v41, v188
	v_mul_f32_e32 v38, v41, v189
	v_mul_f32_e32 v39, v41, v190
	v_fmac_f32_e32 v32, v40, v182
	v_fmac_f32_e32 v33, v40, v183
; __device__ __forceinline__ unsigned f2bf(float f) { unsigned r; asm("v_cvt_pk_bf16_f32 %0, %1, %1" : "=v"(r) : "v"(f)); return r & 0xffffu; }
; template <bool FINAL>
; __device__ __forceinline__ void rg_item(PREF p, int l, int item, LAS unsigned char* wl, int lane) {
;     ...
;         for (int tt = 0; tt < 64; ++tt) { const float xc = xv[tt] * cw0 + xv[tt + 1] * cw1 + xv[tt + 2] * cw2 + xv[tt + 3] * cw3 + cb; sXc[tt * 72 + lane] = (bf16_t)f2bf(xc); }
	v_fmac_f32_e32 v34, v40, v184
	v_fmac_f32_e32 v35, v40, v185
	v_fmac_f32_e32 v36, v40, v186
	v_fmac_f32_e32 v37, v40, v187
	v_fmac_f32_e32 v38, v40, v188
	v_fmac_f32_e32 v39, v40, v189
	v_fmac_f32_e32 v32, v42, v184
	v_fmac_f32_e32 v33, v42, v185
	v_fmac_f32_e32 v34, v42, v186
	v_fmac_f32_e32 v35, v42, v187
	v_fmac_f32_e32 v36, v42, v188
	v_fmac_f32_e32 v37, v42, v189
	v_fmac_f32_e32 v38, v42, v190
	v_fmac_f32_e32 v39, v42, v191
	v_fmac_f32_e32 v32, v43, v185
	v_fmac_f32_e32 v33, v43, v186
	v_fmac_f32_e32 v34, v43, v187
	v_fmac_f32_e32 v35, v43, v188
	v_fmac_f32_e32 v36, v43, v189
	v_fmac_f32_e32 v37, v43, v190
	v_fmac_f32_e32 v38, v43, v191
	v_fmac_f32_e32 v39, v43, v192
	v_add_f32_e32 v32, v44, v32
	v_add_f32_e32 v33, v44, v33
	v_add_f32_e32 v34, v44, v34
	v_add_f32_e32 v35, v44, v35
	v_add_f32_e32 v36, v44, v36
	v_add_f32_e32 v37, v44, v37
	v_add_f32_e32 v38, v44, v38
	v_add_f32_e32 v39, v44, v39
	v_cvt_pk_bf16_f32 v32, v32, v33
	v_cvt_pk_bf16_f32 v34, v34, v35
	v_cvt_pk_bf16_f32 v36, v36, v37
	v_cvt_pk_bf16_f32 v38, v38, v39
	ds_write_b16 v240, v32 offset:3456
	ds_write_b16_d16_hi v240, v32 offset:3600
	ds_write_b16 v240, v34 offset:3744
	ds_write_b16_d16_hi v240, v34 offset:3888
	ds_write_b16 v240, v36 offset:4032
	ds_write_b16_d16_hi v240, v36 offset:4176
	ds_write_b16 v240, v38 offset:4320
	ds_write_b16_d16_hi v240, v38 offset:4464
	v_mul_f32_e32 v32, v41, v191
	v_mul_f32_e32 v33, v41, v192
	v_mul_f32_e32 v34, v41, v193
	v_mul_f32_e32 v35, v41, v194
	v_mul_f32_e32 v36, v41, v195
	v_mul_f32_e32 v37, v41, v196
	v_mul_f32_e32 v38, v41, v197
	v_mul_f32_e32 v39, v41, v198
	v_fmac_f32_e32 v32, v40, v190
	v_fmac_f32_e32 v33, v40, v191
	v_fmac_f32_e32 v34, v40, v192
	v_fmac_f32_e32 v35, v40, v193
	v_fmac_f32_e32 v36, v40, v194
	v_fmac_f32_e32 v37, v40, v195
	v_fmac_f32_e32 v38, v40, v196
	v_fmac_f32_e32 v39, v40, v197
	v_fmac_f32_e32 v32, v42, v192
	v_fmac_f32_e32 v33, v42, v193
	v_fmac_f32_e32 v34, v42, v194
	v_fmac_f32_e32 v35, v42, v195
	v_fmac_f32_e32 v36, v42, v196
	v_fmac_f32_e32 v37, v42, v197
	v_fmac_f32_e32 v38, v42, v198
	v_fmac_f32_e32 v39, v42, v199
	v_fmac_f32_e32 v32, v43, v193
	v_fmac_f32_e32 v33, v43, v194
	v_fmac_f32_e32 v34, v43, v195
	v_fmac_f32_e32 v35, v43, v196
	v_fmac_f32_e32 v36, v43, v197
	v_fmac_f32_e32 v37, v43, v198
	v_fmac_f32_e32 v38, v43, v199
	v_fmac_f32_e32 v39, v43, v200
	v_add_f32_e32 v32, v44, v32
	v_add_f32_e32 v33, v44, v33
	v_add_f32_e32 v34, v44, v34
	v_add_f32_e32 v35, v44, v35
	v_add_f32_e32 v36, v44, v36
	v_add_f32_e32 v37, v44, v37
	v_add_f32_e32 v38, v44, v38
	v_add_f32_e32 v39, v44, v39
	v_cvt_pk_bf16_f32 v32, v32, v33
	v_cvt_pk_bf16_f32 v34, v34, v35
	v_cvt_pk_bf16_f32 v36, v36, v37
	v_cvt_pk_bf16_f32 v38, v38, v39
	ds_write_b16 v240, v32 offset:4608
	ds_write_b16_d16_hi v240, v32 offset:4752
	ds_write_b16 v240, v34 offset:4896
	ds_write_b16_d16_hi v240, v34 offset:5040
	ds_write_b16 v240, v36 offset:5184
	ds_write_b16_d16_hi v240, v36 offset:5328
	ds_write_b16 v240, v38 offset:5472
	ds_write_b16_d16_hi v240, v38 offset:5616
	v_mul_f32_e32 v32, v41, v199
	v_mul_f32_e32 v33, v41, v200
	v_mul_f32_e32 v34, v41, v201
	v_mul_f32_e32 v35, v41, v202
	v_mul_f32_e32 v36, v41, v203
	v_mul_f32_e32 v37, v41, v204
	v_mul_f32_e32 v38, v41, v205
	v_mul_f32_e32 v39, v41, v206
	v_fmac_f32_e32 v32, v40, v198
	v_fmac_f32_e32 v33, v40, v199
	v_fmac_f32_e32 v34, v40, v200
	v_fmac_f32_e32 v35, v40, v201
	v_fmac_f32_e32 v36, v40, v202
	v_fmac_f32_e32 v37, v40, v203
	v_fmac_f32_e32 v38, v40, v204
	v_fmac_f32_e32 v39, v40, v205
	v_fmac_f32_e32 v32, v42, v200
	v_fmac_f32_e32 v33, v42, v201
	v_fmac_f32_e32 v34, v42, v202
	v_fmac_f32_e32 v35, v42, v203
	v_fmac_f32_e32 v36, v42, v204
	v_fmac_f32_e32 v37, v42, v205
	v_fmac_f32_e32 v38, v42, v206
	v_fmac_f32_e32 v39, v42, v207
	v_fmac_f32_e32 v32, v43, v201
	v_fmac_f32_e32 v33, v43, v202
	v_fmac_f32_e32 v34, v43, v203
	v_fmac_f32_e32 v35, v43, v204
	v_fmac_f32_e32 v36, v43, v205
	v_fmac_f32_e32 v37, v43, v206
	v_fmac_f32_e32 v38, v43, v207
	v_fmac_f32_e32 v39, v43, v208
	v_add_f32_e32 v32, v44, v32
	v_add_f32_e32 v33, v44, v33
	v_add_f32_e32 v34, v44, v34
	v_add_f32_e32 v35, v44, v35
	v_add_f32_e32 v36, v44, v36
	v_add_f32_e32 v37, v44, v37
	v_add_f32_e32 v38, v44, v38
	v_add_f32_e32 v39, v44, v39
	v_cvt_pk_bf16_f32 v32, v32, v33
	v_cvt_pk_bf16_f32 v34, v34, v35
	v_cvt_pk_bf16_f32 v36, v36, v37
	v_cvt_pk_bf16_f32 v38, v38, v39
	ds_write_b16 v240, v32 offset:5760
	ds_write_b16_d16_hi v240, v32 offset:5904
	ds_write_b16 v240, v34 offset:6048
	ds_write_b16_d16_hi v240, v34 offset:6192
	ds_write_b16 v240, v36 offset:6336
	ds_write_b16_d16_hi v240, v36 offset:6480
	ds_write_b16 v240, v38 offset:6624
	ds_write_b16_d16_hi v240, v38 offset:6768
	v_mul_f32_e32 v32, v41, v207
	v_mul_f32_e32 v33, v41, v208
	v_mul_f32_e32 v34, v41, v209
	v_mul_f32_e32 v35, v41, v210
	v_mul_f32_e32 v36, v41, v211
	v_mul_f32_e32 v37, v41, v212
	v_mul_f32_e32 v38, v41, v213
	v_mul_f32_e32 v39, v41, v214
	v_fmac_f32_e32 v32, v40, v206
	v_fmac_f32_e32 v33, v40, v207
	v_fmac_f32_e32 v34, v40, v208
	v_fmac_f32_e32 v35, v40, v209
	v_fmac_f32_e32 v36, v40, v210
	v_fmac_f32_e32 v37, v40, v211
	v_fmac_f32_e32 v38, v40, v212
	v_fmac_f32_e32 v39, v40, v213
	v_fmac_f32_e32 v32, v42, v208
	v_fmac_f32_e32 v33, v42, v209
	v_fmac_f32_e32 v34, v42, v210
	v_fmac_f32_e32 v35, v42, v211
	v_fmac_f32_e32 v36, v42, v212
	v_fmac_f32_e32 v37, v42, v213
	v_fmac_f32_e32 v38, v42, v214
	v_fmac_f32_e32 v39, v42, v215
	v_fmac_f32_e32 v32, v43, v209
	v_fmac_f32_e32 v33, v43, v210
	v_fmac_f32_e32 v34, v43, v211
	v_fmac_f32_e32 v35, v43, v212
	v_fmac_f32_e32 v36, v43, v213
	v_fmac_f32_e32 v37, v43, v214
	v_fmac_f32_e32 v38, v43, v215
; template <bool FINAL, int D>
; __device__ __forceinline__ void rg_dir(PREF p, int l, int h, int ch, int sidx, int rowbase  , LAS bf16_t* sXc, LAS float* stg, int lane) {
;     ...
;     const float ba = p.rg_ba[(l * 2 + D) * 512 + ch], bi = p.rg_bi[(l * 2 + D) * 512 + ch], lam = p.rg_lam[(l * 2 + D) * 512 + ch];
;     const float e_ = __expf(-lam), u_ = 1.f + e_;
;     const float l1p = (u_ == 1.f) ? e_ : __logf(u_) * e_ * rcpf_(u_ - 1.f);
;     const float sp8 = -8.f * 1.4426950408889634f * l1p;
;     float hc = FINAL ? RGC[sidx] : 0.f, Ap = 1.f;
;     bf16x8 Br[4][2], Bi[4][2];
; #pragma unroll
;     for (int nt = 0; nt < 4; ++nt) { const int o0 = (nt * 16 + (lane & 15)) * 64 + (lane >> 4) * 8;
;         Br[nt][0] = *(const bf16x8*)(wr_ + o0); Br[nt][1] = *(const bf16x8*)(wr_ + o0 + 32); Bi[nt][0] = *(const bf16x8*)(wi_ + o0); Bi[nt][1] = *(const bf16x8*)(wi_ + o0 + 32); }
;     if (FINAL && D == 1) asm volatile("s_waitcnt vmcnt(0)" ::: "memory");
; #pragma unroll 1
;     for (int mi = 0; mi < 4; ++mi) { const int mt = D ? 3 - mi : mi;
;         float grv[16], hfv[16];
;         if (FINAL && D == 1) {
; #pragma unroll
;             for (int ti = 0; ti < 16; ++ti) { const size_t row = (size_t)(rowbase + mt * 16 + 15 - ti); grv[ti] = __builtin_bit_cast(float, (unsigned)P[row * PW + 512 + ch]); hfv[ti] = __builtin_bit_cast(float, (unsigned)TMP[row * 512 + ch]); }
;             __builtin_amdgcn_sched_barrier(0);
; #pragma unroll
;             for (int ti = 0; ti < 16; ++ti) { grv[ti] = bf2f(__builtin_bit_cast(unsigned, grv[ti])); hfv[ti] = bf2f(__builtin_bit_cast(unsigned, hfv[ti])); }
;         }
;         const bf16x8 A0 = *(const LAS bf16x8*)(sXc + (mt * 16 + (lane & 15)) * 72 + (lane >> 4) * 8), A1 = *(const LAS bf16x8*)(sXc + (mt * 16 + (lane & 15)) * 72 + 32 + (lane >> 4) * 8);
;         f32x4 ar[4], ai[4];
; #pragma unroll
;         for (int nt = 0; nt < 4; ++nt) { const f32x4 z = {0.f, 0.f, 0.f, 0.f};
;             ar[nt] = mfma16(A0, Br[nt][0], z); ar[nt] = mfma16(A1, Br[nt][1], ar[nt]); ai[nt] = mfma16(A0, Bi[nt][0], z); ai[nt] = mfma16(A1, Bi[nt][1], ai[nt]); }
;         WAVE_SYNC();
; #pragma unroll
;         for (int nt = 0; nt < 4; ++nt)
; #pragma unroll
;             for (int j = 0; j < 4; ++j) { const int o = ((lane >> 4) * 4 + j) * 64 + nt * 16 + (lane & 15); stg[o] = ar[nt][j]; stg[1024 + o] = ai[nt][j]; }
;         WAVE_SYNC();
	v_fmac_f32_e32 v39, v43, v216
	v_add_f32_e32 v32, v44, v32
	v_add_f32_e32 v33, v44, v33
	v_add_f32_e32 v34, v44, v34
	v_add_f32_e32 v35, v44, v35
	v_add_f32_e32 v36, v44, v36
	v_add_f32_e32 v37, v44, v37
	v_add_f32_e32 v38, v44, v38
	v_add_f32_e32 v39, v44, v39
	v_cvt_pk_bf16_f32 v32, v32, v33
	v_cvt_pk_bf16_f32 v34, v34, v35
	v_cvt_pk_bf16_f32 v36, v36, v37
	v_cvt_pk_bf16_f32 v38, v38, v39
	ds_write_b16 v240, v32 offset:6912
	ds_write_b16_d16_hi v240, v32 offset:7056
	ds_write_b16 v240, v34 offset:7200
	ds_write_b16_d16_hi v240, v34 offset:7344
	ds_write_b16 v240, v36 offset:7488
	ds_write_b16_d16_hi v240, v36 offset:7632
	ds_write_b16 v240, v38 offset:7776
	ds_write_b16_d16_hi v240, v38 offset:7920
	v_mul_f32_e32 v32, v41, v215
	v_mul_f32_e32 v33, v41, v216
	v_mul_f32_e32 v34, v41, v217
	v_mul_f32_e32 v35, v41, v218
	v_mul_f32_e32 v36, v41, v219
	v_mul_f32_e32 v37, v41, v222
	v_mul_f32_e32 v38, v41, v223
	v_mul_f32_e32 v39, v41, v140
	v_fmac_f32_e32 v32, v40, v214
	v_fmac_f32_e32 v33, v40, v215
	v_fmac_f32_e32 v34, v40, v216
	v_fmac_f32_e32 v35, v40, v217
	v_fmac_f32_e32 v36, v40, v218
	v_fmac_f32_e32 v37, v40, v219
	v_fmac_f32_e32 v38, v40, v222
	v_fmac_f32_e32 v39, v40, v223
	v_fmac_f32_e32 v32, v42, v216
	v_fmac_f32_e32 v33, v42, v217
	v_fmac_f32_e32 v34, v42, v218
	v_fmac_f32_e32 v35, v42, v219
	v_fmac_f32_e32 v36, v42, v222
	v_fmac_f32_e32 v37, v42, v223
	v_fmac_f32_e32 v38, v42, v140
	v_fmac_f32_e32 v39, v42, v141
	v_fmac_f32_e32 v32, v43, v217
	v_fmac_f32_e32 v33, v43, v218
	v_fmac_f32_e32 v34, v43, v219
	v_fmac_f32_e32 v35, v43, v222
	v_fmac_f32_e32 v36, v43, v223
	v_fmac_f32_e32 v37, v43, v140
	v_fmac_f32_e32 v38, v43, v141
	v_fmac_f32_e32 v39, v43, v232
	v_add_f32_e32 v32, v44, v32
	v_add_f32_e32 v33, v44, v33
	v_add_f32_e32 v34, v44, v34
	v_add_f32_e32 v35, v44, v35
	v_add_f32_e32 v36, v44, v36
	v_add_f32_e32 v37, v44, v37
	v_add_f32_e32 v38, v44, v38
	v_add_f32_e32 v39, v44, v39
	v_cvt_pk_bf16_f32 v32, v32, v33
	v_cvt_pk_bf16_f32 v34, v34, v35
	v_cvt_pk_bf16_f32 v36, v36, v37
	v_cvt_pk_bf16_f32 v38, v38, v39
	ds_write_b16 v240, v32 offset:8064
	ds_write_b16_d16_hi v240, v32 offset:8208
	ds_write_b16 v240, v34 offset:8352
	ds_write_b16_d16_hi v240, v34 offset:8496
	ds_write_b16 v240, v36 offset:8640
	ds_write_b16_d16_hi v240, v36 offset:8784
	ds_write_b16 v240, v38 offset:8928
	ds_write_b16_d16_hi v240, v38 offset:9072
	v_mov_b32_e32 v248, 0xbfb8aa3b
	v_mov_b32_e32 v249, 0xbfb8aa3b
	s_waitcnt vmcnt(16)
	s_mov_b32 s8, 0x800000
	s_mov_b32 s9, 0x3f317217
	s_mov_b32 s14, 0x7f800000
	v_mul_f32_e32 v32, 0xbfb8aa3b, v45
	v_exp_f32_e32 v32, v32
	s_nop 0
	v_add_f32_e32 v33, 1.0, v32
	v_cmp_gt_f32_e32 vcc, s8, v33
	s_nop 1
	v_cndmask_b32_e64 v34, 0, 32, vcc
	v_ldexp_f32 v34, v33, v34
	v_log_f32_e32 v34, v34
	v_cndmask_b32_e32 v36, 0, v226, vcc
	v_cmp_eq_f32_e32 vcc, 1.0, v33
	v_mul_f32_e32 v35, 0x3f317217, v34
	v_fma_f32 v35, v34, s9, -v35
	v_fmac_f32_e32 v35, 0x3377d1cf, v34
	v_fmac_f32_e32 v35, 0x3f317217, v34
	v_cmp_lt_f32_e64 s[10:11], |v34|, s14
	s_nop 1
	v_cndmask_b32_e64 v34, v34, v35, s[10:11]
	v_add_f32_e32 v35, -1.0, v33
	v_rcp_f32_e32 v35, v35
	v_sub_f32_e32 v34, v34, v36
	v_mul_f32_e32 v34, v32, v34
	v_mul_f32_e32 v34, v34, v35
	v_cndmask_b32_e32 v32, v34, v32, vcc
	v_mul_f32_e32 v246, 0xc138aa3b, v32
	v_mov_b32_e32 v247, v246
	v_mul_f32_e32 v242, 0xbfb8aa3b, v46
	v_mul_f32_e32 v244, 0xbfb8aa3b, v47
	v_mov_b32_e32 v243, v242
	v_mov_b32_e32 v245, v244
	v_mov_b32_e32 v250, 0
	v_mov_b32_e32 v232, 1.0
	s_waitcnt vmcnt(0)
	ds_read_b128 v[32:35], v236 offset:0
	ds_read_b128 v[36:39], v236 offset:64
	s_waitcnt lgkmcnt(0)
	v_mfma_f32_16x16x32_bf16 v[0:3], v[32:35], v[80:83], 0
	v_mfma_f32_16x16x32_bf16 v[4:7], v[32:35], v[88:91], 0
	v_mfma_f32_16x16x32_bf16 v[8:11], v[32:35], v[96:99], 0
	v_mfma_f32_16x16x32_bf16 v[12:15], v[32:35], v[104:107], 0
	v_mfma_f32_16x16x32_bf16 v[16:19], v[32:35], v[112:115], 0
	v_mfma_f32_16x16x32_bf16 v[20:23], v[32:35], v[120:123], 0
	v_mfma_f32_16x16x32_bf16 v[24:27], v[32:35], v[128:131], 0
	v_mfma_f32_16x16x32_bf16 v[28:31], v[32:35], v[136:139], 0
	v_mfma_f32_16x16x32_bf16 v[0:3], v[36:39], v[84:87], v[0:3]
	v_mfma_f32_16x16x32_bf16 v[4:7], v[36:39], v[92:95], v[4:7]
	v_mfma_f32_16x16x32_bf16 v[8:11], v[36:39], v[100:103], v[8:11]
	v_mfma_f32_16x16x32_bf16 v[12:15], v[36:39], v[108:111], v[12:15]
	v_mfma_f32_16x16x32_bf16 v[16:19], v[36:39], v[148:151], v[16:19]
	v_mfma_f32_16x16x32_bf16 v[20:23], v[36:39], v[124:127], v[20:23]
	v_mfma_f32_16x16x32_bf16 v[24:27], v[36:39], v[132:135], v[24:27]
	v_mfma_f32_16x16x32_bf16 v[28:31], v[36:39], v[228:231], v[28:31]
	s_nop 3
	ds_write2_b32 v237, v0, v4 offset0:0 offset1:16
	ds_write2_b32 v237, v8, v12 offset0:32 offset1:48
	ds_write2_b32 v237, v1, v5 offset0:64 offset1:80
	ds_write2_b32 v237, v9, v13 offset0:96 offset1:112
	ds_write2_b32 v237, v2, v6 offset0:128 offset1:144
	ds_write2_b32 v237, v10, v14 offset0:160 offset1:176
	ds_write2_b32 v237, v3, v7 offset0:192 offset1:208
	ds_write2_b32 v237, v11, v15 offset0:224 offset1:240
	ds_write2_b32 v238, v16, v20 offset0:0 offset1:16
	ds_write2_b32 v238, v24, v28 offset0:32 offset1:48
	ds_write2_b32 v238, v17, v21 offset0:64 offset1:80
	ds_write2_b32 v238, v25, v29 offset0:96 offset1:112
	ds_write2_b32 v238, v18, v22 offset0:128 offset1:144
	ds_write2_b32 v238, v26, v30 offset0:160 offset1:176
	ds_write2_b32 v238, v19, v23 offset0:192 offset1:208
	ds_write2_b32 v238, v27, v31 offset0:224 offset1:240
	s_waitcnt lgkmcnt(0)
; __device__ __forceinline__ float sigmoid_f(float x) { return rcpf_(1.f + __expf(-x)); }
; __device__ __forceinline__ float gelu_tanh_f(float x) { const float y = 0.7978845608028654f * (x + 0.044715f * x * x * x); return x * sigmoid_f(2.f * y); }
; template <bool FINAL, int D>
; __device__ __forceinline__ void rg_dir(PREF p, int l, int h, int ch, int sidx, int rowbase  , LAS bf16_t* sXc, LAS float* stg, int lane) {
;     ...
;         float av[16], iv[16];
; #pragma unroll
;         for (int ti = 0; ti < 16; ++ti) { const int tk = D ? 15 - ti : ti;
;             const float zr = stg[tk * 64 + lane] + ba, zi = stg[1024 + tk * 64 + lane] + bi;
;             const float r = sigmoid_f(zr), ig = sigmoid_f(zi);
;             const float a = __builtin_amdgcn_exp2f(r * sp8);
;             const float xc = bf2f(sXc[(mt * 16 + tk) * 72 + lane]);
;             av[ti] = a; iv[ti] = __builtin_amdgcn_sqrtf(fmaxf(1.f - a * a, 0.f)) * ig * xc;
;             if (FINAL && D == 1) grv[ti] = gelu_tanh_f(grv[ti]);
;         }
	ds_read2st64_b32 v[0:1], v239 offset0:36 offset1:37
	ds_read2st64_b32 v[2:3], v239 offset0:38 offset1:39
	ds_read2st64_b32 v[4:5], v239 offset0:40 offset1:41
	ds_read2st64_b32 v[6:7], v239 offset0:42 offset1:43
	ds_read2st64_b32 v[8:9], v239 offset0:44 offset1:45
	ds_read2st64_b32 v[10:11], v239 offset0:46 offset1:47
	ds_read2st64_b32 v[12:13], v239 offset0:48 offset1:49
	ds_read2st64_b32 v[14:15], v239 offset0:50 offset1:51
	ds_read2st64_b32 v[16:17], v239 offset0:52 offset1:53
	ds_read2st64_b32 v[18:19], v239 offset0:54 offset1:55
	ds_read2st64_b32 v[20:21], v239 offset0:56 offset1:57
	ds_read2st64_b32 v[22:23], v239 offset0:58 offset1:59
	ds_read2st64_b32 v[24:25], v239 offset0:60 offset1:61
	ds_read2st64_b32 v[26:27], v239 offset0:62 offset1:63
	ds_read2st64_b32 v[28:29], v239 offset0:64 offset1:65
	ds_read2st64_b32 v[30:31], v239 offset0:66 offset1:67
	ds_read_u16 v48, v240 offset:0
	ds_read_u16 v49, v240 offset:144
	ds_read_u16 v50, v240 offset:288
	ds_read_u16 v51, v240 offset:432
	ds_read_u16 v52, v240 offset:576
	ds_read_u16 v53, v240 offset:720
	ds_read_u16 v54, v240 offset:864
	ds_read_u16 v55, v240 offset:1008
	ds_read_u16 v56, v240 offset:1152
	ds_read_u16 v57, v240 offset:1296
	ds_read_u16 v58, v240 offset:1440
	ds_read_u16 v59, v240 offset:1584
	ds_read_u16 v60, v240 offset:1728
	ds_read_u16 v61, v240 offset:1872
	ds_read_u16 v62, v240 offset:2016
	ds_read_u16 v63, v240 offset:2160
	s_waitcnt lgkmcnt(0)
	v_pk_fma_f32 v[0:1], v[0:1], v[248:249], v[242:243]
	v_pk_fma_f32 v[2:3], v[2:3], v[248:249], v[242:243]
	v_pk_fma_f32 v[4:5], v[4:5], v[248:249], v[242:243]
	v_pk_fma_f32 v[6:7], v[6:7], v[248:249], v[242:243]
	v_pk_fma_f32 v[8:9], v[8:9], v[248:249], v[242:243]
	v_pk_fma_f32 v[10:11], v[10:11], v[248:249], v[242:243]
	v_pk_fma_f32 v[12:13], v[12:13], v[248:249], v[242:243]
	v_pk_fma_f32 v[14:15], v[14:15], v[248:249], v[242:243]
	v_pk_fma_f32 v[16:17], v[16:17], v[248:249], v[244:245]
	v_pk_fma_f32 v[18:19], v[18:19], v[248:249], v[244:245]
	v_pk_fma_f32 v[20:21], v[20:21], v[248:249], v[244:245]
	v_pk_fma_f32 v[22:23], v[22:23], v[248:249], v[244:245]
	v_pk_fma_f32 v[24:25], v[24:25], v[248:249], v[244:245]
	v_pk_fma_f32 v[26:27], v[26:27], v[248:249], v[244:245]
	v_pk_fma_f32 v[28:29], v[28:29], v[248:249], v[244:245]
	v_pk_fma_f32 v[30:31], v[30:31], v[248:249], v[244:245]
	v_exp_f32_e32 v0, v0
	v_exp_f32_e32 v1, v1
	v_exp_f32_e32 v2, v2
	v_exp_f32_e32 v3, v3
	v_exp_f32_e32 v4, v4
	v_exp_f32_e32 v5, v5
	v_exp_f32_e32 v6, v6
	v_exp_f32_e32 v7, v7
	v_exp_f32_e32 v8, v8
	v_exp_f32_e32 v9, v9
	v_exp_f32_e32 v10, v10
	v_exp_f32_e32 v11, v11
	v_exp_f32_e32 v12, v12
	v_exp_f32_e32 v13, v13
	v_exp_f32_e32 v14, v14
	v_exp_f32_e32 v15, v15
	v_exp_f32_e32 v16, v16
	v_exp_f32_e32 v17, v17
	v_exp_f32_e32 v18, v18
	v_exp_f32_e32 v19, v19
	v_exp_f32_e32 v20, v20
	v_exp_f32_e32 v21, v21
	v_exp_f32_e32 v22, v22
	v_exp_f32_e32 v23, v23
	v_exp_f32_e32 v24, v24
	v_exp_f32_e32 v25, v25
	v_exp_f32_e32 v26, v26
	v_exp_f32_e32 v27, v27
	v_exp_f32_e32 v28, v28
	v_exp_f32_e32 v29, v29
	v_exp_f32_e32 v30, v30
	v_exp_f32_e32 v31, v31
	v_pk_add_f32 v[0:1], v[0:1], 1.0 op_sel_hi:[1,0]
	v_pk_add_f32 v[2:3], v[2:3], 1.0 op_sel_hi:[1,0]
	v_pk_add_f32 v[4:5], v[4:5], 1.0 op_sel_hi:[1,0]
	v_pk_add_f32 v[6:7], v[6:7], 1.0 op_sel_hi:[1,0]
	v_pk_add_f32 v[8:9], v[8:9], 1.0 op_sel_hi:[1,0]
	v_pk_add_f32 v[10:11], v[10:11], 1.0 op_sel_hi:[1,0]
	v_pk_add_f32 v[12:13], v[12:13], 1.0 op_sel_hi:[1,0]
	v_pk_add_f32 v[14:15], v[14:15], 1.0 op_sel_hi:[1,0]
	v_pk_add_f32 v[16:17], v[16:17], 1.0 op_sel_hi:[1,0]
	v_pk_add_f32 v[18:19], v[18:19], 1.0 op_sel_hi:[1,0]
	v_pk_add_f32 v[20:21], v[20:21], 1.0 op_sel_hi:[1,0]
	v_pk_add_f32 v[22:23], v[22:23], 1.0 op_sel_hi:[1,0]
	v_pk_add_f32 v[24:25], v[24:25], 1.0 op_sel_hi:[1,0]
	v_pk_add_f32 v[26:27], v[26:27], 1.0 op_sel_hi:[1,0]
	v_pk_add_f32 v[28:29], v[28:29], 1.0 op_sel_hi:[1,0]
	v_pk_add_f32 v[30:31], v[30:31], 1.0 op_sel_hi:[1,0]
	v_rcp_f32_e32 v0, v0
	v_rcp_f32_e32 v1, v1
	v_rcp_f32_e32 v2, v2
	v_rcp_f32_e32 v3, v3
	v_rcp_f32_e32 v4, v4
	v_rcp_f32_e32 v5, v5
	v_rcp_f32_e32 v6, v6
	v_rcp_f32_e32 v7, v7
	v_rcp_f32_e32 v8, v8
	v_rcp_f32_e32 v9, v9
	v_rcp_f32_e32 v10, v10
	v_rcp_f32_e32 v11, v11
	v_rcp_f32_e32 v12, v12
	v_rcp_f32_e32 v13, v13
	v_rcp_f32_e32 v14, v14
	v_rcp_f32_e32 v15, v15
	v_rcp_f32_e32 v16, v16
	v_rcp_f32_e32 v17, v17
	v_rcp_f32_e32 v18, v18
	v_rcp_f32_e32 v19, v19
	v_rcp_f32_e32 v20, v20
	v_rcp_f32_e32 v21, v21
	v_rcp_f32_e32 v22, v22
	v_rcp_f32_e32 v23, v23
	v_rcp_f32_e32 v24, v24
	v_rcp_f32_e32 v25, v25
	v_rcp_f32_e32 v26, v26
	v_rcp_f32_e32 v27, v27
	v_rcp_f32_e32 v28, v28
	v_rcp_f32_e32 v29, v29
	v_rcp_f32_e32 v30, v30
	v_rcp_f32_e32 v31, v31
	v_pk_mul_f32 v[0:1], v[246:247], v[0:1]
	v_pk_mul_f32 v[2:3], v[246:247], v[2:3]
	v_pk_mul_f32 v[4:5], v[246:247], v[4:5]
	v_pk_mul_f32 v[6:7], v[246:247], v[6:7]
	v_pk_mul_f32 v[8:9], v[246:247], v[8:9]
	v_pk_mul_f32 v[10:11], v[246:247], v[10:11]
	v_pk_mul_f32 v[12:13], v[246:247], v[12:13]
	v_pk_mul_f32 v[14:15], v[246:247], v[14:15]
	v_lshlrev_b32_e32 v48, 16, v48
	v_lshlrev_b32_e32 v49, 16, v49
	v_lshlrev_b32_e32 v50, 16, v50
	v_lshlrev_b32_e32 v51, 16, v51
	v_lshlrev_b32_e32 v52, 16, v52
	v_lshlrev_b32_e32 v53, 16, v53
	v_lshlrev_b32_e32 v54, 16, v54
	v_lshlrev_b32_e32 v55, 16, v55
	v_lshlrev_b32_e32 v56, 16, v56
	v_lshlrev_b32_e32 v57, 16, v57
	v_lshlrev_b32_e32 v58, 16, v58
	v_lshlrev_b32_e32 v59, 16, v59
	v_lshlrev_b32_e32 v60, 16, v60
	v_lshlrev_b32_e32 v61, 16, v61
	v_lshlrev_b32_e32 v62, 16, v62
	v_lshlrev_b32_e32 v63, 16, v63
	v_exp_f32_e32 v0, v0
	v_exp_f32_e32 v1, v1
	v_exp_f32_e32 v2, v2
	v_exp_f32_e32 v3, v3
	v_exp_f32_e32 v4, v4
; #define LAS __attribute__((address_space(3)))
; #define WAVE_SYNC() asm volatile("s_waitcnt lgkmcnt(0)" ::: "memory")
; __device__ __forceinline__ unsigned f2bf(float f) { unsigned r; asm("v_cvt_pk_bf16_f32 %0, %1, %1" : "=v"(r) : "v"(f)); return r & 0xffffu; }
; __device__ __forceinline__ float sigmoid_f(float x) { return rcpf_(1.f + __expf(-x)); }
; template <bool FINAL, int D>
; __device__ __forceinline__ void rg_dir(PREF p, int l, int h, int ch, int sidx, int rowbase  , LAS bf16_t* sXc, LAS float* stg, int lane) {
;     ...
;         const bf16x8 A0 = *(const LAS bf16x8*)(sXc + (mt * 16 + (lane & 15)) * 72 + (lane >> 4) * 8), A1 = *(const LAS bf16x8*)(sXc + (mt * 16 + (lane & 15)) * 72 + 32 + (lane >> 4) * 8);
;         f32x4 ar[4], ai[4];
; #pragma unroll
;         for (int nt = 0; nt < 4; ++nt) { const f32x4 z = {0.f, 0.f, 0.f, 0.f};
;             ar[nt] = mfma16(A0, Br[nt][0], z); ar[nt] = mfma16(A1, Br[nt][1], ar[nt]); ai[nt] = mfma16(A0, Bi[nt][0], z); ai[nt] = mfma16(A1, Bi[nt][1], ai[nt]); }
;         WAVE_SYNC();
; #pragma unroll
;         for (int nt = 0; nt < 4; ++nt)
; #pragma unroll
;             for (int j = 0; j < 4; ++j) { const int o = ((lane >> 4) * 4 + j) * 64 + nt * 16 + (lane & 15); stg[o] = ar[nt][j]; stg[1024 + o] = ai[nt][j]; }
;         WAVE_SYNC();
;         float av[16], iv[16];
; #pragma unroll
;         for (int ti = 0; ti < 16; ++ti) { const int tk = D ? 15 - ti : ti;
;             const float zr = stg[tk * 64 + lane] + ba, zi = stg[1024 + tk * 64 + lane] + bi;
;             const float r = sigmoid_f(zr), ig = sigmoid_f(zi);
;             const float a = __builtin_amdgcn_exp2f(r * sp8);
;             const float xc = bf2f(sXc[(mt * 16 + tk) * 72 + lane]);
;             av[ti] = a; iv[ti] = __builtin_amdgcn_sqrtf(fmaxf(1.f - a * a, 0.f)) * ig * xc;
;             if (FINAL && D == 1) grv[ti] = gelu_tanh_f(grv[ti]);
;         }
; #pragma unroll
;         for (int ti = 0; ti < 16; ++ti) { const int tk = D ? 15 - ti : ti;
;             hc = av[ti] * hc + iv[ti]; Ap *= av[ti];
;             if (FINAL) { const size_t row = (size_t)(rowbase + mt * 16 + tk);
;                 if (D == 0) TMP[row * 512 + ch] = (bf16_t)f2bf(hc);
;                 else MIX[row * DM + ch] = (bf16_t)f2bf(grv[ti] * (hfv[ti] + hc)); }
;         }
	v_exp_f32_e32 v5, v5
	v_exp_f32_e32 v6, v6
	v_exp_f32_e32 v7, v7
	v_exp_f32_e32 v8, v8
	v_exp_f32_e32 v9, v9
	v_exp_f32_e32 v10, v10
	v_exp_f32_e32 v11, v11
	v_exp_f32_e32 v12, v12
	v_exp_f32_e32 v13, v13
	v_exp_f32_e32 v14, v14
	v_exp_f32_e32 v15, v15
	v_fma_f32 v32, -v0, v0, 1.0
	v_fma_f32 v33, -v1, v1, 1.0
	v_fma_f32 v34, -v2, v2, 1.0
	v_fma_f32 v35, -v3, v3, 1.0
	v_fma_f32 v36, -v4, v4, 1.0
	v_fma_f32 v37, -v5, v5, 1.0
	v_fma_f32 v38, -v6, v6, 1.0
	v_fma_f32 v39, -v7, v7, 1.0
	v_fma_f32 v40, -v8, v8, 1.0
	v_fma_f32 v41, -v9, v9, 1.0
	v_fma_f32 v42, -v10, v10, 1.0
	v_fma_f32 v43, -v11, v11, 1.0
	v_fma_f32 v44, -v12, v12, 1.0
	v_fma_f32 v45, -v13, v13, 1.0
	v_fma_f32 v46, -v14, v14, 1.0
	v_fma_f32 v47, -v15, v15, 1.0
	v_max_f32_e32 v32, 0, v32
	v_max_f32_e32 v33, 0, v33
	v_max_f32_e32 v34, 0, v34
	v_max_f32_e32 v35, 0, v35
	v_max_f32_e32 v36, 0, v36
	v_max_f32_e32 v37, 0, v37
	v_max_f32_e32 v38, 0, v38
	v_max_f32_e32 v39, 0, v39
	v_max_f32_e32 v40, 0, v40
	v_max_f32_e32 v41, 0, v41
	v_max_f32_e32 v42, 0, v42
	v_max_f32_e32 v43, 0, v43
	v_max_f32_e32 v44, 0, v44
	v_max_f32_e32 v45, 0, v45
	v_max_f32_e32 v46, 0, v46
	v_max_f32_e32 v47, 0, v47
	v_sqrt_f32_e32 v32, v32
	v_sqrt_f32_e32 v33, v33
	v_sqrt_f32_e32 v34, v34
	v_sqrt_f32_e32 v35, v35
	v_sqrt_f32_e32 v36, v36
	v_sqrt_f32_e32 v37, v37
	v_sqrt_f32_e32 v38, v38
	v_sqrt_f32_e32 v39, v39
	v_sqrt_f32_e32 v40, v40
	v_sqrt_f32_e32 v41, v41
	v_sqrt_f32_e32 v42, v42
	v_sqrt_f32_e32 v43, v43
	v_sqrt_f32_e32 v44, v44
	v_sqrt_f32_e32 v45, v45
	v_sqrt_f32_e32 v46, v46
	v_sqrt_f32_e32 v47, v47
	s_nop 0
	v_pk_mul_f32 v[16:17], v[16:17], v[32:33]
	v_pk_mul_f32 v[18:19], v[18:19], v[34:35]
	v_pk_mul_f32 v[20:21], v[20:21], v[36:37]
	v_pk_mul_f32 v[22:23], v[22:23], v[38:39]
	v_pk_mul_f32 v[24:25], v[24:25], v[40:41]
	v_pk_mul_f32 v[26:27], v[26:27], v[42:43]
	v_pk_mul_f32 v[28:29], v[28:29], v[44:45]
	v_pk_mul_f32 v[30:31], v[30:31], v[46:47]
	v_pk_mul_f32 v[16:17], v[16:17], v[48:49]
	v_pk_mul_f32 v[18:19], v[18:19], v[50:51]
	v_pk_mul_f32 v[20:21], v[20:21], v[52:53]
	v_pk_mul_f32 v[22:23], v[22:23], v[54:55]
	v_pk_mul_f32 v[24:25], v[24:25], v[56:57]
	v_pk_mul_f32 v[26:27], v[26:27], v[58:59]
	v_pk_mul_f32 v[28:29], v[28:29], v[60:61]
	v_pk_mul_f32 v[30:31], v[30:31], v[62:63]
	v_fma_f32 v32, v0, v250, v16
	v_mul_f32_e32 v232, v232, v0
	v_fma_f32 v250, v1, v32, v17
	v_mul_f32_e32 v232, v232, v1
	v_fma_f32 v32, v2, v250, v18
	v_mul_f32_e32 v232, v232, v2
	v_fma_f32 v250, v3, v32, v19
	v_mul_f32_e32 v232, v232, v3
	v_fma_f32 v32, v4, v250, v20
	v_mul_f32_e32 v232, v232, v4
	v_fma_f32 v250, v5, v32, v21
	v_mul_f32_e32 v232, v232, v5
	v_fma_f32 v32, v6, v250, v22
	v_mul_f32_e32 v232, v232, v6
	v_fma_f32 v250, v7, v32, v23
	v_mul_f32_e32 v232, v232, v7
	v_fma_f32 v32, v8, v250, v24
	v_mul_f32_e32 v232, v232, v8
	v_fma_f32 v250, v9, v32, v25
	v_mul_f32_e32 v232, v232, v9
	v_fma_f32 v32, v10, v250, v26
	v_mul_f32_e32 v232, v232, v10
	v_fma_f32 v250, v11, v32, v27
	v_mul_f32_e32 v232, v232, v11
	v_fma_f32 v32, v12, v250, v28
	v_mul_f32_e32 v232, v232, v12
	v_fma_f32 v250, v13, v32, v29
	v_mul_f32_e32 v232, v232, v13
	v_fma_f32 v32, v14, v250, v30
	v_mul_f32_e32 v232, v232, v14
	v_fma_f32 v250, v15, v32, v31
	v_mul_f32_e32 v232, v232, v15
	ds_read_b128 v[32:35], v236 offset:2304
	ds_read_b128 v[36:39], v236 offset:2368
	s_waitcnt lgkmcnt(0)
	v_mfma_f32_16x16x32_bf16 v[0:3], v[32:35], v[80:83], 0
	v_mfma_f32_16x16x32_bf16 v[4:7], v[32:35], v[88:91], 0
	v_mfma_f32_16x16x32_bf16 v[8:11], v[32:35], v[96:99], 0
	v_mfma_f32_16x16x32_bf16 v[12:15], v[32:35], v[104:107], 0
	v_mfma_f32_16x16x32_bf16 v[16:19], v[32:35], v[112:115], 0
	v_mfma_f32_16x16x32_bf16 v[20:23], v[32:35], v[120:123], 0
	v_mfma_f32_16x16x32_bf16 v[24:27], v[32:35], v[128:131], 0
	v_mfma_f32_16x16x32_bf16 v[28:31], v[32:35], v[136:139], 0
	v_mfma_f32_16x16x32_bf16 v[0:3], v[36:39], v[84:87], v[0:3]
	v_mfma_f32_16x16x32_bf16 v[4:7], v[36:39], v[92:95], v[4:7]
	v_mfma_f32_16x16x32_bf16 v[8:11], v[36:39], v[100:103], v[8:11]
	v_mfma_f32_16x16x32_bf16 v[12:15], v[36:39], v[108:111], v[12:15]
	v_mfma_f32_16x16x32_bf16 v[16:19], v[36:39], v[148:151], v[16:19]
	v_mfma_f32_16x16x32_bf16 v[20:23], v[36:39], v[124:127], v[20:23]
	v_mfma_f32_16x16x32_bf16 v[24:27], v[36:39], v[132:135], v[24:27]
	v_mfma_f32_16x16x32_bf16 v[28:31], v[36:39], v[228:231], v[28:31]
	s_nop 3
	ds_write2_b32 v237, v0, v4 offset0:0 offset1:16
	ds_write2_b32 v237, v8, v12 offset0:32 offset1:48
	ds_write2_b32 v237, v1, v5 offset0:64 offset1:80
	ds_write2_b32 v237, v9, v13 offset0:96 offset1:112
	ds_write2_b32 v237, v2, v6 offset0:128 offset1:144
	ds_write2_b32 v237, v10, v14 offset0:160 offset1:176
	ds_write2_b32 v237, v3, v7 offset0:192 offset1:208
	ds_write2_b32 v237, v11, v15 offset0:224 offset1:240
	ds_write2_b32 v238, v16, v20 offset0:0 offset1:16
	ds_write2_b32 v238, v24, v28 offset0:32 offset1:48
	ds_write2_b32 v238, v17, v21 offset0:64 offset1:80
	ds_write2_b32 v238, v25, v29 offset0:96 offset1:112
	ds_write2_b32 v238, v18, v22 offset0:128 offset1:144
	ds_write2_b32 v238, v26, v30 offset0:160 offset1:176
	ds_write2_b32 v238, v19, v23 offset0:192 offset1:208
	ds_write2_b32 v238, v27, v31 offset0:224 offset1:240
	s_waitcnt lgkmcnt(0)
; __device__ __forceinline__ float sigmoid_f(float x) { return rcpf_(1.f + __expf(-x)); }
; __device__ __forceinline__ float gelu_tanh_f(float x) { const float y = 0.7978845608028654f * (x + 0.044715f * x * x * x); return x * sigmoid_f(2.f * y); }
; template <bool FINAL, int D>
; __device__ __forceinline__ void rg_dir(PREF p, int l, int h, int ch, int sidx, int rowbase  , LAS bf16_t* sXc, LAS float* stg, int lane) {
;     ...
;         float av[16], iv[16];
; #pragma unroll
;         for (int ti = 0; ti < 16; ++ti) { const int tk = D ? 15 - ti : ti;
;             const float zr = stg[tk * 64 + lane] + ba, zi = stg[1024 + tk * 64 + lane] + bi;
;             const float r = sigmoid_f(zr), ig = sigmoid_f(zi);
;             const float a = __builtin_amdgcn_exp2f(r * sp8);
;             const float xc = bf2f(sXc[(mt * 16 + tk) * 72 + lane]);
;             av[ti] = a; iv[ti] = __builtin_amdgcn_sqrtf(fmaxf(1.f - a * a, 0.f)) * ig * xc;
;             if (FINAL && D == 1) grv[ti] = gelu_tanh_f(grv[ti]);
;         }
	ds_read2st64_b32 v[0:1], v239 offset0:36 offset1:37
	ds_read2st64_b32 v[2:3], v239 offset0:38 offset1:39
	ds_read2st64_b32 v[4:5], v239 offset0:40 offset1:41
	ds_read2st64_b32 v[6:7], v239 offset0:42 offset1:43
	ds_read2st64_b32 v[8:9], v239 offset0:44 offset1:45
	ds_read2st64_b32 v[10:11], v239 offset0:46 offset1:47
	ds_read2st64_b32 v[12:13], v239 offset0:48 offset1:49
	ds_read2st64_b32 v[14:15], v239 offset0:50 offset1:51
	ds_read2st64_b32 v[16:17], v239 offset0:52 offset1:53
	ds_read2st64_b32 v[18:19], v239 offset0:54 offset1:55
	ds_read2st64_b32 v[20:21], v239 offset0:56 offset1:57
	ds_read2st64_b32 v[22:23], v239 offset0:58 offset1:59
	ds_read2st64_b32 v[24:25], v239 offset0:60 offset1:61
	ds_read2st64_b32 v[26:27], v239 offset0:62 offset1:63
	ds_read2st64_b32 v[28:29], v239 offset0:64 offset1:65
	ds_read2st64_b32 v[30:31], v239 offset0:66 offset1:67
	ds_read_u16_d16_hi v48, v240 offset:2304
	ds_read_u16_d16_hi v49, v240 offset:2448
	ds_read_u16_d16_hi v50, v240 offset:2592
	ds_read_u16_d16_hi v51, v240 offset:2736
	ds_read_u16_d16_hi v52, v240 offset:2880
	ds_read_u16_d16_hi v53, v240 offset:3024
	ds_read_u16_d16_hi v54, v240 offset:3168
	ds_read_u16_d16_hi v55, v240 offset:3312
	ds_read_u16_d16_hi v56, v240 offset:3456
	ds_read_u16_d16_hi v57, v240 offset:3600
	ds_read_u16_d16_hi v58, v240 offset:3744
	ds_read_u16_d16_hi v59, v240 offset:3888
	ds_read_u16_d16_hi v60, v240 offset:4032
	ds_read_u16_d16_hi v61, v240 offset:4176
	ds_read_u16_d16_hi v62, v240 offset:4320
	ds_read_u16_d16_hi v63, v240 offset:4464
	s_waitcnt lgkmcnt(0)
	v_pk_fma_f32 v[0:1], v[0:1], v[248:249], v[242:243]
	v_pk_fma_f32 v[2:3], v[2:3], v[248:249], v[242:243]
	v_pk_fma_f32 v[4:5], v[4:5], v[248:249], v[242:243]
	v_pk_fma_f32 v[6:7], v[6:7], v[248:249], v[242:243]
	v_pk_fma_f32 v[8:9], v[8:9], v[248:249], v[242:243]
	v_pk_fma_f32 v[10:11], v[10:11], v[248:249], v[242:243]
	v_pk_fma_f32 v[12:13], v[12:13], v[248:249], v[242:243]
	v_pk_fma_f32 v[14:15], v[14:15], v[248:249], v[242:243]
	v_pk_fma_f32 v[16:17], v[16:17], v[248:249], v[244:245]
	v_pk_fma_f32 v[18:19], v[18:19], v[248:249], v[244:245]
	v_pk_fma_f32 v[20:21], v[20:21], v[248:249], v[244:245]
	v_pk_fma_f32 v[22:23], v[22:23], v[248:249], v[244:245]
	v_pk_fma_f32 v[24:25], v[24:25], v[248:249], v[244:245]
	v_pk_fma_f32 v[26:27], v[26:27], v[248:249], v[244:245]
	v_pk_fma_f32 v[28:29], v[28:29], v[248:249], v[244:245]
	v_pk_fma_f32 v[30:31], v[30:31], v[248:249], v[244:245]
	v_exp_f32_e32 v0, v0
	v_exp_f32_e32 v1, v1
	v_exp_f32_e32 v2, v2
	v_exp_f32_e32 v3, v3
	v_exp_f32_e32 v4, v4
	v_exp_f32_e32 v5, v5
	v_exp_f32_e32 v6, v6
	v_exp_f32_e32 v7, v7
	v_exp_f32_e32 v8, v8
	v_exp_f32_e32 v9, v9
	v_exp_f32_e32 v10, v10
	v_exp_f32_e32 v11, v11
	v_exp_f32_e32 v12, v12
	v_exp_f32_e32 v13, v13
	v_exp_f32_e32 v14, v14
	v_exp_f32_e32 v15, v15
	v_exp_f32_e32 v16, v16
	v_exp_f32_e32 v17, v17
	v_exp_f32_e32 v18, v18
	v_exp_f32_e32 v19, v19
	v_exp_f32_e32 v20, v20
	v_exp_f32_e32 v21, v21
	v_exp_f32_e32 v22, v22
	v_exp_f32_e32 v23, v23
	v_exp_f32_e32 v24, v24
	v_exp_f32_e32 v25, v25
	v_exp_f32_e32 v26, v26
	v_exp_f32_e32 v27, v27
	v_exp_f32_e32 v28, v28
	v_exp_f32_e32 v29, v29
	v_exp_f32_e32 v30, v30
	v_exp_f32_e32 v31, v31
	v_pk_add_f32 v[0:1], v[0:1], 1.0 op_sel_hi:[1,0]
	v_pk_add_f32 v[2:3], v[2:3], 1.0 op_sel_hi:[1,0]
	v_pk_add_f32 v[4:5], v[4:5], 1.0 op_sel_hi:[1,0]
	v_pk_add_f32 v[6:7], v[6:7], 1.0 op_sel_hi:[1,0]
	v_pk_add_f32 v[8:9], v[8:9], 1.0 op_sel_hi:[1,0]
	v_pk_add_f32 v[10:11], v[10:11], 1.0 op_sel_hi:[1,0]
	v_pk_add_f32 v[12:13], v[12:13], 1.0 op_sel_hi:[1,0]
	v_pk_add_f32 v[14:15], v[14:15], 1.0 op_sel_hi:[1,0]
	v_pk_add_f32 v[16:17], v[16:17], 1.0 op_sel_hi:[1,0]
	v_pk_add_f32 v[18:19], v[18:19], 1.0 op_sel_hi:[1,0]
	v_pk_add_f32 v[20:21], v[20:21], 1.0 op_sel_hi:[1,0]
	v_pk_add_f32 v[22:23], v[22:23], 1.0 op_sel_hi:[1,0]
	v_pk_add_f32 v[24:25], v[24:25], 1.0 op_sel_hi:[1,0]
	v_pk_add_f32 v[26:27], v[26:27], 1.0 op_sel_hi:[1,0]
	v_pk_add_f32 v[28:29], v[28:29], 1.0 op_sel_hi:[1,0]
	v_pk_add_f32 v[30:31], v[30:31], 1.0 op_sel_hi:[1,0]
	v_rcp_f32_e32 v0, v0
	v_rcp_f32_e32 v1, v1
	v_rcp_f32_e32 v2, v2
	v_rcp_f32_e32 v3, v3
	v_rcp_f32_e32 v4, v4
	v_rcp_f32_e32 v5, v5
	v_rcp_f32_e32 v6, v6
	v_rcp_f32_e32 v7, v7
	v_rcp_f32_e32 v8, v8
	v_rcp_f32_e32 v9, v9
	v_rcp_f32_e32 v10, v10
	v_rcp_f32_e32 v11, v11
	v_rcp_f32_e32 v12, v12
	v_rcp_f32_e32 v13, v13
	v_rcp_f32_e32 v14, v14
	v_rcp_f32_e32 v15, v15
	v_rcp_f32_e32 v16, v16
	v_rcp_f32_e32 v17, v17
	v_rcp_f32_e32 v18, v18
	v_rcp_f32_e32 v19, v19
	v_rcp_f32_e32 v20, v20
	v_rcp_f32_e32 v21, v21
	v_rcp_f32_e32 v22, v22
	v_rcp_f32_e32 v23, v23
	v_rcp_f32_e32 v24, v24
	v_rcp_f32_e32 v25, v25
	v_rcp_f32_e32 v26, v26
	v_rcp_f32_e32 v27, v27
	v_rcp_f32_e32 v28, v28
	v_rcp_f32_e32 v29, v29
	v_rcp_f32_e32 v30, v30
	v_rcp_f32_e32 v31, v31
	v_pk_mul_f32 v[0:1], v[246:247], v[0:1]
	v_pk_mul_f32 v[2:3], v[246:247], v[2:3]
	v_pk_mul_f32 v[4:5], v[246:247], v[4:5]
	v_pk_mul_f32 v[6:7], v[246:247], v[6:7]
	v_pk_mul_f32 v[8:9], v[246:247], v[8:9]
	v_pk_mul_f32 v[10:11], v[246:247], v[10:11]
	v_pk_mul_f32 v[12:13], v[246:247], v[12:13]
	v_pk_mul_f32 v[14:15], v[246:247], v[14:15]
	v_exp_f32_e32 v0, v0
	v_exp_f32_e32 v1, v1
	v_exp_f32_e32 v2, v2
	v_exp_f32_e32 v3, v3
	v_exp_f32_e32 v4, v4
	v_exp_f32_e32 v5, v5
	v_exp_f32_e32 v6, v6
	v_exp_f32_e32 v7, v7
	v_exp_f32_e32 v8, v8
	v_exp_f32_e32 v9, v9
	v_exp_f32_e32 v10, v10
	v_exp_f32_e32 v11, v11
	v_exp_f32_e32 v12, v12
	v_exp_f32_e32 v13, v13
	v_exp_f32_e32 v14, v14
	v_exp_f32_e32 v15, v15
	v_fma_f32 v32, -v0, v0, 1.0
	v_fma_f32 v33, -v1, v1, 1.0
	v_fma_f32 v34, -v2, v2, 1.0
	v_fma_f32 v35, -v3, v3, 1.0
	v_fma_f32 v36, -v4, v4, 1.0
; #define LAS __attribute__((address_space(3)))
; #define WAVE_SYNC() asm volatile("s_waitcnt lgkmcnt(0)" ::: "memory")
; __device__ __forceinline__ unsigned f2bf(float f) { unsigned r; asm("v_cvt_pk_bf16_f32 %0, %1, %1" : "=v"(r) : "v"(f)); return r & 0xffffu; }
; __device__ __forceinline__ float sigmoid_f(float x) { return rcpf_(1.f + __expf(-x)); }
; template <bool FINAL, int D>
; __device__ __forceinline__ void rg_dir(PREF p, int l, int h, int ch, int sidx, int rowbase  , LAS bf16_t* sXc, LAS float* stg, int lane) {
;     ...
;         const bf16x8 A0 = *(const LAS bf16x8*)(sXc + (mt * 16 + (lane & 15)) * 72 + (lane >> 4) * 8), A1 = *(const LAS bf16x8*)(sXc + (mt * 16 + (lane & 15)) * 72 + 32 + (lane >> 4) * 8);
;         f32x4 ar[4], ai[4];
; #pragma unroll
;         for (int nt = 0; nt < 4; ++nt) { const f32x4 z = {0.f, 0.f, 0.f, 0.f};
;             ar[nt] = mfma16(A0, Br[nt][0], z); ar[nt] = mfma16(A1, Br[nt][1], ar[nt]); ai[nt] = mfma16(A0, Bi[nt][0], z); ai[nt] = mfma16(A1, Bi[nt][1], ai[nt]); }
;         WAVE_SYNC();
; #pragma unroll
;         for (int nt = 0; nt < 4; ++nt)
; #pragma unroll
;             for (int j = 0; j < 4; ++j) { const int o = ((lane >> 4) * 4 + j) * 64 + nt * 16 + (lane & 15); stg[o] = ar[nt][j]; stg[1024 + o] = ai[nt][j]; }
;         WAVE_SYNC();
;         float av[16], iv[16];
; #pragma unroll
;         for (int ti = 0; ti < 16; ++ti) { const int tk = D ? 15 - ti : ti;
;             const float zr = stg[tk * 64 + lane] + ba, zi = stg[1024 + tk * 64 + lane] + bi;
;             const float r = sigmoid_f(zr), ig = sigmoid_f(zi);
;             const float a = __builtin_amdgcn_exp2f(r * sp8);
;             const float xc = bf2f(sXc[(mt * 16 + tk) * 72 + lane]);
;             av[ti] = a; iv[ti] = __builtin_amdgcn_sqrtf(fmaxf(1.f - a * a, 0.f)) * ig * xc;
;             if (FINAL && D == 1) grv[ti] = gelu_tanh_f(grv[ti]);
;         }
; #pragma unroll
;         for (int ti = 0; ti < 16; ++ti) { const int tk = D ? 15 - ti : ti;
;             hc = av[ti] * hc + iv[ti]; Ap *= av[ti];
;             if (FINAL) { const size_t row = (size_t)(rowbase + mt * 16 + tk);
;                 if (D == 0) TMP[row * 512 + ch] = (bf16_t)f2bf(hc);
;                 else MIX[row * DM + ch] = (bf16_t)f2bf(grv[ti] * (hfv[ti] + hc)); }
;         }
	v_fma_f32 v37, -v5, v5, 1.0
	v_fma_f32 v38, -v6, v6, 1.0
	v_fma_f32 v39, -v7, v7, 1.0
	v_fma_f32 v40, -v8, v8, 1.0
	v_fma_f32 v41, -v9, v9, 1.0
	v_fma_f32 v42, -v10, v10, 1.0
	v_fma_f32 v43, -v11, v11, 1.0
	v_fma_f32 v44, -v12, v12, 1.0
	v_fma_f32 v45, -v13, v13, 1.0
	v_fma_f32 v46, -v14, v14, 1.0
	v_fma_f32 v47, -v15, v15, 1.0
	v_max_f32_e32 v32, 0, v32
	v_max_f32_e32 v33, 0, v33
	v_max_f32_e32 v34, 0, v34
	v_max_f32_e32 v35, 0, v35
	v_max_f32_e32 v36, 0, v36
	v_max_f32_e32 v37, 0, v37
	v_max_f32_e32 v38, 0, v38
	v_max_f32_e32 v39, 0, v39
	v_max_f32_e32 v40, 0, v40
	v_max_f32_e32 v41, 0, v41
	v_max_f32_e32 v42, 0, v42
	v_max_f32_e32 v43, 0, v43
	v_max_f32_e32 v44, 0, v44
	v_max_f32_e32 v45, 0, v45
	v_max_f32_e32 v46, 0, v46
	v_max_f32_e32 v47, 0, v47
	v_sqrt_f32_e32 v32, v32
	v_sqrt_f32_e32 v33, v33
	v_sqrt_f32_e32 v34, v34
	v_sqrt_f32_e32 v35, v35
	v_sqrt_f32_e32 v36, v36
	v_sqrt_f32_e32 v37, v37
	v_sqrt_f32_e32 v38, v38
	v_sqrt_f32_e32 v39, v39
	v_sqrt_f32_e32 v40, v40
	v_sqrt_f32_e32 v41, v41
	v_sqrt_f32_e32 v42, v42
	v_sqrt_f32_e32 v43, v43
	v_sqrt_f32_e32 v44, v44
	v_sqrt_f32_e32 v45, v45
	v_sqrt_f32_e32 v46, v46
	v_sqrt_f32_e32 v47, v47
	s_nop 0
	v_pk_mul_f32 v[16:17], v[16:17], v[32:33]
	v_pk_mul_f32 v[18:19], v[18:19], v[34:35]
	v_pk_mul_f32 v[20:21], v[20:21], v[36:37]
	v_pk_mul_f32 v[22:23], v[22:23], v[38:39]
	v_pk_mul_f32 v[24:25], v[24:25], v[40:41]
	v_pk_mul_f32 v[26:27], v[26:27], v[42:43]
	v_pk_mul_f32 v[28:29], v[28:29], v[44:45]
	v_pk_mul_f32 v[30:31], v[30:31], v[46:47]
	v_pk_mul_f32 v[16:17], v[16:17], v[48:49]
	v_pk_mul_f32 v[18:19], v[18:19], v[50:51]
	v_pk_mul_f32 v[20:21], v[20:21], v[52:53]
	v_pk_mul_f32 v[22:23], v[22:23], v[54:55]
	v_pk_mul_f32 v[24:25], v[24:25], v[56:57]
	v_pk_mul_f32 v[26:27], v[26:27], v[58:59]
	v_pk_mul_f32 v[28:29], v[28:29], v[60:61]
	v_pk_mul_f32 v[30:31], v[30:31], v[62:63]
	v_fma_f32 v32, v0, v250, v16
	v_mul_f32_e32 v232, v232, v0
	v_fma_f32 v250, v1, v32, v17
	v_mul_f32_e32 v232, v232, v1
	v_fma_f32 v32, v2, v250, v18
	v_mul_f32_e32 v232, v232, v2
	v_fma_f32 v250, v3, v32, v19
	v_mul_f32_e32 v232, v232, v3
	v_fma_f32 v32, v4, v250, v20
	v_mul_f32_e32 v232, v232, v4
	v_fma_f32 v250, v5, v32, v21
	v_mul_f32_e32 v232, v232, v5
	v_fma_f32 v32, v6, v250, v22
	v_mul_f32_e32 v232, v232, v6
	v_fma_f32 v250, v7, v32, v23
	v_mul_f32_e32 v232, v232, v7
	v_fma_f32 v32, v8, v250, v24
	v_mul_f32_e32 v232, v232, v8
	v_fma_f32 v250, v9, v32, v25
	v_mul_f32_e32 v232, v232, v9
	v_fma_f32 v32, v10, v250, v26
	v_mul_f32_e32 v232, v232, v10
	v_fma_f32 v250, v11, v32, v27
	v_mul_f32_e32 v232, v232, v11
	v_fma_f32 v32, v12, v250, v28
	v_mul_f32_e32 v232, v232, v12
	v_fma_f32 v250, v13, v32, v29
	v_mul_f32_e32 v232, v232, v13
	v_fma_f32 v32, v14, v250, v30
	v_mul_f32_e32 v232, v232, v14
	v_fma_f32 v250, v15, v32, v31
	v_mul_f32_e32 v232, v232, v15
	ds_read_b128 v[32:35], v236 offset:4608
	ds_read_b128 v[36:39], v236 offset:4672
	s_waitcnt lgkmcnt(0)
	v_mfma_f32_16x16x32_bf16 v[0:3], v[32:35], v[80:83], 0
	v_mfma_f32_16x16x32_bf16 v[4:7], v[32:35], v[88:91], 0
	v_mfma_f32_16x16x32_bf16 v[8:11], v[32:35], v[96:99], 0
	v_mfma_f32_16x16x32_bf16 v[12:15], v[32:35], v[104:107], 0
	v_mfma_f32_16x16x32_bf16 v[16:19], v[32:35], v[112:115], 0
	v_mfma_f32_16x16x32_bf16 v[20:23], v[32:35], v[120:123], 0
	v_mfma_f32_16x16x32_bf16 v[24:27], v[32:35], v[128:131], 0
	v_mfma_f32_16x16x32_bf16 v[28:31], v[32:35], v[136:139], 0
	v_mfma_f32_16x16x32_bf16 v[0:3], v[36:39], v[84:87], v[0:3]
	v_mfma_f32_16x16x32_bf16 v[4:7], v[36:39], v[92:95], v[4:7]
	v_mfma_f32_16x16x32_bf16 v[8:11], v[36:39], v[100:103], v[8:11]
	v_mfma_f32_16x16x32_bf16 v[12:15], v[36:39], v[108:111], v[12:15]
	v_mfma_f32_16x16x32_bf16 v[16:19], v[36:39], v[148:151], v[16:19]
	v_mfma_f32_16x16x32_bf16 v[20:23], v[36:39], v[124:127], v[20:23]
	v_mfma_f32_16x16x32_bf16 v[24:27], v[36:39], v[132:135], v[24:27]
	v_mfma_f32_16x16x32_bf16 v[28:31], v[36:39], v[228:231], v[28:31]
	s_nop 3
	ds_write2_b32 v237, v0, v4 offset0:0 offset1:16
	ds_write2_b32 v237, v8, v12 offset0:32 offset1:48
	ds_write2_b32 v237, v1, v5 offset0:64 offset1:80
	ds_write2_b32 v237, v9, v13 offset0:96 offset1:112
	ds_write2_b32 v237, v2, v6 offset0:128 offset1:144
	ds_write2_b32 v237, v10, v14 offset0:160 offset1:176
	ds_write2_b32 v237, v3, v7 offset0:192 offset1:208
	ds_write2_b32 v237, v11, v15 offset0:224 offset1:240
	ds_write2_b32 v238, v16, v20 offset0:0 offset1:16
	ds_write2_b32 v238, v24, v28 offset0:32 offset1:48
	ds_write2_b32 v238, v17, v21 offset0:64 offset1:80
	ds_write2_b32 v238, v25, v29 offset0:96 offset1:112
	ds_write2_b32 v238, v18, v22 offset0:128 offset1:144
	ds_write2_b32 v238, v26, v30 offset0:160 offset1:176
	ds_write2_b32 v238, v19, v23 offset0:192 offset1:208
	ds_write2_b32 v238, v27, v31 offset0:224 offset1:240
	s_waitcnt lgkmcnt(0)
	ds_read2st64_b32 v[0:1], v239 offset0:36 offset1:37
	ds_read2st64_b32 v[2:3], v239 offset0:38 offset1:39
	ds_read2st64_b32 v[4:5], v239 offset0:40 offset1:41
	ds_read2st64_b32 v[6:7], v239 offset0:42 offset1:43
	ds_read2st64_b32 v[8:9], v239 offset0:44 offset1:45
	ds_read2st64_b32 v[10:11], v239 offset0:46 offset1:47
	ds_read2st64_b32 v[12:13], v239 offset0:48 offset1:49
	ds_read2st64_b32 v[14:15], v239 offset0:50 offset1:51
	ds_read2st64_b32 v[16:17], v239 offset0:52 offset1:53
	ds_read2st64_b32 v[18:19], v239 offset0:54 offset1:55
	ds_read2st64_b32 v[20:21], v239 offset0:56 offset1:57
	ds_read2st64_b32 v[22:23], v239 offset0:58 offset1:59
	ds_read2st64_b32 v[24:25], v239 offset0:60 offset1:61
	ds_read2st64_b32 v[26:27], v239 offset0:62 offset1:63
	ds_read2st64_b32 v[28:29], v239 offset0:64 offset1:65
	ds_read2st64_b32 v[30:31], v239 offset0:66 offset1:67
	ds_read_u16_d16_hi v48, v240 offset:4608
	ds_read_u16_d16_hi v49, v240 offset:4752
	ds_read_u16_d16_hi v50, v240 offset:4896
	ds_read_u16_d16_hi v51, v240 offset:5040
	ds_read_u16_d16_hi v52, v240 offset:5184
	ds_read_u16_d16_hi v53, v240 offset:5328
	ds_read_u16_d16_hi v54, v240 offset:5472
	ds_read_u16_d16_hi v55, v240 offset:5616
	ds_read_u16_d16_hi v56, v240 offset:5760
	ds_read_u16_d16_hi v57, v240 offset:5904
	ds_read_u16_d16_hi v58, v240 offset:6048
	ds_read_u16_d16_hi v59, v240 offset:6192
	ds_read_u16_d16_hi v60, v240 offset:6336
	ds_read_u16_d16_hi v61, v240 offset:6480
	ds_read_u16_d16_hi v62, v240 offset:6624
	ds_read_u16_d16_hi v63, v240 offset:6768
	s_waitcnt lgkmcnt(0)
; __device__ __forceinline__ unsigned f2bf(float f) { unsigned r; asm("v_cvt_pk_bf16_f32 %0, %1, %1" : "=v"(r) : "v"(f)); return r & 0xffffu; }
; __device__ __forceinline__ float sigmoid_f(float x) { return rcpf_(1.f + __expf(-x)); }
; __device__ __forceinline__ float gelu_tanh_f(float x) { const float y = 0.7978845608028654f * (x + 0.044715f * x * x * x); return x * sigmoid_f(2.f * y); }
; template <bool FINAL, int D>
; __device__ __forceinline__ void rg_dir(PREF p, int l, int h, int ch, int sidx, int rowbase  , LAS bf16_t* sXc, LAS float* stg, int lane) {
;     ...
;         float av[16], iv[16];
; #pragma unroll
;         for (int ti = 0; ti < 16; ++ti) { const int tk = D ? 15 - ti : ti;
;             const float zr = stg[tk * 64 + lane] + ba, zi = stg[1024 + tk * 64 + lane] + bi;
;             const float r = sigmoid_f(zr), ig = sigmoid_f(zi);
;             const float a = __builtin_amdgcn_exp2f(r * sp8);
;             const float xc = bf2f(sXc[(mt * 16 + tk) * 72 + lane]);
;             av[ti] = a; iv[ti] = __builtin_amdgcn_sqrtf(fmaxf(1.f - a * a, 0.f)) * ig * xc;
;             if (FINAL && D == 1) grv[ti] = gelu_tanh_f(grv[ti]);
;         }
; #pragma unroll
;         for (int ti = 0; ti < 16; ++ti) { const int tk = D ? 15 - ti : ti;
;             hc = av[ti] * hc + iv[ti]; Ap *= av[ti];
;             if (FINAL) { const size_t row = (size_t)(rowbase + mt * 16 + tk);
;                 if (D == 0) TMP[row * 512 + ch] = (bf16_t)f2bf(hc);
;                 else MIX[row * DM + ch] = (bf16_t)f2bf(grv[ti] * (hfv[ti] + hc)); }
;         }
	v_pk_fma_f32 v[0:1], v[0:1], v[248:249], v[242:243]
	v_pk_fma_f32 v[2:3], v[2:3], v[248:249], v[242:243]
	v_pk_fma_f32 v[4:5], v[4:5], v[248:249], v[242:243]
	v_pk_fma_f32 v[6:7], v[6:7], v[248:249], v[242:243]
	v_pk_fma_f32 v[8:9], v[8:9], v[248:249], v[242:243]
	v_pk_fma_f32 v[10:11], v[10:11], v[248:249], v[242:243]
	v_pk_fma_f32 v[12:13], v[12:13], v[248:249], v[242:243]
	v_pk_fma_f32 v[14:15], v[14:15], v[248:249], v[242:243]
	v_pk_fma_f32 v[16:17], v[16:17], v[248:249], v[244:245]
	v_pk_fma_f32 v[18:19], v[18:19], v[248:249], v[244:245]
	v_pk_fma_f32 v[20:21], v[20:21], v[248:249], v[244:245]
	v_pk_fma_f32 v[22:23], v[22:23], v[248:249], v[244:245]
	v_pk_fma_f32 v[24:25], v[24:25], v[248:249], v[244:245]
	v_pk_fma_f32 v[26:27], v[26:27], v[248:249], v[244:245]
	v_pk_fma_f32 v[28:29], v[28:29], v[248:249], v[244:245]
	v_pk_fma_f32 v[30:31], v[30:31], v[248:249], v[244:245]
	v_exp_f32_e32 v0, v0
	v_exp_f32_e32 v1, v1
	v_exp_f32_e32 v2, v2
	v_exp_f32_e32 v3, v3
	v_exp_f32_e32 v4, v4
	v_exp_f32_e32 v5, v5
	v_exp_f32_e32 v6, v6
	v_exp_f32_e32 v7, v7
	v_exp_f32_e32 v8, v8
	v_exp_f32_e32 v9, v9
	v_exp_f32_e32 v10, v10
	v_exp_f32_e32 v11, v11
	v_exp_f32_e32 v12, v12
	v_exp_f32_e32 v13, v13
	v_exp_f32_e32 v14, v14
	v_exp_f32_e32 v15, v15
	v_exp_f32_e32 v16, v16
	v_exp_f32_e32 v17, v17
	v_exp_f32_e32 v18, v18
	v_exp_f32_e32 v19, v19
	v_exp_f32_e32 v20, v20
	v_exp_f32_e32 v21, v21
	v_exp_f32_e32 v22, v22
	v_exp_f32_e32 v23, v23
	v_exp_f32_e32 v24, v24
	v_exp_f32_e32 v25, v25
	v_exp_f32_e32 v26, v26
	v_exp_f32_e32 v27, v27
	v_exp_f32_e32 v28, v28
	v_exp_f32_e32 v29, v29
	v_exp_f32_e32 v30, v30
	v_exp_f32_e32 v31, v31
	v_pk_add_f32 v[0:1], v[0:1], 1.0 op_sel_hi:[1,0]
	v_pk_add_f32 v[2:3], v[2:3], 1.0 op_sel_hi:[1,0]
	v_pk_add_f32 v[4:5], v[4:5], 1.0 op_sel_hi:[1,0]
	v_pk_add_f32 v[6:7], v[6:7], 1.0 op_sel_hi:[1,0]
	v_pk_add_f32 v[8:9], v[8:9], 1.0 op_sel_hi:[1,0]
	v_pk_add_f32 v[10:11], v[10:11], 1.0 op_sel_hi:[1,0]
	v_pk_add_f32 v[12:13], v[12:13], 1.0 op_sel_hi:[1,0]
	v_pk_add_f32 v[14:15], v[14:15], 1.0 op_sel_hi:[1,0]
	v_pk_add_f32 v[16:17], v[16:17], 1.0 op_sel_hi:[1,0]
	v_pk_add_f32 v[18:19], v[18:19], 1.0 op_sel_hi:[1,0]
	v_pk_add_f32 v[20:21], v[20:21], 1.0 op_sel_hi:[1,0]
	v_pk_add_f32 v[22:23], v[22:23], 1.0 op_sel_hi:[1,0]
	v_pk_add_f32 v[24:25], v[24:25], 1.0 op_sel_hi:[1,0]
	v_pk_add_f32 v[26:27], v[26:27], 1.0 op_sel_hi:[1,0]
	v_pk_add_f32 v[28:29], v[28:29], 1.0 op_sel_hi:[1,0]
	v_pk_add_f32 v[30:31], v[30:31], 1.0 op_sel_hi:[1,0]
	v_rcp_f32_e32 v0, v0
	v_rcp_f32_e32 v1, v1
	v_rcp_f32_e32 v2, v2
	v_rcp_f32_e32 v3, v3
	v_rcp_f32_e32 v4, v4
	v_rcp_f32_e32 v5, v5
	v_rcp_f32_e32 v6, v6
	v_rcp_f32_e32 v7, v7
	v_rcp_f32_e32 v8, v8
	v_rcp_f32_e32 v9, v9
	v_rcp_f32_e32 v10, v10
	v_rcp_f32_e32 v11, v11
	v_rcp_f32_e32 v12, v12
	v_rcp_f32_e32 v13, v13
	v_rcp_f32_e32 v14, v14
	v_rcp_f32_e32 v15, v15
	v_rcp_f32_e32 v16, v16
	v_rcp_f32_e32 v17, v17
	v_rcp_f32_e32 v18, v18
	v_rcp_f32_e32 v19, v19
	v_rcp_f32_e32 v20, v20
	v_rcp_f32_e32 v21, v21
	v_rcp_f32_e32 v22, v22
	v_rcp_f32_e32 v23, v23
	v_rcp_f32_e32 v24, v24
	v_rcp_f32_e32 v25, v25
	v_rcp_f32_e32 v26, v26
	v_rcp_f32_e32 v27, v27
	v_rcp_f32_e32 v28, v28
	v_rcp_f32_e32 v29, v29
	v_rcp_f32_e32 v30, v30
	v_rcp_f32_e32 v31, v31
	v_pk_mul_f32 v[0:1], v[246:247], v[0:1]
	v_pk_mul_f32 v[2:3], v[246:247], v[2:3]
	v_pk_mul_f32 v[4:5], v[246:247], v[4:5]
	v_pk_mul_f32 v[6:7], v[246:247], v[6:7]
	v_pk_mul_f32 v[8:9], v[246:247], v[8:9]
	v_pk_mul_f32 v[10:11], v[246:247], v[10:11]
	v_pk_mul_f32 v[12:13], v[246:247], v[12:13]
	v_pk_mul_f32 v[14:15], v[246:247], v[14:15]
	v_exp_f32_e32 v0, v0
	v_exp_f32_e32 v1, v1
	v_exp_f32_e32 v2, v2
	v_exp_f32_e32 v3, v3
	v_exp_f32_e32 v4, v4
	v_exp_f32_e32 v5, v5
	v_exp_f32_e32 v6, v6
	v_exp_f32_e32 v7, v7
	v_exp_f32_e32 v8, v8
	v_exp_f32_e32 v9, v9
	v_exp_f32_e32 v10, v10
	v_exp_f32_e32 v11, v11
	v_exp_f32_e32 v12, v12
	v_exp_f32_e32 v13, v13
	v_exp_f32_e32 v14, v14
	v_exp_f32_e32 v15, v15
	v_fma_f32 v32, -v0, v0, 1.0
	v_fma_f32 v33, -v1, v1, 1.0
	v_fma_f32 v34, -v2, v2, 1.0
	v_fma_f32 v35, -v3, v3, 1.0
	v_fma_f32 v36, -v4, v4, 1.0
	v_fma_f32 v37, -v5, v5, 1.0
	v_fma_f32 v38, -v6, v6, 1.0
	v_fma_f32 v39, -v7, v7, 1.0
	v_fma_f32 v40, -v8, v8, 1.0
	v_fma_f32 v41, -v9, v9, 1.0
	v_fma_f32 v42, -v10, v10, 1.0
	v_fma_f32 v43, -v11, v11, 1.0
	v_fma_f32 v44, -v12, v12, 1.0
	v_fma_f32 v45, -v13, v13, 1.0
	v_fma_f32 v46, -v14, v14, 1.0
	v_fma_f32 v47, -v15, v15, 1.0
	v_max_f32_e32 v32, 0, v32
	v_max_f32_e32 v33, 0, v33
	v_max_f32_e32 v34, 0, v34
	v_max_f32_e32 v35, 0, v35
	v_max_f32_e32 v36, 0, v36
	v_max_f32_e32 v37, 0, v37
	v_max_f32_e32 v38, 0, v38
	v_max_f32_e32 v39, 0, v39
	v_max_f32_e32 v40, 0, v40
	v_max_f32_e32 v41, 0, v41
	v_max_f32_e32 v42, 0, v42
	v_max_f32_e32 v43, 0, v43
	v_max_f32_e32 v44, 0, v44
	v_max_f32_e32 v45, 0, v45
	v_max_f32_e32 v46, 0, v46
	v_max_f32_e32 v47, 0, v47
	v_sqrt_f32_e32 v32, v32
	v_sqrt_f32_e32 v33, v33
	v_sqrt_f32_e32 v34, v34
	v_sqrt_f32_e32 v35, v35
	v_sqrt_f32_e32 v36, v36
	v_sqrt_f32_e32 v37, v37
	v_sqrt_f32_e32 v38, v38
	v_sqrt_f32_e32 v39, v39
	v_sqrt_f32_e32 v40, v40
	v_sqrt_f32_e32 v41, v41
	v_sqrt_f32_e32 v42, v42
	v_sqrt_f32_e32 v43, v43
	v_sqrt_f32_e32 v44, v44
	v_sqrt_f32_e32 v45, v45
	v_sqrt_f32_e32 v46, v46
	v_sqrt_f32_e32 v47, v47
	s_nop 0
	v_pk_mul_f32 v[16:17], v[16:17], v[32:33]
	v_pk_mul_f32 v[18:19], v[18:19], v[34:35]
	v_pk_mul_f32 v[20:21], v[20:21], v[36:37]
	v_pk_mul_f32 v[22:23], v[22:23], v[38:39]
	v_pk_mul_f32 v[24:25], v[24:25], v[40:41]
	v_pk_mul_f32 v[26:27], v[26:27], v[42:43]
	v_pk_mul_f32 v[28:29], v[28:29], v[44:45]
	v_pk_mul_f32 v[30:31], v[30:31], v[46:47]
	v_pk_mul_f32 v[16:17], v[16:17], v[48:49]
	v_pk_mul_f32 v[18:19], v[18:19], v[50:51]
	v_pk_mul_f32 v[20:21], v[20:21], v[52:53]
	v_pk_mul_f32 v[22:23], v[22:23], v[54:55]
	v_pk_mul_f32 v[24:25], v[24:25], v[56:57]
	v_pk_mul_f32 v[26:27], v[26:27], v[58:59]
	v_pk_mul_f32 v[28:29], v[28:29], v[60:61]
	v_pk_mul_f32 v[30:31], v[30:31], v[62:63]
	v_fma_f32 v32, v0, v250, v16
	v_mul_f32_e32 v232, v232, v0
	v_fma_f32 v250, v1, v32, v17
	v_mul_f32_e32 v232, v232, v1
	v_fma_f32 v32, v2, v250, v18
	v_mul_f32_e32 v232, v232, v2
	v_fma_f32 v250, v3, v32, v19
	v_mul_f32_e32 v232, v232, v3
	v_fma_f32 v32, v4, v250, v20
	v_mul_f32_e32 v232, v232, v4
	v_fma_f32 v250, v5, v32, v21
	v_mul_f32_e32 v232, v232, v5
	v_fma_f32 v32, v6, v250, v22
	v_mul_f32_e32 v232, v232, v6
	v_fma_f32 v250, v7, v32, v23
	v_mul_f32_e32 v232, v232, v7
	v_fma_f32 v32, v8, v250, v24
	v_mul_f32_e32 v232, v232, v8
	v_fma_f32 v250, v9, v32, v25
	v_mul_f32_e32 v232, v232, v9
	v_fma_f32 v32, v10, v250, v26
	v_mul_f32_e32 v232, v232, v10
	v_fma_f32 v250, v11, v32, v27
	v_mul_f32_e32 v232, v232, v11
	v_fma_f32 v32, v12, v250, v28
	v_mul_f32_e32 v232, v232, v12
	v_fma_f32 v250, v13, v32, v29
	v_mul_f32_e32 v232, v232, v13
	v_fma_f32 v32, v14, v250, v30
	v_mul_f32_e32 v232, v232, v14
	v_fma_f32 v250, v15, v32, v31
	v_mul_f32_e32 v232, v232, v15
	ds_read_b128 v[32:35], v236 offset:6912
	ds_read_b128 v[36:39], v236 offset:6976
	s_waitcnt lgkmcnt(0)
; #define LAS __attribute__((address_space(3)))
; #define WAVE_SYNC() asm volatile("s_waitcnt lgkmcnt(0)" ::: "memory")
; __device__ __forceinline__ float sigmoid_f(float x) { return rcpf_(1.f + __expf(-x)); }
; __device__ __forceinline__ f32x4 mfma16(bf16x8 a, bf16x8 b, f32x4 c) { return __builtin_amdgcn_mfma_f32_16x16x32_bf16(a, b, c, 0, 0, 0); }
; template <bool FINAL, int D>
; __device__ __forceinline__ void rg_dir(PREF p, int l, int h, int ch, int sidx, int rowbase  , LAS bf16_t* sXc, LAS float* stg, int lane) {
;     ...
;     for (int nt = 0; nt < 4; ++nt) { const int o0 = (nt * 16 + (lane & 15)) * 64 + (lane >> 4) * 8;
;         Br[nt][0] = *(const bf16x8*)(wr_ + o0); Br[nt][1] = *(const bf16x8*)(wr_ + o0 + 32); Bi[nt][0] = *(const bf16x8*)(wi_ + o0); Bi[nt][1] = *(const bf16x8*)(wi_ + o0 + 32); }
;     ...
;         const bf16x8 A0 = *(const LAS bf16x8*)(sXc + (mt * 16 + (lane & 15)) * 72 + (lane >> 4) * 8), A1 = *(const LAS bf16x8*)(sXc + (mt * 16 + (lane & 15)) * 72 + 32 + (lane >> 4) * 8);
;         f32x4 ar[4], ai[4];
; #pragma unroll
;         for (int nt = 0; nt < 4; ++nt) { const f32x4 z = {0.f, 0.f, 0.f, 0.f};
;             ar[nt] = mfma16(A0, Br[nt][0], z); ar[nt] = mfma16(A1, Br[nt][1], ar[nt]); ai[nt] = mfma16(A0, Bi[nt][0], z); ai[nt] = mfma16(A1, Bi[nt][1], ai[nt]); }
;         WAVE_SYNC();
; #pragma unroll
;         for (int nt = 0; nt < 4; ++nt)
; #pragma unroll
;             for (int j = 0; j < 4; ++j) { const int o = ((lane >> 4) * 4 + j) * 64 + nt * 16 + (lane & 15); stg[o] = ar[nt][j]; stg[1024 + o] = ai[nt][j]; }
;         WAVE_SYNC();
;         float av[16], iv[16];
; #pragma unroll
;         for (int ti = 0; ti < 16; ++ti) { const int tk = D ? 15 - ti : ti;
;             const float zr = stg[tk * 64 + lane] + ba, zi = stg[1024 + tk * 64 + lane] + bi;
;             const float r = sigmoid_f(zr), ig = sigmoid_f(zi);
;             const float a = __builtin_amdgcn_exp2f(r * sp8);
;             const float xc = bf2f(sXc[(mt * 16 + tk) * 72 + lane]);
	v_mfma_f32_16x16x32_bf16 v[0:3], v[32:35], v[80:83], 0
	v_mfma_f32_16x16x32_bf16 v[4:7], v[32:35], v[88:91], 0
	v_mfma_f32_16x16x32_bf16 v[8:11], v[32:35], v[96:99], 0
	v_mfma_f32_16x16x32_bf16 v[12:15], v[32:35], v[104:107], 0
	v_mfma_f32_16x16x32_bf16 v[16:19], v[32:35], v[112:115], 0
	v_mfma_f32_16x16x32_bf16 v[20:23], v[32:35], v[120:123], 0
	v_mfma_f32_16x16x32_bf16 v[24:27], v[32:35], v[128:131], 0
	v_mfma_f32_16x16x32_bf16 v[28:31], v[32:35], v[136:139], 0
	v_mfma_f32_16x16x32_bf16 v[0:3], v[36:39], v[84:87], v[0:3]
	v_mfma_f32_16x16x32_bf16 v[4:7], v[36:39], v[92:95], v[4:7]
	v_mfma_f32_16x16x32_bf16 v[8:11], v[36:39], v[100:103], v[8:11]
	v_mfma_f32_16x16x32_bf16 v[12:15], v[36:39], v[108:111], v[12:15]
	v_mfma_f32_16x16x32_bf16 v[16:19], v[36:39], v[148:151], v[16:19]
	v_mfma_f32_16x16x32_bf16 v[20:23], v[36:39], v[124:127], v[20:23]
	v_mfma_f32_16x16x32_bf16 v[24:27], v[36:39], v[132:135], v[24:27]
	v_mfma_f32_16x16x32_bf16 v[28:31], v[36:39], v[228:231], v[28:31]
	s_nop 3
	ds_write2_b32 v237, v0, v4 offset0:0 offset1:16
	ds_write2_b32 v237, v8, v12 offset0:32 offset1:48
	ds_write2_b32 v237, v1, v5 offset0:64 offset1:80
	ds_write2_b32 v237, v9, v13 offset0:96 offset1:112
	ds_write2_b32 v237, v2, v6 offset0:128 offset1:144
	ds_write2_b32 v237, v10, v14 offset0:160 offset1:176
	ds_write2_b32 v237, v3, v7 offset0:192 offset1:208
	ds_write2_b32 v237, v11, v15 offset0:224 offset1:240
	ds_write2_b32 v238, v16, v20 offset0:0 offset1:16
	ds_write2_b32 v238, v24, v28 offset0:32 offset1:48
	ds_write2_b32 v238, v17, v21 offset0:64 offset1:80
	ds_write2_b32 v238, v25, v29 offset0:96 offset1:112
	ds_write2_b32 v238, v18, v22 offset0:128 offset1:144
	ds_write2_b32 v238, v26, v30 offset0:160 offset1:176
	ds_write2_b32 v238, v19, v23 offset0:192 offset1:208
	ds_write2_b32 v238, v27, v31 offset0:224 offset1:240
	s_waitcnt lgkmcnt(0)
	ds_read2st64_b32 v[0:1], v239 offset0:36 offset1:37
	ds_read2st64_b32 v[2:3], v239 offset0:38 offset1:39
	ds_read2st64_b32 v[4:5], v239 offset0:40 offset1:41
	ds_read2st64_b32 v[6:7], v239 offset0:42 offset1:43
	ds_read2st64_b32 v[8:9], v239 offset0:44 offset1:45
	ds_read2st64_b32 v[10:11], v239 offset0:46 offset1:47
	ds_read2st64_b32 v[12:13], v239 offset0:48 offset1:49
	ds_read2st64_b32 v[14:15], v239 offset0:50 offset1:51
	ds_read2st64_b32 v[16:17], v239 offset0:52 offset1:53
	ds_read2st64_b32 v[18:19], v239 offset0:54 offset1:55
	ds_read2st64_b32 v[20:21], v239 offset0:56 offset1:57
	ds_read2st64_b32 v[22:23], v239 offset0:58 offset1:59
	ds_read2st64_b32 v[24:25], v239 offset0:60 offset1:61
	ds_read2st64_b32 v[26:27], v239 offset0:62 offset1:63
	ds_read2st64_b32 v[28:29], v239 offset0:64 offset1:65
	ds_read2st64_b32 v[30:31], v239 offset0:66 offset1:67
	ds_read_u16_d16_hi v48, v240 offset:6912
	ds_read_u16_d16_hi v49, v240 offset:7056
	ds_read_u16_d16_hi v50, v240 offset:7200
	ds_read_u16_d16_hi v51, v240 offset:7344
	ds_read_u16_d16_hi v52, v240 offset:7488
	ds_read_u16_d16_hi v53, v240 offset:7632
	ds_read_u16_d16_hi v54, v240 offset:7776
	ds_read_u16_d16_hi v55, v240 offset:7920
	ds_read_u16_d16_hi v56, v240 offset:8064
	ds_read_u16_d16_hi v57, v240 offset:8208
	ds_read_u16_d16_hi v58, v240 offset:8352
	ds_read_u16_d16_hi v59, v240 offset:8496
	ds_read_u16_d16_hi v60, v240 offset:8640
	ds_read_u16_d16_hi v61, v240 offset:8784
	ds_read_u16_d16_hi v62, v240 offset:8928
	ds_read_u16_d16_hi v63, v240 offset:9072
	s_add_u32 s90, s92, 0x20000
	s_addc_u32 s91, s93, 0
	global_load_dwordx4 v[80:83], v241, s[90:91]
	global_load_dwordx4 v[84:87], v241, s[90:91] offset:64
	global_load_dwordx4 v[88:91], v241, s[90:91] offset:2048
	global_load_dwordx4 v[92:95], v241, s[90:91] offset:2112
	s_add_u32 s90, s92, 0x21000
	s_addc_u32 s91, s93, 0
	global_load_dwordx4 v[96:99], v241, s[90:91]
	global_load_dwordx4 v[100:103], v241, s[90:91] offset:64
	global_load_dwordx4 v[104:107], v241, s[90:91] offset:2048
	global_load_dwordx4 v[108:111], v241, s[90:91] offset:2112
	s_add_u32 s90, s92, 0x30000
	s_addc_u32 s91, s93, 0
	global_load_dwordx4 v[112:115], v241, s[90:91]
	global_load_dwordx4 v[148:151], v241, s[90:91] offset:64
	global_load_dwordx4 v[120:123], v241, s[90:91] offset:2048
	global_load_dwordx4 v[124:127], v241, s[90:91] offset:2112
	s_add_u32 s90, s92, 0x31000
	s_addc_u32 s91, s93, 0
	global_load_dwordx4 v[128:131], v241, s[90:91]
	global_load_dwordx4 v[132:135], v241, s[90:91] offset:64
	global_load_dwordx4 v[136:139], v241, s[90:91] offset:2048
	global_load_dwordx4 v[228:231], v241, s[90:91] offset:2112
	s_waitcnt lgkmcnt(0)
; __device__ __forceinline__ float sigmoid_f(float x) { return rcpf_(1.f + __expf(-x)); }
; __device__ __forceinline__ float gelu_tanh_f(float x) { const float y = 0.7978845608028654f * (x + 0.044715f * x * x * x); return x * sigmoid_f(2.f * y); }
; template <bool FINAL, int D>
; __device__ __forceinline__ void rg_dir(PREF p, int l, int h, int ch, int sidx, int rowbase  , LAS bf16_t* sXc, LAS float* stg, int lane) {
;     ...
;         float av[16], iv[16];
; #pragma unroll
;         for (int ti = 0; ti < 16; ++ti) { const int tk = D ? 15 - ti : ti;
;             const float zr = stg[tk * 64 + lane] + ba, zi = stg[1024 + tk * 64 + lane] + bi;
;             const float r = sigmoid_f(zr), ig = sigmoid_f(zi);
;             const float a = __builtin_amdgcn_exp2f(r * sp8);
;             const float xc = bf2f(sXc[(mt * 16 + tk) * 72 + lane]);
;             av[ti] = a; iv[ti] = __builtin_amdgcn_sqrtf(fmaxf(1.f - a * a, 0.f)) * ig * xc;
;             if (FINAL && D == 1) grv[ti] = gelu_tanh_f(grv[ti]);
;         }
; #pragma unroll
;         for (int ti = 0; ti < 16; ++ti) { const int tk = D ? 15 - ti : ti;
;             hc = av[ti] * hc + iv[ti]; Ap *= av[ti];
	v_pk_fma_f32 v[0:1], v[0:1], v[248:249], v[242:243]
	v_pk_fma_f32 v[2:3], v[2:3], v[248:249], v[242:243]
	v_pk_fma_f32 v[4:5], v[4:5], v[248:249], v[242:243]
	v_pk_fma_f32 v[6:7], v[6:7], v[248:249], v[242:243]
	v_pk_fma_f32 v[8:9], v[8:9], v[248:249], v[242:243]
	v_pk_fma_f32 v[10:11], v[10:11], v[248:249], v[242:243]
	v_pk_fma_f32 v[12:13], v[12:13], v[248:249], v[242:243]
	v_pk_fma_f32 v[14:15], v[14:15], v[248:249], v[242:243]
	v_pk_fma_f32 v[16:17], v[16:17], v[248:249], v[244:245]
	v_pk_fma_f32 v[18:19], v[18:19], v[248:249], v[244:245]
	v_pk_fma_f32 v[20:21], v[20:21], v[248:249], v[244:245]
	v_pk_fma_f32 v[22:23], v[22:23], v[248:249], v[244:245]
	v_pk_fma_f32 v[24:25], v[24:25], v[248:249], v[244:245]
	v_pk_fma_f32 v[26:27], v[26:27], v[248:249], v[244:245]
	v_pk_fma_f32 v[28:29], v[28:29], v[248:249], v[244:245]
	v_pk_fma_f32 v[30:31], v[30:31], v[248:249], v[244:245]
	v_exp_f32_e32 v0, v0
	v_exp_f32_e32 v1, v1
	v_exp_f32_e32 v2, v2
	v_exp_f32_e32 v3, v3
	v_exp_f32_e32 v4, v4
	v_exp_f32_e32 v5, v5
	v_exp_f32_e32 v6, v6
	v_exp_f32_e32 v7, v7
	v_exp_f32_e32 v8, v8
	v_exp_f32_e32 v9, v9
	v_exp_f32_e32 v10, v10
	v_exp_f32_e32 v11, v11
	v_exp_f32_e32 v12, v12
	v_exp_f32_e32 v13, v13
	v_exp_f32_e32 v14, v14
	v_exp_f32_e32 v15, v15
	v_exp_f32_e32 v16, v16
	v_exp_f32_e32 v17, v17
	v_exp_f32_e32 v18, v18
	v_exp_f32_e32 v19, v19
	v_exp_f32_e32 v20, v20
	v_exp_f32_e32 v21, v21
	v_exp_f32_e32 v22, v22
	v_exp_f32_e32 v23, v23
	v_exp_f32_e32 v24, v24
	v_exp_f32_e32 v25, v25
	v_exp_f32_e32 v26, v26
	v_exp_f32_e32 v27, v27
	v_exp_f32_e32 v28, v28
	v_exp_f32_e32 v29, v29
	v_exp_f32_e32 v30, v30
	v_exp_f32_e32 v31, v31
	v_pk_add_f32 v[0:1], v[0:1], 1.0 op_sel_hi:[1,0]
	v_pk_add_f32 v[2:3], v[2:3], 1.0 op_sel_hi:[1,0]
	v_pk_add_f32 v[4:5], v[4:5], 1.0 op_sel_hi:[1,0]
	v_pk_add_f32 v[6:7], v[6:7], 1.0 op_sel_hi:[1,0]
	v_pk_add_f32 v[8:9], v[8:9], 1.0 op_sel_hi:[1,0]
	v_pk_add_f32 v[10:11], v[10:11], 1.0 op_sel_hi:[1,0]
	v_pk_add_f32 v[12:13], v[12:13], 1.0 op_sel_hi:[1,0]
	v_pk_add_f32 v[14:15], v[14:15], 1.0 op_sel_hi:[1,0]
	v_pk_add_f32 v[16:17], v[16:17], 1.0 op_sel_hi:[1,0]
	v_pk_add_f32 v[18:19], v[18:19], 1.0 op_sel_hi:[1,0]
	v_pk_add_f32 v[20:21], v[20:21], 1.0 op_sel_hi:[1,0]
	v_pk_add_f32 v[22:23], v[22:23], 1.0 op_sel_hi:[1,0]
	v_pk_add_f32 v[24:25], v[24:25], 1.0 op_sel_hi:[1,0]
	v_pk_add_f32 v[26:27], v[26:27], 1.0 op_sel_hi:[1,0]
	v_pk_add_f32 v[28:29], v[28:29], 1.0 op_sel_hi:[1,0]
	v_pk_add_f32 v[30:31], v[30:31], 1.0 op_sel_hi:[1,0]
	v_rcp_f32_e32 v0, v0
	v_rcp_f32_e32 v1, v1
	v_rcp_f32_e32 v2, v2
	v_rcp_f32_e32 v3, v3
	v_rcp_f32_e32 v4, v4
	v_rcp_f32_e32 v5, v5
	v_rcp_f32_e32 v6, v6
	v_rcp_f32_e32 v7, v7
	v_rcp_f32_e32 v8, v8
	v_rcp_f32_e32 v9, v9
	v_rcp_f32_e32 v10, v10
	v_rcp_f32_e32 v11, v11
	v_rcp_f32_e32 v12, v12
	v_rcp_f32_e32 v13, v13
	v_rcp_f32_e32 v14, v14
	v_rcp_f32_e32 v15, v15
	v_rcp_f32_e32 v16, v16
	v_rcp_f32_e32 v17, v17
	v_rcp_f32_e32 v18, v18
	v_rcp_f32_e32 v19, v19
	v_rcp_f32_e32 v20, v20
	v_rcp_f32_e32 v21, v21
	v_rcp_f32_e32 v22, v22
	v_rcp_f32_e32 v23, v23
	v_rcp_f32_e32 v24, v24
	v_rcp_f32_e32 v25, v25
	v_rcp_f32_e32 v26, v26
	v_rcp_f32_e32 v27, v27
	v_rcp_f32_e32 v28, v28
	v_rcp_f32_e32 v29, v29
	v_rcp_f32_e32 v30, v30
	v_rcp_f32_e32 v31, v31
	v_pk_mul_f32 v[0:1], v[246:247], v[0:1]
	v_pk_mul_f32 v[2:3], v[246:247], v[2:3]
	v_pk_mul_f32 v[4:5], v[246:247], v[4:5]
	v_pk_mul_f32 v[6:7], v[246:247], v[6:7]
	v_pk_mul_f32 v[8:9], v[246:247], v[8:9]
	v_pk_mul_f32 v[10:11], v[246:247], v[10:11]
	v_pk_mul_f32 v[12:13], v[246:247], v[12:13]
	v_pk_mul_f32 v[14:15], v[246:247], v[14:15]
	v_exp_f32_e32 v0, v0
	v_exp_f32_e32 v1, v1
	v_exp_f32_e32 v2, v2
	v_exp_f32_e32 v3, v3
	v_exp_f32_e32 v4, v4
	v_exp_f32_e32 v5, v5
	v_exp_f32_e32 v6, v6
	v_exp_f32_e32 v7, v7
	v_exp_f32_e32 v8, v8
	v_exp_f32_e32 v9, v9
	v_exp_f32_e32 v10, v10
	v_exp_f32_e32 v11, v11
	v_exp_f32_e32 v12, v12
	v_exp_f32_e32 v13, v13
	v_exp_f32_e32 v14, v14
	v_exp_f32_e32 v15, v15
	v_fma_f32 v32, -v0, v0, 1.0
	v_fma_f32 v33, -v1, v1, 1.0
	v_fma_f32 v34, -v2, v2, 1.0
	v_fma_f32 v35, -v3, v3, 1.0
	v_fma_f32 v36, -v4, v4, 1.0
	v_fma_f32 v37, -v5, v5, 1.0
	v_fma_f32 v38, -v6, v6, 1.0
	v_fma_f32 v39, -v7, v7, 1.0
	v_fma_f32 v40, -v8, v8, 1.0
	v_fma_f32 v41, -v9, v9, 1.0
	v_fma_f32 v42, -v10, v10, 1.0
	v_fma_f32 v43, -v11, v11, 1.0
	v_fma_f32 v44, -v12, v12, 1.0
	v_fma_f32 v45, -v13, v13, 1.0
	v_fma_f32 v46, -v14, v14, 1.0
	v_fma_f32 v47, -v15, v15, 1.0
	v_max_f32_e32 v32, 0, v32
	v_max_f32_e32 v33, 0, v33
	v_max_f32_e32 v34, 0, v34
	v_max_f32_e32 v35, 0, v35
	v_max_f32_e32 v36, 0, v36
	v_max_f32_e32 v37, 0, v37
	v_max_f32_e32 v38, 0, v38
	v_max_f32_e32 v39, 0, v39
	v_max_f32_e32 v40, 0, v40
	v_max_f32_e32 v41, 0, v41
	v_max_f32_e32 v42, 0, v42
	v_max_f32_e32 v43, 0, v43
	v_max_f32_e32 v44, 0, v44
	v_max_f32_e32 v45, 0, v45
	v_max_f32_e32 v46, 0, v46
	v_max_f32_e32 v47, 0, v47
	v_sqrt_f32_e32 v32, v32
	v_sqrt_f32_e32 v33, v33
	v_sqrt_f32_e32 v34, v34
	v_sqrt_f32_e32 v35, v35
	v_sqrt_f32_e32 v36, v36
	v_sqrt_f32_e32 v37, v37
	v_sqrt_f32_e32 v38, v38
	v_sqrt_f32_e32 v39, v39
	v_sqrt_f32_e32 v40, v40
	v_sqrt_f32_e32 v41, v41
	v_sqrt_f32_e32 v42, v42
	v_sqrt_f32_e32 v43, v43
	v_sqrt_f32_e32 v44, v44
	v_sqrt_f32_e32 v45, v45
	v_sqrt_f32_e32 v46, v46
	v_sqrt_f32_e32 v47, v47
	s_nop 0
	v_pk_mul_f32 v[16:17], v[16:17], v[32:33]
	v_pk_mul_f32 v[18:19], v[18:19], v[34:35]
	v_pk_mul_f32 v[20:21], v[20:21], v[36:37]
	v_pk_mul_f32 v[22:23], v[22:23], v[38:39]
	v_pk_mul_f32 v[24:25], v[24:25], v[40:41]
	v_pk_mul_f32 v[26:27], v[26:27], v[42:43]
	v_pk_mul_f32 v[28:29], v[28:29], v[44:45]
	v_pk_mul_f32 v[30:31], v[30:31], v[46:47]
	v_pk_mul_f32 v[16:17], v[16:17], v[48:49]
; template <bool FINAL, int D>
; __device__ __forceinline__ void rg_dir(PREF p, int l, int h, int ch, int sidx, int rowbase  , LAS bf16_t* sXc, LAS float* stg, int lane) {
;     ...
;     const float ba = p.rg_ba[(l * 2 + D) * 512 + ch], bi = p.rg_bi[(l * 2 + D) * 512 + ch], lam = p.rg_lam[(l * 2 + D) * 512 + ch];
;     const float e_ = __expf(-lam), u_ = 1.f + e_;
;     const float l1p = (u_ == 1.f) ? e_ : __logf(u_) * e_ * rcpf_(u_ - 1.f);
;     const float sp8 = -8.f * 1.4426950408889634f * l1p;
;     float hc = FINAL ? RGC[sidx] : 0.f, Ap = 1.f;
;     bf16x8 Br[4][2], Bi[4][2];
; #pragma unroll
;     for (int nt = 0; nt < 4; ++nt) { const int o0 = (nt * 16 + (lane & 15)) * 64 + (lane >> 4) * 8;
;         Br[nt][0] = *(const bf16x8*)(wr_ + o0); Br[nt][1] = *(const bf16x8*)(wr_ + o0 + 32); Bi[nt][0] = *(const bf16x8*)(wi_ + o0); Bi[nt][1] = *(const bf16x8*)(wi_ + o0 + 32); }
;     if (FINAL && D == 1) asm volatile("s_waitcnt vmcnt(0)" ::: "memory");
; #pragma unroll 1
;     for (int mi = 0; mi < 4; ++mi) { const int mt = D ? 3 - mi : mi;
;         float grv[16], hfv[16];
;         if (FINAL && D == 1) {
; #pragma unroll
;             for (int ti = 0; ti < 16; ++ti) { const size_t row = (size_t)(rowbase + mt * 16 + 15 - ti); grv[ti] = __builtin_bit_cast(float, (unsigned)P[row * PW + 512 + ch]); hfv[ti] = __builtin_bit_cast(float, (unsigned)TMP[row * 512 + ch]); }
;             __builtin_amdgcn_sched_barrier(0);
; #pragma unroll
;             for (int ti = 0; ti < 16; ++ti) { grv[ti] = bf2f(__builtin_bit_cast(unsigned, grv[ti])); hfv[ti] = bf2f(__builtin_bit_cast(unsigned, hfv[ti])); }
;         }
;         const bf16x8 A0 = *(const LAS bf16x8*)(sXc + (mt * 16 + (lane & 15)) * 72 + (lane >> 4) * 8), A1 = *(const LAS bf16x8*)(sXc + (mt * 16 + (lane & 15)) * 72 + 32 + (lane >> 4) * 8);
;         f32x4 ar[4], ai[4];
; #pragma unroll
;         for (int nt = 0; nt < 4; ++nt) { const f32x4 z = {0.f, 0.f, 0.f, 0.f};
;             ar[nt] = mfma16(A0, Br[nt][0], z); ar[nt] = mfma16(A1, Br[nt][1], ar[nt]); ai[nt] = mfma16(A0, Bi[nt][0], z); ai[nt] = mfma16(A1, Bi[nt][1], ai[nt]); }
;         WAVE_SYNC();
; #pragma unroll
;         for (int nt = 0; nt < 4; ++nt)
; #pragma unroll
;             for (int j = 0; j < 4; ++j) { const int o = ((lane >> 4) * 4 + j) * 64 + nt * 16 + (lane & 15); stg[o] = ar[nt][j]; stg[1024 + o] = ai[nt][j]; }
;         WAVE_SYNC();
	v_pk_mul_f32 v[18:19], v[18:19], v[50:51]
	v_pk_mul_f32 v[20:21], v[20:21], v[52:53]
	v_pk_mul_f32 v[22:23], v[22:23], v[54:55]
	v_pk_mul_f32 v[24:25], v[24:25], v[56:57]
	v_pk_mul_f32 v[26:27], v[26:27], v[58:59]
	v_pk_mul_f32 v[28:29], v[28:29], v[60:61]
	v_pk_mul_f32 v[30:31], v[30:31], v[62:63]
	v_fma_f32 v32, v0, v250, v16
	v_mul_f32_e32 v232, v232, v0
	v_fma_f32 v250, v1, v32, v17
	v_mul_f32_e32 v232, v232, v1
	v_fma_f32 v32, v2, v250, v18
	v_mul_f32_e32 v232, v232, v2
	v_fma_f32 v250, v3, v32, v19
	v_mul_f32_e32 v232, v232, v3
	v_fma_f32 v32, v4, v250, v20
	v_mul_f32_e32 v232, v232, v4
	v_fma_f32 v250, v5, v32, v21
	v_mul_f32_e32 v232, v232, v5
	v_fma_f32 v32, v6, v250, v22
	v_mul_f32_e32 v232, v232, v6
	v_fma_f32 v250, v7, v32, v23
	v_mul_f32_e32 v232, v232, v7
	v_fma_f32 v32, v8, v250, v24
	v_mul_f32_e32 v232, v232, v8
	v_fma_f32 v250, v9, v32, v25
	v_mul_f32_e32 v232, v232, v9
	v_fma_f32 v32, v10, v250, v26
	v_mul_f32_e32 v232, v232, v10
	v_fma_f32 v250, v11, v32, v27
	v_mul_f32_e32 v232, v232, v11
	v_fma_f32 v32, v12, v250, v28
	v_mul_f32_e32 v232, v232, v12
	v_fma_f32 v250, v13, v32, v29
	v_mul_f32_e32 v232, v232, v13
	v_fma_f32 v32, v14, v250, v30
	v_mul_f32_e32 v232, v232, v14
	v_fma_f32 v250, v15, v32, v31
	v_mul_f32_e32 v232, v232, v15
	s_add_u32 s96, s0, 0x400000
	s_addc_u32 s97, s1, 0
	s_add_u32 s96, s96, s36
	s_addc_u32 s97, s97, 0
	global_store_dword v235, v232, s[96:97]
	s_add_u32 s96, s96, 0x300000
	s_addc_u32 s97, s97, 0
	global_store_dword v235, v250, s[96:97]
	global_load_dword v45, v235, s[76:77] offset:2048
	global_load_dword v46, v235, s[78:79] offset:2048
	global_load_dword v47, v235, s[80:81] offset:2048
	s_waitcnt vmcnt(0)
	s_mov_b32 s8, 0x800000
	s_mov_b32 s9, 0x3f317217
	s_mov_b32 s14, 0x7f800000
	v_mul_f32_e32 v32, 0xbfb8aa3b, v45
	v_exp_f32_e32 v32, v32
	s_nop 0
	v_add_f32_e32 v33, 1.0, v32
	v_cmp_gt_f32_e32 vcc, s8, v33
	s_nop 1
	v_cndmask_b32_e64 v34, 0, 32, vcc
	v_ldexp_f32 v34, v33, v34
	v_log_f32_e32 v34, v34
	v_cndmask_b32_e32 v36, 0, v226, vcc
	v_cmp_eq_f32_e32 vcc, 1.0, v33
	v_mul_f32_e32 v35, 0x3f317217, v34
	v_fma_f32 v35, v34, s9, -v35
	v_fmac_f32_e32 v35, 0x3377d1cf, v34
	v_fmac_f32_e32 v35, 0x3f317217, v34
	v_cmp_lt_f32_e64 s[10:11], |v34|, s14
	s_nop 1
	v_cndmask_b32_e64 v34, v34, v35, s[10:11]
	v_add_f32_e32 v35, -1.0, v33
	v_rcp_f32_e32 v35, v35
	v_sub_f32_e32 v34, v34, v36
	v_mul_f32_e32 v34, v32, v34
	v_mul_f32_e32 v34, v34, v35
	v_cndmask_b32_e32 v32, v34, v32, vcc
	v_mul_f32_e32 v246, 0xc138aa3b, v32
	v_mov_b32_e32 v247, v246
	v_mul_f32_e32 v242, 0xbfb8aa3b, v46
	v_mul_f32_e32 v244, 0xbfb8aa3b, v47
	v_mov_b32_e32 v243, v242
	v_mov_b32_e32 v245, v244
	v_mov_b32_e32 v250, 0
	v_mov_b32_e32 v232, 1.0
	ds_read_b128 v[32:35], v236 offset:6912
	ds_read_b128 v[36:39], v236 offset:6976
	s_waitcnt lgkmcnt(0)
	v_mfma_f32_16x16x32_bf16 v[0:3], v[32:35], v[80:83], 0
	v_mfma_f32_16x16x32_bf16 v[4:7], v[32:35], v[88:91], 0
	v_mfma_f32_16x16x32_bf16 v[8:11], v[32:35], v[96:99], 0
	v_mfma_f32_16x16x32_bf16 v[12:15], v[32:35], v[104:107], 0
	v_mfma_f32_16x16x32_bf16 v[16:19], v[32:35], v[112:115], 0
	v_mfma_f32_16x16x32_bf16 v[20:23], v[32:35], v[120:123], 0
	v_mfma_f32_16x16x32_bf16 v[24:27], v[32:35], v[128:131], 0
	v_mfma_f32_16x16x32_bf16 v[28:31], v[32:35], v[136:139], 0
	v_mfma_f32_16x16x32_bf16 v[0:3], v[36:39], v[84:87], v[0:3]
	v_mfma_f32_16x16x32_bf16 v[4:7], v[36:39], v[92:95], v[4:7]
	v_mfma_f32_16x16x32_bf16 v[8:11], v[36:39], v[100:103], v[8:11]
	v_mfma_f32_16x16x32_bf16 v[12:15], v[36:39], v[108:111], v[12:15]
	v_mfma_f32_16x16x32_bf16 v[16:19], v[36:39], v[148:151], v[16:19]
	v_mfma_f32_16x16x32_bf16 v[20:23], v[36:39], v[124:127], v[20:23]
	v_mfma_f32_16x16x32_bf16 v[24:27], v[36:39], v[132:135], v[24:27]
	v_mfma_f32_16x16x32_bf16 v[28:31], v[36:39], v[228:231], v[28:31]
	s_nop 3
	ds_write2_b32 v237, v0, v4 offset0:0 offset1:16
	ds_write2_b32 v237, v8, v12 offset0:32 offset1:48
	ds_write2_b32 v237, v1, v5 offset0:64 offset1:80
	ds_write2_b32 v237, v9, v13 offset0:96 offset1:112
	ds_write2_b32 v237, v2, v6 offset0:128 offset1:144
	ds_write2_b32 v237, v10, v14 offset0:160 offset1:176
	ds_write2_b32 v237, v3, v7 offset0:192 offset1:208
	ds_write2_b32 v237, v11, v15 offset0:224 offset1:240
	ds_write2_b32 v238, v16, v20 offset0:0 offset1:16
	ds_write2_b32 v238, v24, v28 offset0:32 offset1:48
	ds_write2_b32 v238, v17, v21 offset0:64 offset1:80
	ds_write2_b32 v238, v25, v29 offset0:96 offset1:112
	ds_write2_b32 v238, v18, v22 offset0:128 offset1:144
	ds_write2_b32 v238, v26, v30 offset0:160 offset1:176
	ds_write2_b32 v238, v19, v23 offset0:192 offset1:208
	ds_write2_b32 v238, v27, v31 offset0:224 offset1:240
	s_waitcnt lgkmcnt(0)
	ds_read2st64_b32 v[0:1], v239 offset0:36 offset1:37
	ds_read2st64_b32 v[2:3], v239 offset0:38 offset1:39
	ds_read2st64_b32 v[4:5], v239 offset0:40 offset1:41
	ds_read2st64_b32 v[6:7], v239 offset0:42 offset1:43
	ds_read2st64_b32 v[8:9], v239 offset0:44 offset1:45
	ds_read2st64_b32 v[10:11], v239 offset0:46 offset1:47
	ds_read2st64_b32 v[12:13], v239 offset0:48 offset1:49
	ds_read2st64_b32 v[14:15], v239 offset0:50 offset1:51
	ds_read2st64_b32 v[16:17], v239 offset0:52 offset1:53
	ds_read2st64_b32 v[18:19], v239 offset0:54 offset1:55
	ds_read2st64_b32 v[20:21], v239 offset0:56 offset1:57
	ds_read2st64_b32 v[22:23], v239 offset0:58 offset1:59
	ds_read2st64_b32 v[24:25], v239 offset0:60 offset1:61
	ds_read2st64_b32 v[26:27], v239 offset0:62 offset1:63
	ds_read2st64_b32 v[28:29], v239 offset0:64 offset1:65
	ds_read2st64_b32 v[30:31], v239 offset0:66 offset1:67
	ds_read_u16_d16_hi v48, v240 offset:6912
	ds_read_u16_d16_hi v49, v240 offset:7056
	ds_read_u16_d16_hi v50, v240 offset:7200
	ds_read_u16_d16_hi v51, v240 offset:7344
	ds_read_u16_d16_hi v52, v240 offset:7488
	ds_read_u16_d16_hi v53, v240 offset:7632
	ds_read_u16_d16_hi v54, v240 offset:7776
	ds_read_u16_d16_hi v55, v240 offset:7920
	ds_read_u16_d16_hi v56, v240 offset:8064
	ds_read_u16_d16_hi v57, v240 offset:8208
	ds_read_u16_d16_hi v58, v240 offset:8352
	ds_read_u16_d16_hi v59, v240 offset:8496
	ds_read_u16_d16_hi v60, v240 offset:8640
	ds_read_u16_d16_hi v61, v240 offset:8784
	ds_read_u16_d16_hi v62, v240 offset:8928
	ds_read_u16_d16_hi v63, v240 offset:9072
	s_waitcnt lgkmcnt(0)
; __device__ __forceinline__ float sigmoid_f(float x) { return rcpf_(1.f + __expf(-x)); }
; __device__ __forceinline__ float gelu_tanh_f(float x) { const float y = 0.7978845608028654f * (x + 0.044715f * x * x * x); return x * sigmoid_f(2.f * y); }
; template <bool FINAL, int D>
; __device__ __forceinline__ void rg_dir(PREF p, int l, int h, int ch, int sidx, int rowbase  , LAS bf16_t* sXc, LAS float* stg, int lane) {
;     ...
;         float av[16], iv[16];
; #pragma unroll
;         for (int ti = 0; ti < 16; ++ti) { const int tk = D ? 15 - ti : ti;
;             const float zr = stg[tk * 64 + lane] + ba, zi = stg[1024 + tk * 64 + lane] + bi;
;             const float r = sigmoid_f(zr), ig = sigmoid_f(zi);
;             const float a = __builtin_amdgcn_exp2f(r * sp8);
;             const float xc = bf2f(sXc[(mt * 16 + tk) * 72 + lane]);
;             av[ti] = a; iv[ti] = __builtin_amdgcn_sqrtf(fmaxf(1.f - a * a, 0.f)) * ig * xc;
;             if (FINAL && D == 1) grv[ti] = gelu_tanh_f(grv[ti]);
;         }
; #pragma unroll
;         for (int ti = 0; ti < 16; ++ti) { const int tk = D ? 15 - ti : ti;
;             hc = av[ti] * hc + iv[ti]; Ap *= av[ti];
	v_pk_fma_f32 v[0:1], v[0:1], v[248:249], v[242:243]
	v_pk_fma_f32 v[2:3], v[2:3], v[248:249], v[242:243]
	v_pk_fma_f32 v[4:5], v[4:5], v[248:249], v[242:243]
	v_pk_fma_f32 v[6:7], v[6:7], v[248:249], v[242:243]
	v_pk_fma_f32 v[8:9], v[8:9], v[248:249], v[242:243]
	v_pk_fma_f32 v[10:11], v[10:11], v[248:249], v[242:243]
	v_pk_fma_f32 v[12:13], v[12:13], v[248:249], v[242:243]
	v_pk_fma_f32 v[14:15], v[14:15], v[248:249], v[242:243]
	v_pk_fma_f32 v[16:17], v[16:17], v[248:249], v[244:245]
	v_pk_fma_f32 v[18:19], v[18:19], v[248:249], v[244:245]
	v_pk_fma_f32 v[20:21], v[20:21], v[248:249], v[244:245]
	v_pk_fma_f32 v[22:23], v[22:23], v[248:249], v[244:245]
	v_pk_fma_f32 v[24:25], v[24:25], v[248:249], v[244:245]
	v_pk_fma_f32 v[26:27], v[26:27], v[248:249], v[244:245]
	v_pk_fma_f32 v[28:29], v[28:29], v[248:249], v[244:245]
	v_pk_fma_f32 v[30:31], v[30:31], v[248:249], v[244:245]
	v_exp_f32_e32 v0, v0
	v_exp_f32_e32 v1, v1
	v_exp_f32_e32 v2, v2
	v_exp_f32_e32 v3, v3
	v_exp_f32_e32 v4, v4
	v_exp_f32_e32 v5, v5
	v_exp_f32_e32 v6, v6
	v_exp_f32_e32 v7, v7
	v_exp_f32_e32 v8, v8
	v_exp_f32_e32 v9, v9
	v_exp_f32_e32 v10, v10
	v_exp_f32_e32 v11, v11
	v_exp_f32_e32 v12, v12
	v_exp_f32_e32 v13, v13
	v_exp_f32_e32 v14, v14
	v_exp_f32_e32 v15, v15
	v_exp_f32_e32 v16, v16
	v_exp_f32_e32 v17, v17
	v_exp_f32_e32 v18, v18
	v_exp_f32_e32 v19, v19
	v_exp_f32_e32 v20, v20
	v_exp_f32_e32 v21, v21
	v_exp_f32_e32 v22, v22
	v_exp_f32_e32 v23, v23
	v_exp_f32_e32 v24, v24
	v_exp_f32_e32 v25, v25
	v_exp_f32_e32 v26, v26
	v_exp_f32_e32 v27, v27
	v_exp_f32_e32 v28, v28
	v_exp_f32_e32 v29, v29
	v_exp_f32_e32 v30, v30
	v_exp_f32_e32 v31, v31
	v_pk_add_f32 v[0:1], v[0:1], 1.0 op_sel_hi:[1,0]
	v_pk_add_f32 v[2:3], v[2:3], 1.0 op_sel_hi:[1,0]
	v_pk_add_f32 v[4:5], v[4:5], 1.0 op_sel_hi:[1,0]
	v_pk_add_f32 v[6:7], v[6:7], 1.0 op_sel_hi:[1,0]
	v_pk_add_f32 v[8:9], v[8:9], 1.0 op_sel_hi:[1,0]
	v_pk_add_f32 v[10:11], v[10:11], 1.0 op_sel_hi:[1,0]
	v_pk_add_f32 v[12:13], v[12:13], 1.0 op_sel_hi:[1,0]
	v_pk_add_f32 v[14:15], v[14:15], 1.0 op_sel_hi:[1,0]
	v_pk_add_f32 v[16:17], v[16:17], 1.0 op_sel_hi:[1,0]
	v_pk_add_f32 v[18:19], v[18:19], 1.0 op_sel_hi:[1,0]
	v_pk_add_f32 v[20:21], v[20:21], 1.0 op_sel_hi:[1,0]
	v_pk_add_f32 v[22:23], v[22:23], 1.0 op_sel_hi:[1,0]
	v_pk_add_f32 v[24:25], v[24:25], 1.0 op_sel_hi:[1,0]
	v_pk_add_f32 v[26:27], v[26:27], 1.0 op_sel_hi:[1,0]
	v_pk_add_f32 v[28:29], v[28:29], 1.0 op_sel_hi:[1,0]
	v_pk_add_f32 v[30:31], v[30:31], 1.0 op_sel_hi:[1,0]
	v_rcp_f32_e32 v0, v0
	v_rcp_f32_e32 v1, v1
	v_rcp_f32_e32 v2, v2
	v_rcp_f32_e32 v3, v3
	v_rcp_f32_e32 v4, v4
	v_rcp_f32_e32 v5, v5
	v_rcp_f32_e32 v6, v6
	v_rcp_f32_e32 v7, v7
	v_rcp_f32_e32 v8, v8
	v_rcp_f32_e32 v9, v9
	v_rcp_f32_e32 v10, v10
	v_rcp_f32_e32 v11, v11
	v_rcp_f32_e32 v12, v12
	v_rcp_f32_e32 v13, v13
	v_rcp_f32_e32 v14, v14
	v_rcp_f32_e32 v15, v15
	v_rcp_f32_e32 v16, v16
	v_rcp_f32_e32 v17, v17
	v_rcp_f32_e32 v18, v18
	v_rcp_f32_e32 v19, v19
	v_rcp_f32_e32 v20, v20
	v_rcp_f32_e32 v21, v21
	v_rcp_f32_e32 v22, v22
	v_rcp_f32_e32 v23, v23
	v_rcp_f32_e32 v24, v24
	v_rcp_f32_e32 v25, v25
	v_rcp_f32_e32 v26, v26
	v_rcp_f32_e32 v27, v27
	v_rcp_f32_e32 v28, v28
	v_rcp_f32_e32 v29, v29
	v_rcp_f32_e32 v30, v30
	v_rcp_f32_e32 v31, v31
	v_pk_mul_f32 v[0:1], v[246:247], v[0:1]
	v_pk_mul_f32 v[2:3], v[246:247], v[2:3]
	v_pk_mul_f32 v[4:5], v[246:247], v[4:5]
	v_pk_mul_f32 v[6:7], v[246:247], v[6:7]
	v_pk_mul_f32 v[8:9], v[246:247], v[8:9]
	v_pk_mul_f32 v[10:11], v[246:247], v[10:11]
	v_pk_mul_f32 v[12:13], v[246:247], v[12:13]
	v_pk_mul_f32 v[14:15], v[246:247], v[14:15]
	v_exp_f32_e32 v0, v0
	v_exp_f32_e32 v1, v1
	v_exp_f32_e32 v2, v2
	v_exp_f32_e32 v3, v3
	v_exp_f32_e32 v4, v4
	v_exp_f32_e32 v5, v5
	v_exp_f32_e32 v6, v6
	v_exp_f32_e32 v7, v7
	v_exp_f32_e32 v8, v8
	v_exp_f32_e32 v9, v9
	v_exp_f32_e32 v10, v10
	v_exp_f32_e32 v11, v11
	v_exp_f32_e32 v12, v12
	v_exp_f32_e32 v13, v13
	v_exp_f32_e32 v14, v14
	v_exp_f32_e32 v15, v15
	v_fma_f32 v32, -v0, v0, 1.0
	v_fma_f32 v33, -v1, v1, 1.0
	v_fma_f32 v34, -v2, v2, 1.0
	v_fma_f32 v35, -v3, v3, 1.0
	v_fma_f32 v36, -v4, v4, 1.0
	v_fma_f32 v37, -v5, v5, 1.0
	v_fma_f32 v38, -v6, v6, 1.0
	v_fma_f32 v39, -v7, v7, 1.0
	v_fma_f32 v40, -v8, v8, 1.0
	v_fma_f32 v41, -v9, v9, 1.0
	v_fma_f32 v42, -v10, v10, 1.0
	v_fma_f32 v43, -v11, v11, 1.0
	v_fma_f32 v44, -v12, v12, 1.0
	v_fma_f32 v45, -v13, v13, 1.0
	v_fma_f32 v46, -v14, v14, 1.0
	v_fma_f32 v47, -v15, v15, 1.0
	v_max_f32_e32 v32, 0, v32
	v_max_f32_e32 v33, 0, v33
	v_max_f32_e32 v34, 0, v34
	v_max_f32_e32 v35, 0, v35
	v_max_f32_e32 v36, 0, v36
	v_max_f32_e32 v37, 0, v37
	v_max_f32_e32 v38, 0, v38
	v_max_f32_e32 v39, 0, v39
	v_max_f32_e32 v40, 0, v40
	v_max_f32_e32 v41, 0, v41
	v_max_f32_e32 v42, 0, v42
	v_max_f32_e32 v43, 0, v43
	v_max_f32_e32 v44, 0, v44
	v_max_f32_e32 v45, 0, v45
	v_max_f32_e32 v46, 0, v46
	v_max_f32_e32 v47, 0, v47
	v_sqrt_f32_e32 v32, v32
	v_sqrt_f32_e32 v33, v33
	v_sqrt_f32_e32 v34, v34
	v_sqrt_f32_e32 v35, v35
	v_sqrt_f32_e32 v36, v36
	v_sqrt_f32_e32 v37, v37
	v_sqrt_f32_e32 v38, v38
	v_sqrt_f32_e32 v39, v39
	v_sqrt_f32_e32 v40, v40
	v_sqrt_f32_e32 v41, v41
	v_sqrt_f32_e32 v42, v42
	v_sqrt_f32_e32 v43, v43
	v_sqrt_f32_e32 v44, v44
	v_sqrt_f32_e32 v45, v45
	v_sqrt_f32_e32 v46, v46
	v_sqrt_f32_e32 v47, v47
	s_nop 0
	v_pk_mul_f32 v[16:17], v[16:17], v[32:33]
	v_pk_mul_f32 v[18:19], v[18:19], v[34:35]
	v_pk_mul_f32 v[20:21], v[20:21], v[36:37]
	v_pk_mul_f32 v[22:23], v[22:23], v[38:39]
	v_pk_mul_f32 v[24:25], v[24:25], v[40:41]
	v_pk_mul_f32 v[26:27], v[26:27], v[42:43]
	v_pk_mul_f32 v[28:29], v[28:29], v[44:45]
	v_pk_mul_f32 v[30:31], v[30:31], v[46:47]
	v_pk_mul_f32 v[16:17], v[16:17], v[48:49]
	v_pk_mul_f32 v[18:19], v[18:19], v[50:51]
	v_pk_mul_f32 v[20:21], v[20:21], v[52:53]
	v_pk_mul_f32 v[22:23], v[22:23], v[54:55]
	v_pk_mul_f32 v[24:25], v[24:25], v[56:57]
	v_pk_mul_f32 v[26:27], v[26:27], v[58:59]
	v_pk_mul_f32 v[28:29], v[28:29], v[60:61]
	v_pk_mul_f32 v[30:31], v[30:31], v[62:63]
	v_fma_f32 v250, v15, v250, v31
	v_mul_f32_e32 v232, v232, v15
	v_fma_f32 v250, v14, v250, v30
	v_mul_f32_e32 v232, v232, v14
	v_fma_f32 v250, v13, v250, v29
	v_mul_f32_e32 v232, v232, v13
	v_fma_f32 v250, v12, v250, v28
	v_mul_f32_e32 v232, v232, v12
	v_fma_f32 v250, v11, v250, v27
	v_mul_f32_e32 v232, v232, v11
	v_fma_f32 v250, v10, v250, v26
	v_mul_f32_e32 v232, v232, v10
	v_fma_f32 v250, v9, v250, v25
	v_mul_f32_e32 v232, v232, v9
	v_fma_f32 v250, v8, v250, v24
	v_mul_f32_e32 v232, v232, v8
	v_fma_f32 v250, v7, v250, v23
	v_mul_f32_e32 v232, v232, v7
	v_fma_f32 v250, v6, v250, v22
	v_mul_f32_e32 v232, v232, v6
	v_fma_f32 v250, v5, v250, v21
	v_mul_f32_e32 v232, v232, v5
	v_fma_f32 v250, v4, v250, v20
	v_mul_f32_e32 v232, v232, v4
	v_fma_f32 v250, v3, v250, v19
	v_mul_f32_e32 v232, v232, v3
	v_fma_f32 v250, v2, v250, v18
	v_mul_f32_e32 v232, v232, v2
	v_fma_f32 v250, v1, v250, v17
	v_mul_f32_e32 v232, v232, v1
	v_fma_f32 v250, v0, v250, v16
	v_mul_f32_e32 v232, v232, v0
	ds_read_b128 v[32:35], v236 offset:4608
	ds_read_b128 v[36:39], v236 offset:4672
	s_waitcnt lgkmcnt(0)
; #define LAS __attribute__((address_space(3)))
; #define WAVE_SYNC() asm volatile("s_waitcnt lgkmcnt(0)" ::: "memory")
; __device__ __forceinline__ float sigmoid_f(float x) { return rcpf_(1.f + __expf(-x)); }
; __device__ __forceinline__ f32x4 mfma16(bf16x8 a, bf16x8 b, f32x4 c) { return __builtin_amdgcn_mfma_f32_16x16x32_bf16(a, b, c, 0, 0, 0); }
; template <bool FINAL, int D>
; __device__ __forceinline__ void rg_dir(PREF p, int l, int h, int ch, int sidx, int rowbase  , LAS bf16_t* sXc, LAS float* stg, int lane) {
;     ...
;         const bf16x8 A0 = *(const LAS bf16x8*)(sXc + (mt * 16 + (lane & 15)) * 72 + (lane >> 4) * 8), A1 = *(const LAS bf16x8*)(sXc + (mt * 16 + (lane & 15)) * 72 + 32 + (lane >> 4) * 8);
;         f32x4 ar[4], ai[4];
; #pragma unroll
;         for (int nt = 0; nt < 4; ++nt) { const f32x4 z = {0.f, 0.f, 0.f, 0.f};
;             ar[nt] = mfma16(A0, Br[nt][0], z); ar[nt] = mfma16(A1, Br[nt][1], ar[nt]); ai[nt] = mfma16(A0, Bi[nt][0], z); ai[nt] = mfma16(A1, Bi[nt][1], ai[nt]); }
;         WAVE_SYNC();
; #pragma unroll
;         for (int nt = 0; nt < 4; ++nt)
; #pragma unroll
;             for (int j = 0; j < 4; ++j) { const int o = ((lane >> 4) * 4 + j) * 64 + nt * 16 + (lane & 15); stg[o] = ar[nt][j]; stg[1024 + o] = ai[nt][j]; }
;         WAVE_SYNC();
;         float av[16], iv[16];
; #pragma unroll
;         for (int ti = 0; ti < 16; ++ti) { const int tk = D ? 15 - ti : ti;
;             const float zr = stg[tk * 64 + lane] + ba, zi = stg[1024 + tk * 64 + lane] + bi;
;             const float r = sigmoid_f(zr), ig = sigmoid_f(zi);
;             const float a = __builtin_amdgcn_exp2f(r * sp8);
;             const float xc = bf2f(sXc[(mt * 16 + tk) * 72 + lane]);
	v_mfma_f32_16x16x32_bf16 v[0:3], v[32:35], v[80:83], 0
	v_mfma_f32_16x16x32_bf16 v[4:7], v[32:35], v[88:91], 0
	v_mfma_f32_16x16x32_bf16 v[8:11], v[32:35], v[96:99], 0
	v_mfma_f32_16x16x32_bf16 v[12:15], v[32:35], v[104:107], 0
	v_mfma_f32_16x16x32_bf16 v[16:19], v[32:35], v[112:115], 0
	v_mfma_f32_16x16x32_bf16 v[20:23], v[32:35], v[120:123], 0
	v_mfma_f32_16x16x32_bf16 v[24:27], v[32:35], v[128:131], 0
	v_mfma_f32_16x16x32_bf16 v[28:31], v[32:35], v[136:139], 0
	v_mfma_f32_16x16x32_bf16 v[0:3], v[36:39], v[84:87], v[0:3]
	v_mfma_f32_16x16x32_bf16 v[4:7], v[36:39], v[92:95], v[4:7]
	v_mfma_f32_16x16x32_bf16 v[8:11], v[36:39], v[100:103], v[8:11]
	v_mfma_f32_16x16x32_bf16 v[12:15], v[36:39], v[108:111], v[12:15]
	v_mfma_f32_16x16x32_bf16 v[16:19], v[36:39], v[148:151], v[16:19]
	v_mfma_f32_16x16x32_bf16 v[20:23], v[36:39], v[124:127], v[20:23]
	v_mfma_f32_16x16x32_bf16 v[24:27], v[36:39], v[132:135], v[24:27]
	v_mfma_f32_16x16x32_bf16 v[28:31], v[36:39], v[228:231], v[28:31]
	s_nop 3
	ds_write2_b32 v237, v0, v4 offset0:0 offset1:16
	ds_write2_b32 v237, v8, v12 offset0:32 offset1:48
	ds_write2_b32 v237, v1, v5 offset0:64 offset1:80
	ds_write2_b32 v237, v9, v13 offset0:96 offset1:112
	ds_write2_b32 v237, v2, v6 offset0:128 offset1:144
	ds_write2_b32 v237, v10, v14 offset0:160 offset1:176
	ds_write2_b32 v237, v3, v7 offset0:192 offset1:208
	ds_write2_b32 v237, v11, v15 offset0:224 offset1:240
	ds_write2_b32 v238, v16, v20 offset0:0 offset1:16
	ds_write2_b32 v238, v24, v28 offset0:32 offset1:48
	ds_write2_b32 v238, v17, v21 offset0:64 offset1:80
	ds_write2_b32 v238, v25, v29 offset0:96 offset1:112
	ds_write2_b32 v238, v18, v22 offset0:128 offset1:144
	ds_write2_b32 v238, v26, v30 offset0:160 offset1:176
	ds_write2_b32 v238, v19, v23 offset0:192 offset1:208
	ds_write2_b32 v238, v27, v31 offset0:224 offset1:240
	s_waitcnt lgkmcnt(0)
	ds_read2st64_b32 v[0:1], v239 offset0:36 offset1:37
	ds_read2st64_b32 v[2:3], v239 offset0:38 offset1:39
	ds_read2st64_b32 v[4:5], v239 offset0:40 offset1:41
	ds_read2st64_b32 v[6:7], v239 offset0:42 offset1:43
	ds_read2st64_b32 v[8:9], v239 offset0:44 offset1:45
	ds_read2st64_b32 v[10:11], v239 offset0:46 offset1:47
	ds_read2st64_b32 v[12:13], v239 offset0:48 offset1:49
	ds_read2st64_b32 v[14:15], v239 offset0:50 offset1:51
	ds_read2st64_b32 v[16:17], v239 offset0:52 offset1:53
	ds_read2st64_b32 v[18:19], v239 offset0:54 offset1:55
	ds_read2st64_b32 v[20:21], v239 offset0:56 offset1:57
	ds_read2st64_b32 v[22:23], v239 offset0:58 offset1:59
	ds_read2st64_b32 v[24:25], v239 offset0:60 offset1:61
	ds_read2st64_b32 v[26:27], v239 offset0:62 offset1:63
	ds_read2st64_b32 v[28:29], v239 offset0:64 offset1:65
	ds_read2st64_b32 v[30:31], v239 offset0:66 offset1:67
	ds_read_u16_d16_hi v48, v240 offset:4608
	ds_read_u16_d16_hi v49, v240 offset:4752
	ds_read_u16_d16_hi v50, v240 offset:4896
	ds_read_u16_d16_hi v51, v240 offset:5040
	ds_read_u16_d16_hi v52, v240 offset:5184
	ds_read_u16_d16_hi v53, v240 offset:5328
	ds_read_u16_d16_hi v54, v240 offset:5472
	ds_read_u16_d16_hi v55, v240 offset:5616
	ds_read_u16_d16_hi v56, v240 offset:5760
	ds_read_u16_d16_hi v57, v240 offset:5904
	ds_read_u16_d16_hi v58, v240 offset:6048
	ds_read_u16_d16_hi v59, v240 offset:6192
	ds_read_u16_d16_hi v60, v240 offset:6336
	ds_read_u16_d16_hi v61, v240 offset:6480
	ds_read_u16_d16_hi v62, v240 offset:6624
	ds_read_u16_d16_hi v63, v240 offset:6768
	s_waitcnt lgkmcnt(0)
	v_pk_fma_f32 v[0:1], v[0:1], v[248:249], v[242:243]
	v_pk_fma_f32 v[2:3], v[2:3], v[248:249], v[242:243]
	v_pk_fma_f32 v[4:5], v[4:5], v[248:249], v[242:243]
	v_pk_fma_f32 v[6:7], v[6:7], v[248:249], v[242:243]
	v_pk_fma_f32 v[8:9], v[8:9], v[248:249], v[242:243]
	v_pk_fma_f32 v[10:11], v[10:11], v[248:249], v[242:243]
	v_pk_fma_f32 v[12:13], v[12:13], v[248:249], v[242:243]
	v_pk_fma_f32 v[14:15], v[14:15], v[248:249], v[242:243]
	v_pk_fma_f32 v[16:17], v[16:17], v[248:249], v[244:245]
	v_pk_fma_f32 v[18:19], v[18:19], v[248:249], v[244:245]
	v_pk_fma_f32 v[20:21], v[20:21], v[248:249], v[244:245]
	v_pk_fma_f32 v[22:23], v[22:23], v[248:249], v[244:245]
	v_pk_fma_f32 v[24:25], v[24:25], v[248:249], v[244:245]
	v_pk_fma_f32 v[26:27], v[26:27], v[248:249], v[244:245]
	v_pk_fma_f32 v[28:29], v[28:29], v[248:249], v[244:245]
	v_pk_fma_f32 v[30:31], v[30:31], v[248:249], v[244:245]
	v_exp_f32_e32 v0, v0
	v_exp_f32_e32 v1, v1
	v_exp_f32_e32 v2, v2
	v_exp_f32_e32 v3, v3
	v_exp_f32_e32 v4, v4
	v_exp_f32_e32 v5, v5
	v_exp_f32_e32 v6, v6
	v_exp_f32_e32 v7, v7
	v_exp_f32_e32 v8, v8
	v_exp_f32_e32 v9, v9
	v_exp_f32_e32 v10, v10
	v_exp_f32_e32 v11, v11
	v_exp_f32_e32 v12, v12
	v_exp_f32_e32 v13, v13
	v_exp_f32_e32 v14, v14
	v_exp_f32_e32 v15, v15
	v_exp_f32_e32 v16, v16
	v_exp_f32_e32 v17, v17
	v_exp_f32_e32 v18, v18
	v_exp_f32_e32 v19, v19
	v_exp_f32_e32 v20, v20
	v_exp_f32_e32 v21, v21
	v_exp_f32_e32 v22, v22
	v_exp_f32_e32 v23, v23
	v_exp_f32_e32 v24, v24
	v_exp_f32_e32 v25, v25
	v_exp_f32_e32 v26, v26
	v_exp_f32_e32 v27, v27
	v_exp_f32_e32 v28, v28
	v_exp_f32_e32 v29, v29
	v_exp_f32_e32 v30, v30
	v_exp_f32_e32 v31, v31
	v_pk_add_f32 v[0:1], v[0:1], 1.0 op_sel_hi:[1,0]
	v_pk_add_f32 v[2:3], v[2:3], 1.0 op_sel_hi:[1,0]
	v_pk_add_f32 v[4:5], v[4:5], 1.0 op_sel_hi:[1,0]
	v_pk_add_f32 v[6:7], v[6:7], 1.0 op_sel_hi:[1,0]
	v_pk_add_f32 v[8:9], v[8:9], 1.0 op_sel_hi:[1,0]
	v_pk_add_f32 v[10:11], v[10:11], 1.0 op_sel_hi:[1,0]
	v_pk_add_f32 v[12:13], v[12:13], 1.0 op_sel_hi:[1,0]
	v_pk_add_f32 v[14:15], v[14:15], 1.0 op_sel_hi:[1,0]
	v_pk_add_f32 v[16:17], v[16:17], 1.0 op_sel_hi:[1,0]
	v_pk_add_f32 v[18:19], v[18:19], 1.0 op_sel_hi:[1,0]
	v_pk_add_f32 v[20:21], v[20:21], 1.0 op_sel_hi:[1,0]
; __device__ __forceinline__ float sigmoid_f(float x) { return rcpf_(1.f + __expf(-x)); }
; __device__ __forceinline__ float gelu_tanh_f(float x) { const float y = 0.7978845608028654f * (x + 0.044715f * x * x * x); return x * sigmoid_f(2.f * y); }
; template <bool FINAL, int D>
; __device__ __forceinline__ void rg_dir(PREF p, int l, int h, int ch, int sidx, int rowbase  , LAS bf16_t* sXc, LAS float* stg, int lane) {
;     ...
;         for (int ti = 0; ti < 16; ++ti) { const int tk = D ? 15 - ti : ti;
;             const float zr = stg[tk * 64 + lane] + ba, zi = stg[1024 + tk * 64 + lane] + bi;
;             const float r = sigmoid_f(zr), ig = sigmoid_f(zi);
;             const float a = __builtin_amdgcn_exp2f(r * sp8);
;             const float xc = bf2f(sXc[(mt * 16 + tk) * 72 + lane]);
;             av[ti] = a; iv[ti] = __builtin_amdgcn_sqrtf(fmaxf(1.f - a * a, 0.f)) * ig * xc;
;             if (FINAL && D == 1) grv[ti] = gelu_tanh_f(grv[ti]);
;         }
; #pragma unroll
;         for (int ti = 0; ti < 16; ++ti) { const int tk = D ? 15 - ti : ti;
;             hc = av[ti] * hc + iv[ti]; Ap *= av[ti];
	v_pk_add_f32 v[22:23], v[22:23], 1.0 op_sel_hi:[1,0]
	v_pk_add_f32 v[24:25], v[24:25], 1.0 op_sel_hi:[1,0]
	v_pk_add_f32 v[26:27], v[26:27], 1.0 op_sel_hi:[1,0]
	v_pk_add_f32 v[28:29], v[28:29], 1.0 op_sel_hi:[1,0]
	v_pk_add_f32 v[30:31], v[30:31], 1.0 op_sel_hi:[1,0]
	v_rcp_f32_e32 v0, v0
	v_rcp_f32_e32 v1, v1
	v_rcp_f32_e32 v2, v2
	v_rcp_f32_e32 v3, v3
	v_rcp_f32_e32 v4, v4
	v_rcp_f32_e32 v5, v5
	v_rcp_f32_e32 v6, v6
	v_rcp_f32_e32 v7, v7
	v_rcp_f32_e32 v8, v8
	v_rcp_f32_e32 v9, v9
	v_rcp_f32_e32 v10, v10
	v_rcp_f32_e32 v11, v11
	v_rcp_f32_e32 v12, v12
	v_rcp_f32_e32 v13, v13
	v_rcp_f32_e32 v14, v14
	v_rcp_f32_e32 v15, v15
	v_rcp_f32_e32 v16, v16
	v_rcp_f32_e32 v17, v17
	v_rcp_f32_e32 v18, v18
	v_rcp_f32_e32 v19, v19
	v_rcp_f32_e32 v20, v20
	v_rcp_f32_e32 v21, v21
	v_rcp_f32_e32 v22, v22
	v_rcp_f32_e32 v23, v23
	v_rcp_f32_e32 v24, v24
	v_rcp_f32_e32 v25, v25
	v_rcp_f32_e32 v26, v26
	v_rcp_f32_e32 v27, v27
	v_rcp_f32_e32 v28, v28
	v_rcp_f32_e32 v29, v29
	v_rcp_f32_e32 v30, v30
	v_rcp_f32_e32 v31, v31
	v_pk_mul_f32 v[0:1], v[246:247], v[0:1]
	v_pk_mul_f32 v[2:3], v[246:247], v[2:3]
	v_pk_mul_f32 v[4:5], v[246:247], v[4:5]
	v_pk_mul_f32 v[6:7], v[246:247], v[6:7]
	v_pk_mul_f32 v[8:9], v[246:247], v[8:9]
	v_pk_mul_f32 v[10:11], v[246:247], v[10:11]
	v_pk_mul_f32 v[12:13], v[246:247], v[12:13]
	v_pk_mul_f32 v[14:15], v[246:247], v[14:15]
	v_exp_f32_e32 v0, v0
	v_exp_f32_e32 v1, v1
	v_exp_f32_e32 v2, v2
	v_exp_f32_e32 v3, v3
	v_exp_f32_e32 v4, v4
	v_exp_f32_e32 v5, v5
	v_exp_f32_e32 v6, v6
	v_exp_f32_e32 v7, v7
	v_exp_f32_e32 v8, v8
	v_exp_f32_e32 v9, v9
	v_exp_f32_e32 v10, v10
	v_exp_f32_e32 v11, v11
	v_exp_f32_e32 v12, v12
	v_exp_f32_e32 v13, v13
	v_exp_f32_e32 v14, v14
	v_exp_f32_e32 v15, v15
	v_fma_f32 v32, -v0, v0, 1.0
	v_fma_f32 v33, -v1, v1, 1.0
	v_fma_f32 v34, -v2, v2, 1.0
	v_fma_f32 v35, -v3, v3, 1.0
	v_fma_f32 v36, -v4, v4, 1.0
	v_fma_f32 v37, -v5, v5, 1.0
	v_fma_f32 v38, -v6, v6, 1.0
	v_fma_f32 v39, -v7, v7, 1.0
	v_fma_f32 v40, -v8, v8, 1.0
	v_fma_f32 v41, -v9, v9, 1.0
	v_fma_f32 v42, -v10, v10, 1.0
	v_fma_f32 v43, -v11, v11, 1.0
	v_fma_f32 v44, -v12, v12, 1.0
	v_fma_f32 v45, -v13, v13, 1.0
	v_fma_f32 v46, -v14, v14, 1.0
	v_fma_f32 v47, -v15, v15, 1.0
	v_max_f32_e32 v32, 0, v32
	v_max_f32_e32 v33, 0, v33
	v_max_f32_e32 v34, 0, v34
	v_max_f32_e32 v35, 0, v35
	v_max_f32_e32 v36, 0, v36
	v_max_f32_e32 v37, 0, v37
	v_max_f32_e32 v38, 0, v38
	v_max_f32_e32 v39, 0, v39
	v_max_f32_e32 v40, 0, v40
	v_max_f32_e32 v41, 0, v41
	v_max_f32_e32 v42, 0, v42
	v_max_f32_e32 v43, 0, v43
	v_max_f32_e32 v44, 0, v44
	v_max_f32_e32 v45, 0, v45
	v_max_f32_e32 v46, 0, v46
	v_max_f32_e32 v47, 0, v47
	v_sqrt_f32_e32 v32, v32
	v_sqrt_f32_e32 v33, v33
	v_sqrt_f32_e32 v34, v34
	v_sqrt_f32_e32 v35, v35
	v_sqrt_f32_e32 v36, v36
	v_sqrt_f32_e32 v37, v37
	v_sqrt_f32_e32 v38, v38
	v_sqrt_f32_e32 v39, v39
	v_sqrt_f32_e32 v40, v40
	v_sqrt_f32_e32 v41, v41
	v_sqrt_f32_e32 v42, v42
	v_sqrt_f32_e32 v43, v43
	v_sqrt_f32_e32 v44, v44
	v_sqrt_f32_e32 v45, v45
	v_sqrt_f32_e32 v46, v46
	v_sqrt_f32_e32 v47, v47
	s_nop 0
	v_pk_mul_f32 v[16:17], v[16:17], v[32:33]
	v_pk_mul_f32 v[18:19], v[18:19], v[34:35]
	v_pk_mul_f32 v[20:21], v[20:21], v[36:37]
	v_pk_mul_f32 v[22:23], v[22:23], v[38:39]
	v_pk_mul_f32 v[24:25], v[24:25], v[40:41]
	v_pk_mul_f32 v[26:27], v[26:27], v[42:43]
	v_pk_mul_f32 v[28:29], v[28:29], v[44:45]
	v_pk_mul_f32 v[30:31], v[30:31], v[46:47]
	v_pk_mul_f32 v[16:17], v[16:17], v[48:49]
	v_pk_mul_f32 v[18:19], v[18:19], v[50:51]
	v_pk_mul_f32 v[20:21], v[20:21], v[52:53]
	v_pk_mul_f32 v[22:23], v[22:23], v[54:55]
	v_pk_mul_f32 v[24:25], v[24:25], v[56:57]
	v_pk_mul_f32 v[26:27], v[26:27], v[58:59]
	v_pk_mul_f32 v[28:29], v[28:29], v[60:61]
	v_pk_mul_f32 v[30:31], v[30:31], v[62:63]
	v_fma_f32 v250, v15, v250, v31
	v_mul_f32_e32 v232, v232, v15
	v_fma_f32 v250, v14, v250, v30
	v_mul_f32_e32 v232, v232, v14
	v_fma_f32 v250, v13, v250, v29
	v_mul_f32_e32 v232, v232, v13
	v_fma_f32 v250, v12, v250, v28
	v_mul_f32_e32 v232, v232, v12
	v_fma_f32 v250, v11, v250, v27
	v_mul_f32_e32 v232, v232, v11
	v_fma_f32 v250, v10, v250, v26
	v_mul_f32_e32 v232, v232, v10
	v_fma_f32 v250, v9, v250, v25
	v_mul_f32_e32 v232, v232, v9
	v_fma_f32 v250, v8, v250, v24
	v_mul_f32_e32 v232, v232, v8
	v_fma_f32 v250, v7, v250, v23
	v_mul_f32_e32 v232, v232, v7
	v_fma_f32 v250, v6, v250, v22
	v_mul_f32_e32 v232, v232, v6
	v_fma_f32 v250, v5, v250, v21
	v_mul_f32_e32 v232, v232, v5
	v_fma_f32 v250, v4, v250, v20
	v_mul_f32_e32 v232, v232, v4
	v_fma_f32 v250, v3, v250, v19
	v_mul_f32_e32 v232, v232, v3
	v_fma_f32 v250, v2, v250, v18
	v_mul_f32_e32 v232, v232, v2
	v_fma_f32 v250, v1, v250, v17
	v_mul_f32_e32 v232, v232, v1
	v_fma_f32 v250, v0, v250, v16
	v_mul_f32_e32 v232, v232, v0
	ds_read_b128 v[32:35], v236 offset:2304
	ds_read_b128 v[36:39], v236 offset:2368
	s_waitcnt lgkmcnt(0)
; #define LAS __attribute__((address_space(3)))
; #define WAVE_SYNC() asm volatile("s_waitcnt lgkmcnt(0)" ::: "memory")
; __device__ __forceinline__ float sigmoid_f(float x) { return rcpf_(1.f + __expf(-x)); }
; __device__ __forceinline__ f32x4 mfma16(bf16x8 a, bf16x8 b, f32x4 c) { return __builtin_amdgcn_mfma_f32_16x16x32_bf16(a, b, c, 0, 0, 0); }
; template <bool FINAL, int D>
; __device__ __forceinline__ void rg_dir(PREF p, int l, int h, int ch, int sidx, int rowbase  , LAS bf16_t* sXc, LAS float* stg, int lane) {
;     ...
;         const bf16x8 A0 = *(const LAS bf16x8*)(sXc + (mt * 16 + (lane & 15)) * 72 + (lane >> 4) * 8), A1 = *(const LAS bf16x8*)(sXc + (mt * 16 + (lane & 15)) * 72 + 32 + (lane >> 4) * 8);
;         f32x4 ar[4], ai[4];
; #pragma unroll
;         for (int nt = 0; nt < 4; ++nt) { const f32x4 z = {0.f, 0.f, 0.f, 0.f};
;             ar[nt] = mfma16(A0, Br[nt][0], z); ar[nt] = mfma16(A1, Br[nt][1], ar[nt]); ai[nt] = mfma16(A0, Bi[nt][0], z); ai[nt] = mfma16(A1, Bi[nt][1], ai[nt]); }
;         WAVE_SYNC();
; #pragma unroll
;         for (int nt = 0; nt < 4; ++nt)
; #pragma unroll
;             for (int j = 0; j < 4; ++j) { const int o = ((lane >> 4) * 4 + j) * 64 + nt * 16 + (lane & 15); stg[o] = ar[nt][j]; stg[1024 + o] = ai[nt][j]; }
;         WAVE_SYNC();
;         float av[16], iv[16];
; #pragma unroll
;         for (int ti = 0; ti < 16; ++ti) { const int tk = D ? 15 - ti : ti;
;             const float zr = stg[tk * 64 + lane] + ba, zi = stg[1024 + tk * 64 + lane] + bi;
;             const float r = sigmoid_f(zr), ig = sigmoid_f(zi);
;             const float a = __builtin_amdgcn_exp2f(r * sp8);
;             const float xc = bf2f(sXc[(mt * 16 + tk) * 72 + lane]);
	v_mfma_f32_16x16x32_bf16 v[0:3], v[32:35], v[80:83], 0
	v_mfma_f32_16x16x32_bf16 v[4:7], v[32:35], v[88:91], 0
	v_mfma_f32_16x16x32_bf16 v[8:11], v[32:35], v[96:99], 0
	v_mfma_f32_16x16x32_bf16 v[12:15], v[32:35], v[104:107], 0
	v_mfma_f32_16x16x32_bf16 v[16:19], v[32:35], v[112:115], 0
	v_mfma_f32_16x16x32_bf16 v[20:23], v[32:35], v[120:123], 0
	v_mfma_f32_16x16x32_bf16 v[24:27], v[32:35], v[128:131], 0
	v_mfma_f32_16x16x32_bf16 v[28:31], v[32:35], v[136:139], 0
	v_mfma_f32_16x16x32_bf16 v[0:3], v[36:39], v[84:87], v[0:3]
	v_mfma_f32_16x16x32_bf16 v[4:7], v[36:39], v[92:95], v[4:7]
	v_mfma_f32_16x16x32_bf16 v[8:11], v[36:39], v[100:103], v[8:11]
	v_mfma_f32_16x16x32_bf16 v[12:15], v[36:39], v[108:111], v[12:15]
	v_mfma_f32_16x16x32_bf16 v[16:19], v[36:39], v[148:151], v[16:19]
	v_mfma_f32_16x16x32_bf16 v[20:23], v[36:39], v[124:127], v[20:23]
	v_mfma_f32_16x16x32_bf16 v[24:27], v[36:39], v[132:135], v[24:27]
	v_mfma_f32_16x16x32_bf16 v[28:31], v[36:39], v[228:231], v[28:31]
	s_nop 3
	ds_write2_b32 v237, v0, v4 offset0:0 offset1:16
	ds_write2_b32 v237, v8, v12 offset0:32 offset1:48
	ds_write2_b32 v237, v1, v5 offset0:64 offset1:80
	ds_write2_b32 v237, v9, v13 offset0:96 offset1:112
	ds_write2_b32 v237, v2, v6 offset0:128 offset1:144
	ds_write2_b32 v237, v10, v14 offset0:160 offset1:176
	ds_write2_b32 v237, v3, v7 offset0:192 offset1:208
	ds_write2_b32 v237, v11, v15 offset0:224 offset1:240
	ds_write2_b32 v238, v16, v20 offset0:0 offset1:16
	ds_write2_b32 v238, v24, v28 offset0:32 offset1:48
	ds_write2_b32 v238, v17, v21 offset0:64 offset1:80
	ds_write2_b32 v238, v25, v29 offset0:96 offset1:112
	ds_write2_b32 v238, v18, v22 offset0:128 offset1:144
	ds_write2_b32 v238, v26, v30 offset0:160 offset1:176
	ds_write2_b32 v238, v19, v23 offset0:192 offset1:208
	ds_write2_b32 v238, v27, v31 offset0:224 offset1:240
	s_waitcnt lgkmcnt(0)
	ds_read2st64_b32 v[0:1], v239 offset0:36 offset1:37
	ds_read2st64_b32 v[2:3], v239 offset0:38 offset1:39
	ds_read2st64_b32 v[4:5], v239 offset0:40 offset1:41
	ds_read2st64_b32 v[6:7], v239 offset0:42 offset1:43
	ds_read2st64_b32 v[8:9], v239 offset0:44 offset1:45
	ds_read2st64_b32 v[10:11], v239 offset0:46 offset1:47
	ds_read2st64_b32 v[12:13], v239 offset0:48 offset1:49
	ds_read2st64_b32 v[14:15], v239 offset0:50 offset1:51
	ds_read2st64_b32 v[16:17], v239 offset0:52 offset1:53
	ds_read2st64_b32 v[18:19], v239 offset0:54 offset1:55
	ds_read2st64_b32 v[20:21], v239 offset0:56 offset1:57
	ds_read2st64_b32 v[22:23], v239 offset0:58 offset1:59
	ds_read2st64_b32 v[24:25], v239 offset0:60 offset1:61
	ds_read2st64_b32 v[26:27], v239 offset0:62 offset1:63
	ds_read2st64_b32 v[28:29], v239 offset0:64 offset1:65
	ds_read2st64_b32 v[30:31], v239 offset0:66 offset1:67
	ds_read_u16_d16_hi v48, v240 offset:2304
	ds_read_u16_d16_hi v49, v240 offset:2448
	ds_read_u16_d16_hi v50, v240 offset:2592
	ds_read_u16_d16_hi v51, v240 offset:2736
	ds_read_u16_d16_hi v52, v240 offset:2880
	ds_read_u16_d16_hi v53, v240 offset:3024
	ds_read_u16_d16_hi v54, v240 offset:3168
	ds_read_u16_d16_hi v55, v240 offset:3312
	ds_read_u16_d16_hi v56, v240 offset:3456
	ds_read_u16_d16_hi v57, v240 offset:3600
	ds_read_u16_d16_hi v58, v240 offset:3744
	ds_read_u16_d16_hi v59, v240 offset:3888
	ds_read_u16_d16_hi v60, v240 offset:4032
	ds_read_u16_d16_hi v61, v240 offset:4176
	ds_read_u16_d16_hi v62, v240 offset:4320
	ds_read_u16_d16_hi v63, v240 offset:4464
	s_waitcnt lgkmcnt(0)
	v_pk_fma_f32 v[0:1], v[0:1], v[248:249], v[242:243]
	v_pk_fma_f32 v[2:3], v[2:3], v[248:249], v[242:243]
	v_pk_fma_f32 v[4:5], v[4:5], v[248:249], v[242:243]
	v_pk_fma_f32 v[6:7], v[6:7], v[248:249], v[242:243]
	v_pk_fma_f32 v[8:9], v[8:9], v[248:249], v[242:243]
	v_pk_fma_f32 v[10:11], v[10:11], v[248:249], v[242:243]
	v_pk_fma_f32 v[12:13], v[12:13], v[248:249], v[242:243]
	v_pk_fma_f32 v[14:15], v[14:15], v[248:249], v[242:243]
	v_pk_fma_f32 v[16:17], v[16:17], v[248:249], v[244:245]
	v_pk_fma_f32 v[18:19], v[18:19], v[248:249], v[244:245]
	v_pk_fma_f32 v[20:21], v[20:21], v[248:249], v[244:245]
	v_pk_fma_f32 v[22:23], v[22:23], v[248:249], v[244:245]
	v_pk_fma_f32 v[24:25], v[24:25], v[248:249], v[244:245]
	v_pk_fma_f32 v[26:27], v[26:27], v[248:249], v[244:245]
	v_pk_fma_f32 v[28:29], v[28:29], v[248:249], v[244:245]
	v_pk_fma_f32 v[30:31], v[30:31], v[248:249], v[244:245]
	v_exp_f32_e32 v0, v0
	v_exp_f32_e32 v1, v1
	v_exp_f32_e32 v2, v2
	v_exp_f32_e32 v3, v3
	v_exp_f32_e32 v4, v4
	v_exp_f32_e32 v5, v5
	v_exp_f32_e32 v6, v6
	v_exp_f32_e32 v7, v7
	v_exp_f32_e32 v8, v8
	v_exp_f32_e32 v9, v9
	v_exp_f32_e32 v10, v10
	v_exp_f32_e32 v11, v11
	v_exp_f32_e32 v12, v12
	v_exp_f32_e32 v13, v13
	v_exp_f32_e32 v14, v14
	v_exp_f32_e32 v15, v15
	v_exp_f32_e32 v16, v16
	v_exp_f32_e32 v17, v17
	v_exp_f32_e32 v18, v18
	v_exp_f32_e32 v19, v19
	v_exp_f32_e32 v20, v20
	v_exp_f32_e32 v21, v21
	v_exp_f32_e32 v22, v22
	v_exp_f32_e32 v23, v23
	v_exp_f32_e32 v24, v24
	v_exp_f32_e32 v25, v25
	v_exp_f32_e32 v26, v26
	v_exp_f32_e32 v27, v27
	v_exp_f32_e32 v28, v28
	v_exp_f32_e32 v29, v29
	v_exp_f32_e32 v30, v30
	v_exp_f32_e32 v31, v31
	v_pk_add_f32 v[0:1], v[0:1], 1.0 op_sel_hi:[1,0]
	v_pk_add_f32 v[2:3], v[2:3], 1.0 op_sel_hi:[1,0]
	v_pk_add_f32 v[4:5], v[4:5], 1.0 op_sel_hi:[1,0]
	v_pk_add_f32 v[6:7], v[6:7], 1.0 op_sel_hi:[1,0]
	v_pk_add_f32 v[8:9], v[8:9], 1.0 op_sel_hi:[1,0]
	v_pk_add_f32 v[10:11], v[10:11], 1.0 op_sel_hi:[1,0]
	v_pk_add_f32 v[12:13], v[12:13], 1.0 op_sel_hi:[1,0]
	v_pk_add_f32 v[14:15], v[14:15], 1.0 op_sel_hi:[1,0]
	v_pk_add_f32 v[16:17], v[16:17], 1.0 op_sel_hi:[1,0]
	v_pk_add_f32 v[18:19], v[18:19], 1.0 op_sel_hi:[1,0]
	v_pk_add_f32 v[20:21], v[20:21], 1.0 op_sel_hi:[1,0]
; __device__ __forceinline__ float sigmoid_f(float x) { return rcpf_(1.f + __expf(-x)); }
; __device__ __forceinline__ float gelu_tanh_f(float x) { const float y = 0.7978845608028654f * (x + 0.044715f * x * x * x); return x * sigmoid_f(2.f * y); }
; template <bool FINAL, int D>
; __device__ __forceinline__ void rg_dir(PREF p, int l, int h, int ch, int sidx, int rowbase  , LAS bf16_t* sXc, LAS float* stg, int lane) {
;     ...
;         for (int ti = 0; ti < 16; ++ti) { const int tk = D ? 15 - ti : ti;
;             const float zr = stg[tk * 64 + lane] + ba, zi = stg[1024 + tk * 64 + lane] + bi;
;             const float r = sigmoid_f(zr), ig = sigmoid_f(zi);
;             const float a = __builtin_amdgcn_exp2f(r * sp8);
;             const float xc = bf2f(sXc[(mt * 16 + tk) * 72 + lane]);
;             av[ti] = a; iv[ti] = __builtin_amdgcn_sqrtf(fmaxf(1.f - a * a, 0.f)) * ig * xc;
;             if (FINAL && D == 1) grv[ti] = gelu_tanh_f(grv[ti]);
;         }
; #pragma unroll
;         for (int ti = 0; ti < 16; ++ti) { const int tk = D ? 15 - ti : ti;
;             hc = av[ti] * hc + iv[ti]; Ap *= av[ti];
	v_pk_add_f32 v[22:23], v[22:23], 1.0 op_sel_hi:[1,0]
	v_pk_add_f32 v[24:25], v[24:25], 1.0 op_sel_hi:[1,0]
	v_pk_add_f32 v[26:27], v[26:27], 1.0 op_sel_hi:[1,0]
	v_pk_add_f32 v[28:29], v[28:29], 1.0 op_sel_hi:[1,0]
	v_pk_add_f32 v[30:31], v[30:31], 1.0 op_sel_hi:[1,0]
	v_rcp_f32_e32 v0, v0
	v_rcp_f32_e32 v1, v1
	v_rcp_f32_e32 v2, v2
	v_rcp_f32_e32 v3, v3
	v_rcp_f32_e32 v4, v4
	v_rcp_f32_e32 v5, v5
	v_rcp_f32_e32 v6, v6
	v_rcp_f32_e32 v7, v7
	v_rcp_f32_e32 v8, v8
	v_rcp_f32_e32 v9, v9
	v_rcp_f32_e32 v10, v10
	v_rcp_f32_e32 v11, v11
	v_rcp_f32_e32 v12, v12
	v_rcp_f32_e32 v13, v13
	v_rcp_f32_e32 v14, v14
	v_rcp_f32_e32 v15, v15
	v_rcp_f32_e32 v16, v16
	v_rcp_f32_e32 v17, v17
	v_rcp_f32_e32 v18, v18
	v_rcp_f32_e32 v19, v19
	v_rcp_f32_e32 v20, v20
	v_rcp_f32_e32 v21, v21
	v_rcp_f32_e32 v22, v22
	v_rcp_f32_e32 v23, v23
	v_rcp_f32_e32 v24, v24
	v_rcp_f32_e32 v25, v25
	v_rcp_f32_e32 v26, v26
	v_rcp_f32_e32 v27, v27
	v_rcp_f32_e32 v28, v28
	v_rcp_f32_e32 v29, v29
	v_rcp_f32_e32 v30, v30
	v_rcp_f32_e32 v31, v31
	v_pk_mul_f32 v[0:1], v[246:247], v[0:1]
	v_pk_mul_f32 v[2:3], v[246:247], v[2:3]
	v_pk_mul_f32 v[4:5], v[246:247], v[4:5]
	v_pk_mul_f32 v[6:7], v[246:247], v[6:7]
	v_pk_mul_f32 v[8:9], v[246:247], v[8:9]
	v_pk_mul_f32 v[10:11], v[246:247], v[10:11]
	v_pk_mul_f32 v[12:13], v[246:247], v[12:13]
	v_pk_mul_f32 v[14:15], v[246:247], v[14:15]
	v_exp_f32_e32 v0, v0
	v_exp_f32_e32 v1, v1
	v_exp_f32_e32 v2, v2
	v_exp_f32_e32 v3, v3
	v_exp_f32_e32 v4, v4
	v_exp_f32_e32 v5, v5
	v_exp_f32_e32 v6, v6
	v_exp_f32_e32 v7, v7
	v_exp_f32_e32 v8, v8
	v_exp_f32_e32 v9, v9
	v_exp_f32_e32 v10, v10
	v_exp_f32_e32 v11, v11
	v_exp_f32_e32 v12, v12
	v_exp_f32_e32 v13, v13
	v_exp_f32_e32 v14, v14
	v_exp_f32_e32 v15, v15
	v_fma_f32 v32, -v0, v0, 1.0
	v_fma_f32 v33, -v1, v1, 1.0
	v_fma_f32 v34, -v2, v2, 1.0
	v_fma_f32 v35, -v3, v3, 1.0
	v_fma_f32 v36, -v4, v4, 1.0
	v_fma_f32 v37, -v5, v5, 1.0
	v_fma_f32 v38, -v6, v6, 1.0
	v_fma_f32 v39, -v7, v7, 1.0
	v_fma_f32 v40, -v8, v8, 1.0
	v_fma_f32 v41, -v9, v9, 1.0
	v_fma_f32 v42, -v10, v10, 1.0
	v_fma_f32 v43, -v11, v11, 1.0
	v_fma_f32 v44, -v12, v12, 1.0
	v_fma_f32 v45, -v13, v13, 1.0
	v_fma_f32 v46, -v14, v14, 1.0
	v_fma_f32 v47, -v15, v15, 1.0
	v_max_f32_e32 v32, 0, v32
	v_max_f32_e32 v33, 0, v33
	v_max_f32_e32 v34, 0, v34
	v_max_f32_e32 v35, 0, v35
	v_max_f32_e32 v36, 0, v36
	v_max_f32_e32 v37, 0, v37
	v_max_f32_e32 v38, 0, v38
	v_max_f32_e32 v39, 0, v39
	v_max_f32_e32 v40, 0, v40
	v_max_f32_e32 v41, 0, v41
	v_max_f32_e32 v42, 0, v42
	v_max_f32_e32 v43, 0, v43
	v_max_f32_e32 v44, 0, v44
	v_max_f32_e32 v45, 0, v45
	v_max_f32_e32 v46, 0, v46
	v_max_f32_e32 v47, 0, v47
	v_sqrt_f32_e32 v32, v32
	v_sqrt_f32_e32 v33, v33
	v_sqrt_f32_e32 v34, v34
	v_sqrt_f32_e32 v35, v35
	v_sqrt_f32_e32 v36, v36
	v_sqrt_f32_e32 v37, v37
	v_sqrt_f32_e32 v38, v38
	v_sqrt_f32_e32 v39, v39
	v_sqrt_f32_e32 v40, v40
	v_sqrt_f32_e32 v41, v41
	v_sqrt_f32_e32 v42, v42
	v_sqrt_f32_e32 v43, v43
	v_sqrt_f32_e32 v44, v44
	v_sqrt_f32_e32 v45, v45
	v_sqrt_f32_e32 v46, v46
	v_sqrt_f32_e32 v47, v47
	s_nop 0
	v_pk_mul_f32 v[16:17], v[16:17], v[32:33]
	v_pk_mul_f32 v[18:19], v[18:19], v[34:35]
	v_pk_mul_f32 v[20:21], v[20:21], v[36:37]
	v_pk_mul_f32 v[22:23], v[22:23], v[38:39]
	v_pk_mul_f32 v[24:25], v[24:25], v[40:41]
	v_pk_mul_f32 v[26:27], v[26:27], v[42:43]
	v_pk_mul_f32 v[28:29], v[28:29], v[44:45]
	v_pk_mul_f32 v[30:31], v[30:31], v[46:47]
	v_pk_mul_f32 v[16:17], v[16:17], v[48:49]
	v_pk_mul_f32 v[18:19], v[18:19], v[50:51]
	v_pk_mul_f32 v[20:21], v[20:21], v[52:53]
	v_pk_mul_f32 v[22:23], v[22:23], v[54:55]
	v_pk_mul_f32 v[24:25], v[24:25], v[56:57]
	v_pk_mul_f32 v[26:27], v[26:27], v[58:59]
	v_pk_mul_f32 v[28:29], v[28:29], v[60:61]
	v_pk_mul_f32 v[30:31], v[30:31], v[62:63]
	v_fma_f32 v250, v15, v250, v31
	v_mul_f32_e32 v232, v232, v15
	v_fma_f32 v250, v14, v250, v30
	v_mul_f32_e32 v232, v232, v14
	v_fma_f32 v250, v13, v250, v29
	v_mul_f32_e32 v232, v232, v13
	v_fma_f32 v250, v12, v250, v28
	v_mul_f32_e32 v232, v232, v12
	v_fma_f32 v250, v11, v250, v27
	v_mul_f32_e32 v232, v232, v11
	v_fma_f32 v250, v10, v250, v26
	v_mul_f32_e32 v232, v232, v10
	v_fma_f32 v250, v9, v250, v25
	v_mul_f32_e32 v232, v232, v9
	v_fma_f32 v250, v8, v250, v24
	v_mul_f32_e32 v232, v232, v8
	v_fma_f32 v250, v7, v250, v23
	v_mul_f32_e32 v232, v232, v7
	v_fma_f32 v250, v6, v250, v22
	v_mul_f32_e32 v232, v232, v6
	v_fma_f32 v250, v5, v250, v21
	v_mul_f32_e32 v232, v232, v5
	v_fma_f32 v250, v4, v250, v20
	v_mul_f32_e32 v232, v232, v4
	v_fma_f32 v250, v3, v250, v19
	v_mul_f32_e32 v232, v232, v3
	v_fma_f32 v250, v2, v250, v18
	v_mul_f32_e32 v232, v232, v2
	v_fma_f32 v250, v1, v250, v17
	v_mul_f32_e32 v232, v232, v1
	v_fma_f32 v250, v0, v250, v16
	v_mul_f32_e32 v232, v232, v0
	ds_read_b128 v[32:35], v236 offset:0
	ds_read_b128 v[36:39], v236 offset:64
	s_waitcnt lgkmcnt(0)
; #define LAS __attribute__((address_space(3)))
; #define WAVE_SYNC() asm volatile("s_waitcnt lgkmcnt(0)" ::: "memory")
; __device__ __forceinline__ float sigmoid_f(float x) { return rcpf_(1.f + __expf(-x)); }
; __device__ __forceinline__ f32x4 mfma16(bf16x8 a, bf16x8 b, f32x4 c) { return __builtin_amdgcn_mfma_f32_16x16x32_bf16(a, b, c, 0, 0, 0); }
; template <bool FINAL, int D>
; __device__ __forceinline__ void rg_dir(PREF p, int l, int h, int ch, int sidx, int rowbase  , LAS bf16_t* sXc, LAS float* stg, int lane) {
;     ...
;         const bf16x8 A0 = *(const LAS bf16x8*)(sXc + (mt * 16 + (lane & 15)) * 72 + (lane >> 4) * 8), A1 = *(const LAS bf16x8*)(sXc + (mt * 16 + (lane & 15)) * 72 + 32 + (lane >> 4) * 8);
;         f32x4 ar[4], ai[4];
; #pragma unroll
;         for (int nt = 0; nt < 4; ++nt) { const f32x4 z = {0.f, 0.f, 0.f, 0.f};
;             ar[nt] = mfma16(A0, Br[nt][0], z); ar[nt] = mfma16(A1, Br[nt][1], ar[nt]); ai[nt] = mfma16(A0, Bi[nt][0], z); ai[nt] = mfma16(A1, Bi[nt][1], ai[nt]); }
;         WAVE_SYNC();
; #pragma unroll
;         for (int nt = 0; nt < 4; ++nt)
; #pragma unroll
;             for (int j = 0; j < 4; ++j) { const int o = ((lane >> 4) * 4 + j) * 64 + nt * 16 + (lane & 15); stg[o] = ar[nt][j]; stg[1024 + o] = ai[nt][j]; }
;         WAVE_SYNC();
;         float av[16], iv[16];
; #pragma unroll
;         for (int ti = 0; ti < 16; ++ti) { const int tk = D ? 15 - ti : ti;
;             const float zr = stg[tk * 64 + lane] + ba, zi = stg[1024 + tk * 64 + lane] + bi;
;             const float r = sigmoid_f(zr), ig = sigmoid_f(zi);
;             const float a = __builtin_amdgcn_exp2f(r * sp8);
;             const float xc = bf2f(sXc[(mt * 16 + tk) * 72 + lane]);
	v_mfma_f32_16x16x32_bf16 v[0:3], v[32:35], v[80:83], 0
	v_mfma_f32_16x16x32_bf16 v[4:7], v[32:35], v[88:91], 0
	v_mfma_f32_16x16x32_bf16 v[8:11], v[32:35], v[96:99], 0
	v_mfma_f32_16x16x32_bf16 v[12:15], v[32:35], v[104:107], 0
	v_mfma_f32_16x16x32_bf16 v[16:19], v[32:35], v[112:115], 0
	v_mfma_f32_16x16x32_bf16 v[20:23], v[32:35], v[120:123], 0
	v_mfma_f32_16x16x32_bf16 v[24:27], v[32:35], v[128:131], 0
	v_mfma_f32_16x16x32_bf16 v[28:31], v[32:35], v[136:139], 0
	v_mfma_f32_16x16x32_bf16 v[0:3], v[36:39], v[84:87], v[0:3]
	v_mfma_f32_16x16x32_bf16 v[4:7], v[36:39], v[92:95], v[4:7]
	v_mfma_f32_16x16x32_bf16 v[8:11], v[36:39], v[100:103], v[8:11]
	v_mfma_f32_16x16x32_bf16 v[12:15], v[36:39], v[108:111], v[12:15]
	v_mfma_f32_16x16x32_bf16 v[16:19], v[36:39], v[148:151], v[16:19]
	v_mfma_f32_16x16x32_bf16 v[20:23], v[36:39], v[124:127], v[20:23]
	v_mfma_f32_16x16x32_bf16 v[24:27], v[36:39], v[132:135], v[24:27]
	v_mfma_f32_16x16x32_bf16 v[28:31], v[36:39], v[228:231], v[28:31]
	s_nop 3
	ds_write2_b32 v237, v0, v4 offset0:0 offset1:16
	ds_write2_b32 v237, v8, v12 offset0:32 offset1:48
	ds_write2_b32 v237, v1, v5 offset0:64 offset1:80
	ds_write2_b32 v237, v9, v13 offset0:96 offset1:112
	ds_write2_b32 v237, v2, v6 offset0:128 offset1:144
	ds_write2_b32 v237, v10, v14 offset0:160 offset1:176
	ds_write2_b32 v237, v3, v7 offset0:192 offset1:208
	ds_write2_b32 v237, v11, v15 offset0:224 offset1:240
	ds_write2_b32 v238, v16, v20 offset0:0 offset1:16
	ds_write2_b32 v238, v24, v28 offset0:32 offset1:48
	ds_write2_b32 v238, v17, v21 offset0:64 offset1:80
	ds_write2_b32 v238, v25, v29 offset0:96 offset1:112
	ds_write2_b32 v238, v18, v22 offset0:128 offset1:144
	ds_write2_b32 v238, v26, v30 offset0:160 offset1:176
	ds_write2_b32 v238, v19, v23 offset0:192 offset1:208
	ds_write2_b32 v238, v27, v31 offset0:224 offset1:240
	s_waitcnt lgkmcnt(0)
	ds_read2st64_b32 v[0:1], v239 offset0:36 offset1:37
	ds_read2st64_b32 v[2:3], v239 offset0:38 offset1:39
	ds_read2st64_b32 v[4:5], v239 offset0:40 offset1:41
	ds_read2st64_b32 v[6:7], v239 offset0:42 offset1:43
	ds_read2st64_b32 v[8:9], v239 offset0:44 offset1:45
	ds_read2st64_b32 v[10:11], v239 offset0:46 offset1:47
	ds_read2st64_b32 v[12:13], v239 offset0:48 offset1:49
	ds_read2st64_b32 v[14:15], v239 offset0:50 offset1:51
	ds_read2st64_b32 v[16:17], v239 offset0:52 offset1:53
	ds_read2st64_b32 v[18:19], v239 offset0:54 offset1:55
	ds_read2st64_b32 v[20:21], v239 offset0:56 offset1:57
	ds_read2st64_b32 v[22:23], v239 offset0:58 offset1:59
	ds_read2st64_b32 v[24:25], v239 offset0:60 offset1:61
	ds_read2st64_b32 v[26:27], v239 offset0:62 offset1:63
	ds_read2st64_b32 v[28:29], v239 offset0:64 offset1:65
	ds_read2st64_b32 v[30:31], v239 offset0:66 offset1:67
	ds_read_u16_d16_hi v48, v240 offset:0
	ds_read_u16_d16_hi v49, v240 offset:144
	ds_read_u16_d16_hi v50, v240 offset:288
	ds_read_u16_d16_hi v51, v240 offset:432
	ds_read_u16_d16_hi v52, v240 offset:576
	ds_read_u16_d16_hi v53, v240 offset:720
	ds_read_u16_d16_hi v54, v240 offset:864
	ds_read_u16_d16_hi v55, v240 offset:1008
	ds_read_u16_d16_hi v56, v240 offset:1152
	ds_read_u16_d16_hi v57, v240 offset:1296
	ds_read_u16_d16_hi v58, v240 offset:1440
	ds_read_u16_d16_hi v59, v240 offset:1584
	ds_read_u16_d16_hi v60, v240 offset:1728
	ds_read_u16_d16_hi v61, v240 offset:1872
	ds_read_u16_d16_hi v62, v240 offset:2016
	ds_read_u16_d16_hi v63, v240 offset:2160
	s_waitcnt lgkmcnt(0)
	v_pk_fma_f32 v[0:1], v[0:1], v[248:249], v[242:243]
	v_pk_fma_f32 v[2:3], v[2:3], v[248:249], v[242:243]
	v_pk_fma_f32 v[4:5], v[4:5], v[248:249], v[242:243]
	v_pk_fma_f32 v[6:7], v[6:7], v[248:249], v[242:243]
	v_pk_fma_f32 v[8:9], v[8:9], v[248:249], v[242:243]
	v_pk_fma_f32 v[10:11], v[10:11], v[248:249], v[242:243]
	v_pk_fma_f32 v[12:13], v[12:13], v[248:249], v[242:243]
	v_pk_fma_f32 v[14:15], v[14:15], v[248:249], v[242:243]
	v_pk_fma_f32 v[16:17], v[16:17], v[248:249], v[244:245]
	v_pk_fma_f32 v[18:19], v[18:19], v[248:249], v[244:245]
	v_pk_fma_f32 v[20:21], v[20:21], v[248:249], v[244:245]
	v_pk_fma_f32 v[22:23], v[22:23], v[248:249], v[244:245]
	v_pk_fma_f32 v[24:25], v[24:25], v[248:249], v[244:245]
	v_pk_fma_f32 v[26:27], v[26:27], v[248:249], v[244:245]
	v_pk_fma_f32 v[28:29], v[28:29], v[248:249], v[244:245]
	v_pk_fma_f32 v[30:31], v[30:31], v[248:249], v[244:245]
	v_exp_f32_e32 v0, v0
	v_exp_f32_e32 v1, v1
	v_exp_f32_e32 v2, v2
	v_exp_f32_e32 v3, v3
	v_exp_f32_e32 v4, v4
	v_exp_f32_e32 v5, v5
	v_exp_f32_e32 v6, v6
	v_exp_f32_e32 v7, v7
	v_exp_f32_e32 v8, v8
	v_exp_f32_e32 v9, v9
	v_exp_f32_e32 v10, v10
	v_exp_f32_e32 v11, v11
	v_exp_f32_e32 v12, v12
	v_exp_f32_e32 v13, v13
	v_exp_f32_e32 v14, v14
	v_exp_f32_e32 v15, v15
	v_exp_f32_e32 v16, v16
	v_exp_f32_e32 v17, v17
	v_exp_f32_e32 v18, v18
	v_exp_f32_e32 v19, v19
	v_exp_f32_e32 v20, v20
	v_exp_f32_e32 v21, v21
	v_exp_f32_e32 v22, v22
	v_exp_f32_e32 v23, v23
	v_exp_f32_e32 v24, v24
	v_exp_f32_e32 v25, v25
	v_exp_f32_e32 v26, v26
	v_exp_f32_e32 v27, v27
	v_exp_f32_e32 v28, v28
	v_exp_f32_e32 v29, v29
	v_exp_f32_e32 v30, v30
	v_exp_f32_e32 v31, v31
	v_pk_add_f32 v[0:1], v[0:1], 1.0 op_sel_hi:[1,0]
	v_pk_add_f32 v[2:3], v[2:3], 1.0 op_sel_hi:[1,0]
	v_pk_add_f32 v[4:5], v[4:5], 1.0 op_sel_hi:[1,0]
	v_pk_add_f32 v[6:7], v[6:7], 1.0 op_sel_hi:[1,0]
	v_pk_add_f32 v[8:9], v[8:9], 1.0 op_sel_hi:[1,0]
	v_pk_add_f32 v[10:11], v[10:11], 1.0 op_sel_hi:[1,0]
	v_pk_add_f32 v[12:13], v[12:13], 1.0 op_sel_hi:[1,0]
	v_pk_add_f32 v[14:15], v[14:15], 1.0 op_sel_hi:[1,0]
; __device__ __forceinline__ unsigned f2bf(float f) { unsigned r; asm("v_cvt_pk_bf16_f32 %0, %1, %1" : "=v"(r) : "v"(f)); return r & 0xffffu; }
; __device__ __forceinline__ float sigmoid_f(float x) { return rcpf_(1.f + __expf(-x)); }
; __device__ __forceinline__ float gelu_tanh_f(float x) { const float y = 0.7978845608028654f * (x + 0.044715f * x * x * x); return x * sigmoid_f(2.f * y); }
; template <bool FINAL, int D>
; __device__ __forceinline__ void rg_dir(PREF p, int l, int h, int ch, int sidx, int rowbase  , LAS bf16_t* sXc, LAS float* stg, int lane) {
;     ...
;         for (int ti = 0; ti < 16; ++ti) { const int tk = D ? 15 - ti : ti;
;             const float zr = stg[tk * 64 + lane] + ba, zi = stg[1024 + tk * 64 + lane] + bi;
;             const float r = sigmoid_f(zr), ig = sigmoid_f(zi);
;             const float a = __builtin_amdgcn_exp2f(r * sp8);
;             const float xc = bf2f(sXc[(mt * 16 + tk) * 72 + lane]);
;             av[ti] = a; iv[ti] = __builtin_amdgcn_sqrtf(fmaxf(1.f - a * a, 0.f)) * ig * xc;
;             if (FINAL && D == 1) grv[ti] = gelu_tanh_f(grv[ti]);
;         }
; #pragma unroll
;         for (int ti = 0; ti < 16; ++ti) { const int tk = D ? 15 - ti : ti;
;             hc = av[ti] * hc + iv[ti]; Ap *= av[ti];
;             if (FINAL) { const size_t row = (size_t)(rowbase + mt * 16 + tk);
;                 if (D == 0) TMP[row * 512 + ch] = (bf16_t)f2bf(hc);
;                 else MIX[row * DM + ch] = (bf16_t)f2bf(grv[ti] * (hfv[ti] + hc)); }
;         }
;     }
;     if (!FINAL) { RGA[sidx] = Ap; RGH[sidx] = hc; }
; __global__ void __launch_bounds__(NTHREADS, 2) mega_fwd(Params p_arg) {
;     ...
;             for (int item = gw; item < 2 * NCH * 8; item += NGW) rg_item<false>(p, l, item, lds + wave * 18432, lane);
	v_pk_add_f32 v[16:17], v[16:17], 1.0 op_sel_hi:[1,0]
	v_pk_add_f32 v[18:19], v[18:19], 1.0 op_sel_hi:[1,0]
	v_pk_add_f32 v[20:21], v[20:21], 1.0 op_sel_hi:[1,0]
	v_pk_add_f32 v[22:23], v[22:23], 1.0 op_sel_hi:[1,0]
	v_pk_add_f32 v[24:25], v[24:25], 1.0 op_sel_hi:[1,0]
	v_pk_add_f32 v[26:27], v[26:27], 1.0 op_sel_hi:[1,0]
	v_pk_add_f32 v[28:29], v[28:29], 1.0 op_sel_hi:[1,0]
	v_pk_add_f32 v[30:31], v[30:31], 1.0 op_sel_hi:[1,0]
	v_rcp_f32_e32 v0, v0
	v_rcp_f32_e32 v1, v1
	v_rcp_f32_e32 v2, v2
	v_rcp_f32_e32 v3, v3
	v_rcp_f32_e32 v4, v4
	v_rcp_f32_e32 v5, v5
	v_rcp_f32_e32 v6, v6
	v_rcp_f32_e32 v7, v7
	v_rcp_f32_e32 v8, v8
	v_rcp_f32_e32 v9, v9
	v_rcp_f32_e32 v10, v10
	v_rcp_f32_e32 v11, v11
	v_rcp_f32_e32 v12, v12
	v_rcp_f32_e32 v13, v13
	v_rcp_f32_e32 v14, v14
	v_rcp_f32_e32 v15, v15
	v_rcp_f32_e32 v16, v16
	v_rcp_f32_e32 v17, v17
	v_rcp_f32_e32 v18, v18
	v_rcp_f32_e32 v19, v19
	v_rcp_f32_e32 v20, v20
	v_rcp_f32_e32 v21, v21
	v_rcp_f32_e32 v22, v22
	v_rcp_f32_e32 v23, v23
	v_rcp_f32_e32 v24, v24
	v_rcp_f32_e32 v25, v25
	v_rcp_f32_e32 v26, v26
	v_rcp_f32_e32 v27, v27
	v_rcp_f32_e32 v28, v28
	v_rcp_f32_e32 v29, v29
	v_rcp_f32_e32 v30, v30
	v_rcp_f32_e32 v31, v31
	v_pk_mul_f32 v[0:1], v[246:247], v[0:1]
	v_pk_mul_f32 v[2:3], v[246:247], v[2:3]
	v_pk_mul_f32 v[4:5], v[246:247], v[4:5]
	v_pk_mul_f32 v[6:7], v[246:247], v[6:7]
	v_pk_mul_f32 v[8:9], v[246:247], v[8:9]
	v_pk_mul_f32 v[10:11], v[246:247], v[10:11]
	v_pk_mul_f32 v[12:13], v[246:247], v[12:13]
	v_pk_mul_f32 v[14:15], v[246:247], v[14:15]
	v_exp_f32_e32 v0, v0
	v_exp_f32_e32 v1, v1
	v_exp_f32_e32 v2, v2
	v_exp_f32_e32 v3, v3
	v_exp_f32_e32 v4, v4
	v_exp_f32_e32 v5, v5
	v_exp_f32_e32 v6, v6
	v_exp_f32_e32 v7, v7
	v_exp_f32_e32 v8, v8
	v_exp_f32_e32 v9, v9
	v_exp_f32_e32 v10, v10
	v_exp_f32_e32 v11, v11
	v_exp_f32_e32 v12, v12
	v_exp_f32_e32 v13, v13
	v_exp_f32_e32 v14, v14
	v_exp_f32_e32 v15, v15
	v_fma_f32 v32, -v0, v0, 1.0
	v_fma_f32 v33, -v1, v1, 1.0
	v_fma_f32 v34, -v2, v2, 1.0
	v_fma_f32 v35, -v3, v3, 1.0
	v_fma_f32 v36, -v4, v4, 1.0
	v_fma_f32 v37, -v5, v5, 1.0
	v_fma_f32 v38, -v6, v6, 1.0
	v_fma_f32 v39, -v7, v7, 1.0
	v_fma_f32 v40, -v8, v8, 1.0
	v_fma_f32 v41, -v9, v9, 1.0
	v_fma_f32 v42, -v10, v10, 1.0
	v_fma_f32 v43, -v11, v11, 1.0
	v_fma_f32 v44, -v12, v12, 1.0
	v_fma_f32 v45, -v13, v13, 1.0
	v_fma_f32 v46, -v14, v14, 1.0
	v_fma_f32 v47, -v15, v15, 1.0
	v_max_f32_e32 v32, 0, v32
	v_max_f32_e32 v33, 0, v33
	v_max_f32_e32 v34, 0, v34
	v_max_f32_e32 v35, 0, v35
	v_max_f32_e32 v36, 0, v36
	v_max_f32_e32 v37, 0, v37
	v_max_f32_e32 v38, 0, v38
	v_max_f32_e32 v39, 0, v39
	v_max_f32_e32 v40, 0, v40
	v_max_f32_e32 v41, 0, v41
	v_max_f32_e32 v42, 0, v42
	v_max_f32_e32 v43, 0, v43
	v_max_f32_e32 v44, 0, v44
	v_max_f32_e32 v45, 0, v45
	v_max_f32_e32 v46, 0, v46
	v_max_f32_e32 v47, 0, v47
	v_sqrt_f32_e32 v32, v32
	v_sqrt_f32_e32 v33, v33
	v_sqrt_f32_e32 v34, v34
	v_sqrt_f32_e32 v35, v35
	v_sqrt_f32_e32 v36, v36
	v_sqrt_f32_e32 v37, v37
	v_sqrt_f32_e32 v38, v38
	v_sqrt_f32_e32 v39, v39
	v_sqrt_f32_e32 v40, v40
	v_sqrt_f32_e32 v41, v41
	v_sqrt_f32_e32 v42, v42
	v_sqrt_f32_e32 v43, v43
	v_sqrt_f32_e32 v44, v44
	v_sqrt_f32_e32 v45, v45
	v_sqrt_f32_e32 v46, v46
	v_sqrt_f32_e32 v47, v47
	s_nop 0
	v_pk_mul_f32 v[16:17], v[16:17], v[32:33]
	v_pk_mul_f32 v[18:19], v[18:19], v[34:35]
	v_pk_mul_f32 v[20:21], v[20:21], v[36:37]
	v_pk_mul_f32 v[22:23], v[22:23], v[38:39]
	v_pk_mul_f32 v[24:25], v[24:25], v[40:41]
	v_pk_mul_f32 v[26:27], v[26:27], v[42:43]
	v_pk_mul_f32 v[28:29], v[28:29], v[44:45]
	v_pk_mul_f32 v[30:31], v[30:31], v[46:47]
	v_pk_mul_f32 v[16:17], v[16:17], v[48:49]
	v_pk_mul_f32 v[18:19], v[18:19], v[50:51]
	v_pk_mul_f32 v[20:21], v[20:21], v[52:53]
	v_pk_mul_f32 v[22:23], v[22:23], v[54:55]
	v_pk_mul_f32 v[24:25], v[24:25], v[56:57]
	v_pk_mul_f32 v[26:27], v[26:27], v[58:59]
	v_pk_mul_f32 v[28:29], v[28:29], v[60:61]
	v_pk_mul_f32 v[30:31], v[30:31], v[62:63]
	v_fma_f32 v250, v15, v250, v31
	v_mul_f32_e32 v232, v232, v15
	v_fma_f32 v250, v14, v250, v30
	v_mul_f32_e32 v232, v232, v14
	v_fma_f32 v250, v13, v250, v29
	v_mul_f32_e32 v232, v232, v13
	v_fma_f32 v250, v12, v250, v28
	v_mul_f32_e32 v232, v232, v12
	v_fma_f32 v250, v11, v250, v27
	v_mul_f32_e32 v232, v232, v11
	v_fma_f32 v250, v10, v250, v26
	v_mul_f32_e32 v232, v232, v10
	v_fma_f32 v250, v9, v250, v25
	v_mul_f32_e32 v232, v232, v9
	v_fma_f32 v250, v8, v250, v24
	v_mul_f32_e32 v232, v232, v8
	v_fma_f32 v250, v7, v250, v23
	v_mul_f32_e32 v232, v232, v7
	v_fma_f32 v250, v6, v250, v22
	v_mul_f32_e32 v232, v232, v6
	v_fma_f32 v250, v5, v250, v21
	v_mul_f32_e32 v232, v232, v5
	v_fma_f32 v250, v4, v250, v20
	v_mul_f32_e32 v232, v232, v4
	v_fma_f32 v250, v3, v250, v19
	v_mul_f32_e32 v232, v232, v3
	v_fma_f32 v250, v2, v250, v18
	v_mul_f32_e32 v232, v232, v2
	v_fma_f32 v250, v1, v250, v17
	v_mul_f32_e32 v232, v232, v1
	v_fma_f32 v250, v0, v250, v16
	v_mul_f32_e32 v232, v232, v0
	s_add_u32 s96, s0, 0x400800
	s_addc_u32 s97, s1, 0
	s_add_u32 s96, s96, s36
	s_addc_u32 s97, s97, 0
	global_store_dword v235, v232, s[96:97]
	s_add_u32 s96, s96, 0x300000
	s_addc_u32 s97, s97, 0
	global_store_dword v235, v250, s[96:97]
	s_waitcnt lgkmcnt(0)
	v_readlane_b32 s84, v253, 29
	s_add_i32 s12, s12, s84
	s_cmpk_lt_i32 s12, 0x1000
	s_cbranch_scc1 .Lrg5_keep
	s_sub_i32 s0, s12, 0x1000
	s_lshr_b32 s1, s0, 5
	s_and_b32 s0, s0, 31
	s_and_b32 s12, s1, 7
	s_add_i32 s1, s1, 0x1000
	s_cmp_eq_u32 s0, s12
	s_cselect_b32 s12, s1, 0x2000
